# peeled first K-iteration: first MFMA per accumulator takes C=0, all accumulator re-zeroing v_mov_b64 removed (on top of saddr DMA + barrier/prio edits)
# speedup vs baseline: 1.0189x; 1.0101x over previous
.LBB0_262:
	s_or_b64 exec, exec, s[0:1]
	v_mov_b32_e32 v135, v188
	s_waitcnt vmcnt(0) lgkmcnt(0)
	s_barrier
	s_ashr_i32 s59, s58, 31
	v_ashrrev_i32_e32 v1, 31, v135
	v_lshrrev_b32_e32 v1, 26, v1
	v_add_u32_e32 v1, v135, v1
	v_ashrrev_i32_e32 v3, 6, v1
	v_bfe_i32 v1, v135, 27, 1
	v_lshlrev_b32_e32 v2, 4, v135
	v_lshrrev_b32_e32 v1, 22, v1
	v_add_u32_e32 v1, v2, v1
	v_and_b32_e32 v1, 0xfffffc00, v1
	v_sub_u32_e32 v1, v2, v1
	v_lshrrev_b32_e32 v4, 4, v1
	v_bitop3_b32 v4, v4, v1, 32 bitop3:0x6c
	v_lshlrev_b32_e32 v1, 3, v3
	v_and_b32_e32 v5, -16, v1
	v_ashrrev_i32_e32 v1, 31, v4
	v_lshrrev_b32_e32 v1, 26, v1
	v_add_u32_e32 v6, v4, v1
	v_ashrrev_i32_e32 v1, 6, v6
	v_add_u32_e32 v146, v1, v5
	v_and_b32_e32 v5, 0xc0, v6
	v_lshlrev_b32_e32 v3, 5, v3
	v_sub_u32_e32 v4, v4, v5
	v_mov_b32_e32 v5, 1
	v_and_b32_e32 v3, 32, v3
	v_ashrrev_i16_sdwa v4, v5, sext(v4) dst_sel:DWORD dst_unused:UNUSED_PAD src0_sel:DWORD src1_sel:BYTE_0
	v_add_u32_sdwa v3, v3, sext(v4) dst_sel:DWORD dst_unused:UNUSED_PAD src0_sel:DWORD src1_sel:WORD_0
	v_lshrrev_b32_e32 v147, 5, v3
	v_mov_b32_e32 v3, 31
	v_add_u32_e32 v2, 0x2000, v2
	v_and_b32_sdwa v148, sext(v4), v3 dst_sel:DWORD dst_unused:UNUSED_PAD src0_sel:WORD_0 src1_sel:DWORD
	v_ashrrev_i32_e32 v4, 31, v2
	v_lshrrev_b32_e32 v4, 22, v4
	v_add_u32_e32 v4, v2, v4
	v_ashrrev_i32_e32 v4, 10, v4
	v_mul_i32_i24_e32 v6, 0x400, v4
	v_sub_u32_e32 v2, v2, v6
	v_lshrrev_b32_e32 v6, 4, v2
	v_bitop3_b32 v2, v6, v2, 32 bitop3:0x6c
	v_ashrrev_i32_e32 v7, 31, v2
	v_lshrrev_b32_e32 v7, 26, v7
	v_lshlrev_b32_e32 v6, 3, v4
	v_add_u32_e32 v7, v2, v7
	v_and_b32_e32 v6, -16, v6
	v_ashrrev_i32_e32 v136, 6, v7
	v_add_u32_e32 v149, v136, v6
	v_and_b32_e32 v6, 0xc0, v7
	v_lshlrev_b32_e32 v4, 5, v4
	v_sub_u32_e32 v2, v2, v6
	v_and_b32_e32 v4, 32, v4
	v_ashrrev_i16_sdwa v2, v5, sext(v2) dst_sel:DWORD dst_unused:UNUSED_PAD src0_sel:DWORD src1_sel:BYTE_0
	v_add_u32_sdwa v4, v4, sext(v2) dst_sel:DWORD dst_unused:UNUSED_PAD src0_sel:DWORD src1_sel:WORD_0
	v_readfirstlane_b32 s28, v135
	v_lshrrev_b32_e32 v156, 5, v4
	v_and_b32_sdwa v155, sext(v2), v3 dst_sel:DWORD dst_unused:UNUSED_PAD src0_sel:WORD_0 src1_sel:DWORD
	v_and_b32_e32 v2, 0x1fffffe, v149
	v_lshlrev_b32_e32 v3, 5, v149
	s_ashr_i32 s10, s28, 6
	v_add_lshl_u32 v2, v156, v2, 6
	v_and_b32_e32 v157, 32, v3
	s_ashr_i32 s11, s28, 8
	s_lshl_b32 s5, s10, 10
	v_or3_b32 v2, v2, v157, v155
	s_lshl_b64 s[0:1], s[58:59], 19
	v_lshlrev_b32_e32 v130, 1, v2
	v_and_b32_e32 v2, 0x1fffffe, v146
	v_lshlrev_b32_e32 v3, 5, v146
	s_add_u32 s0, s60, s0
	v_add_lshl_u32 v2, v147, v2, 6
	v_and_b32_e32 v158, 32, v3
	s_addc_u32 s1, s33, s1
	s_add_i32 s36, s5, 0x100
	v_or3_b32 v2, v2, v158, v148
	s_add_i32 s37, s36, 0x2000
	v_lshlrev_b32_e32 v132, 1, v2
	s_mov_b32 m0, s36
	s_add_u32 s8, s0, 0x4000
	global_load_lds_dwordx4 v132, s[0:1] sc1
	s_mov_b32 m0, s37
	s_addc_u32 s9, s1, 0
	s_add_i32 s38, s36, 0x4000
	v_writelane_b32 v252, s12, 15
	global_load_lds_dwordx4 v130, s[0:1] sc1
	s_mov_b32 m0, s38
	s_add_i32 s39, s36, 0x6000
	v_writelane_b32 v252, s13, 16
	global_load_lds_dwordx4 v132, s[8:9] sc1
	s_mov_b32 m0, s39
	v_writelane_b32 v252, s8, 17
	v_mov_b32_e32 v133, 0
	s_cmp_eq_u32 s11, 1
	v_writelane_b32 v252, s9, 18
	v_mov_b32_e32 v131, v133
	s_nop 0
	global_load_lds_dwordx4 v130, s[8:9] sc1
	s_cselect_b64 s[8:9], -1, 0
	s_cmp_lg_u32 s11, 1
	s_cbranch_scc1 .LBB0_264
	s_barrier

.LBB0_267:
	s_mov_b32 s49, s35
	s_add_i32 s35, s35, 1
	s_cmp_lt_u32 s35, s15
	s_mov_b64 s[30:31], s[28:29]
	s_mov_b32 s28, s48
	s_cselect_b64 s[54:55], -1, 0
	s_add_i32 s48, s35, s4
	s_mov_b64 s[52:53], s[6:7]
	s_and_b64 s[6:7], s[54:55], exec
	s_cselect_b32 s6, s48, s28
	s_cselect_b32 s28, s58, s58
	s_ashr_i32 s29, s28, 31
	s_lshl_b64 s[28:29], s[28:29], 19
	s_add_u32 s28, s60, s28
	s_addc_u32 s29, s33, s29
	s_and_b64 s[50:51], s[54:55], exec
	s_cselect_b32 s50, s29, s31
	s_cselect_b32 s51, s28, s30
	s_ashr_i32 s7, s6, 31
	s_lshl_b64 s[6:7], s[6:7], 19
	s_add_u32 s6, s86, s6
	s_addc_u32 s7, s87, s7
	s_and_b64 s[54:55], s[54:55], exec
	s_cselect_b32 s54, s7, s53
	s_cselect_b32 s55, s6, s52
	s_add_u32 s61, s52, 0x10000
	s_addc_u32 s66, s53, 0
	s_mov_b32 s67, -2
	v_add_u32_e32 v160, s43, v1
	ds_read_b128 v[156:159], v160
	ds_read_b128 v[162:165], v160 offset:1024
	ds_read_b128 v[166:169], v160 offset:2048
	ds_read_b128 v[170:173], v160 offset:3072
	v_add_u32_e32 v160, s44, v1
	ds_read_b128 v[174:177], v160
	ds_read_b128 v[178:181], v160 offset:1024
	ds_read_b128 v[182:185], v160 offset:2048
	ds_read_b128 v[192:195], v160 offset:3072
	s_add_u32 s52, s30, 0x10000
	s_addc_u32 s53, s31, 0
	s_cmp_eq_u32 s67, 12
	s_cselect_b32 s64, s51, s52
	s_cselect_b32 s65, s50, s53
	s_cselect_b32 s62, s55, s61
	s_cselect_b32 s63, s54, s66
	s_add_u32 s56, s64, 0x8000
	s_addc_u32 s57, s65, 0
	s_add_i32 m0, s36, 0xc000
	ds_read_b128 v[200:203], v155
	ds_read_b128 v[204:207], v155 offset:1024
	ds_read_b128 v[208:211], v155 offset:2048
	ds_read_b128 v[212:215], v155 offset:3072
	ds_read_b128 v[216:219], v155 offset:4096
	ds_read_b128 v[220:223], v155 offset:5120
	ds_read_b128 v[224:227], v155 offset:6144
	ds_read_b128 v[228:231], v155 offset:7168
	global_load_lds_dwordx4 v146, s[30:31] sc1
	s_add_i32 m0, s36, 0xe000
	s_nop 0
	global_load_lds_dwordx4 v148, s[30:31] sc1
	s_waitcnt vmcnt(8)
	s_waitcnt lgkmcnt(0)
	s_setprio 1
	s_barrier
	v_mfma_f32_16x16x32_bf16 v[118:121], v[156:159], v[200:203], 0
	v_mfma_f32_16x16x32_bf16 v[110:113], v[166:169], v[200:203], 0
	v_mfma_f32_16x16x32_bf16 v[102:105], v[156:159], v[208:211], 0
	v_mfma_f32_16x16x32_bf16 v[94:97], v[166:169], v[208:211], 0
	v_mfma_f32_16x16x32_bf16 v[86:89], v[156:159], v[216:219], 0
	v_mfma_f32_16x16x32_bf16 v[78:81], v[166:169], v[216:219], 0
	v_mfma_f32_16x16x32_bf16 v[62:65], v[156:159], v[224:227], 0
	v_mfma_f32_16x16x32_bf16 v[54:57], v[166:169], v[224:227], 0
	v_mfma_f32_16x16x32_bf16 v[118:121], v[162:165], v[204:207], v[118:121]
	v_mfma_f32_16x16x32_bf16 v[110:113], v[170:173], v[204:207], v[110:113]
	v_mfma_f32_16x16x32_bf16 v[102:105], v[162:165], v[212:215], v[102:105]
	v_mfma_f32_16x16x32_bf16 v[94:97], v[170:173], v[212:215], v[94:97]
	v_mfma_f32_16x16x32_bf16 v[86:89], v[162:165], v[220:223], v[86:89]
	v_mfma_f32_16x16x32_bf16 v[78:81], v[170:173], v[220:223], v[78:81]
	v_mfma_f32_16x16x32_bf16 v[62:65], v[162:165], v[228:231], v[62:65]
	v_mfma_f32_16x16x32_bf16 v[54:57], v[170:173], v[228:231], v[54:57]
	v_mfma_f32_16x16x32_bf16 v[126:129], v[174:177], v[200:203], 0
	v_mfma_f32_16x16x32_bf16 v[122:125], v[182:185], v[200:203], 0
	v_mfma_f32_16x16x32_bf16 v[114:117], v[174:177], v[208:211], 0
	v_mfma_f32_16x16x32_bf16 v[106:109], v[182:185], v[208:211], 0
	v_mfma_f32_16x16x32_bf16 v[98:101], v[174:177], v[216:219], 0
	v_mfma_f32_16x16x32_bf16 v[90:93], v[182:185], v[216:219], 0
	v_mfma_f32_16x16x32_bf16 v[82:85], v[174:177], v[224:227], 0
	v_mfma_f32_16x16x32_bf16 v[70:73], v[182:185], v[224:227], 0
	v_mfma_f32_16x16x32_bf16 v[126:129], v[178:181], v[204:207], v[126:129]
	v_mfma_f32_16x16x32_bf16 v[122:125], v[192:195], v[204:207], v[122:125]
	v_mfma_f32_16x16x32_bf16 v[114:117], v[178:181], v[212:215], v[114:117]
	v_mfma_f32_16x16x32_bf16 v[106:109], v[192:195], v[212:215], v[106:109]
	v_mfma_f32_16x16x32_bf16 v[98:101], v[178:181], v[220:223], v[98:101]
	v_mfma_f32_16x16x32_bf16 v[90:93], v[192:195], v[220:223], v[90:93]
	s_setprio 2
	s_barrier
	v_mfma_f32_16x16x32_bf16 v[82:85], v[178:181], v[228:231], v[82:85]
	v_mfma_f32_16x16x32_bf16 v[70:73], v[192:195], v[228:231], v[70:73]
	s_setprio 0
	s_add_i32 s30, s43, s5
	s_mov_b32 m0, s30
	ds_read_b128 v[200:203], v155 offset:16384
	ds_read_b128 v[204:207], v155 offset:17408
	ds_read_b128 v[208:211], v155 offset:18432
	ds_read_b128 v[212:215], v155 offset:19456
	ds_read_b128 v[216:219], v155 offset:20480
	ds_read_b128 v[220:223], v155 offset:21504
	ds_read_b128 v[224:227], v155 offset:22528
	ds_read_b128 v[228:231], v155 offset:23552
	global_load_lds_dwordx4 v134, s[62:63] sc1
	s_add_i32 m0, s30, 0x2000
	s_add_u32 s30, s62, 0x4000
	s_addc_u32 s31, s63, 0
	s_add_i32 s69, s44, s5
	global_load_lds_dwordx4 v136, s[62:63] sc1
	s_mov_b32 m0, s69
	s_nop 0
	global_load_lds_dwordx4 v134, s[30:31] sc1
	s_add_i32 m0, s69, 0x2000
	s_nop 0
	global_load_lds_dwordx4 v136, s[30:31] sc1
	s_mov_b32 m0, s36
	s_nop 0
	global_load_lds_dwordx4 v132, s[64:65] sc1
	s_mov_b32 m0, s37
	s_nop 0
	global_load_lds_dwordx4 v130, s[64:65] sc1
	s_waitcnt vmcnt(8)
	s_waitcnt lgkmcnt(0)
	s_setprio 1
	s_barrier
	v_mfma_f32_16x16x32_bf16 v[58:61], v[156:159], v[200:203], 0
	v_mfma_f32_16x16x32_bf16 v[46:49], v[166:169], v[200:203], 0
	v_mfma_f32_16x16x32_bf16 v[38:41], v[156:159], v[208:211], 0
	v_mfma_f32_16x16x32_bf16 v[30:33], v[166:169], v[208:211], 0
	v_mfma_f32_16x16x32_bf16 v[22:25], v[156:159], v[216:219], 0
	v_mfma_f32_16x16x32_bf16 v[14:17], v[166:169], v[216:219], 0
	v_mfma_f32_16x16x32_bf16 v[6:9], v[156:159], v[224:227], 0
	v_mfma_f32_16x16x32_bf16 v[2:5], v[166:169], v[224:227], 0
	v_mfma_f32_16x16x32_bf16 v[58:61], v[162:165], v[204:207], v[58:61]
	v_mfma_f32_16x16x32_bf16 v[46:49], v[170:173], v[204:207], v[46:49]
	v_mfma_f32_16x16x32_bf16 v[38:41], v[162:165], v[212:215], v[38:41]
	v_mfma_f32_16x16x32_bf16 v[30:33], v[170:173], v[212:215], v[30:33]
	v_mfma_f32_16x16x32_bf16 v[22:25], v[162:165], v[220:223], v[22:25]
	v_mfma_f32_16x16x32_bf16 v[14:17], v[170:173], v[220:223], v[14:17]
	v_mfma_f32_16x16x32_bf16 v[6:9], v[162:165], v[228:231], v[6:9]
	v_mfma_f32_16x16x32_bf16 v[2:5], v[170:173], v[228:231], v[2:5]
	v_mfma_f32_16x16x32_bf16 v[74:77], v[174:177], v[200:203], 0
	v_mfma_f32_16x16x32_bf16 v[66:69], v[182:185], v[200:203], 0
	v_mfma_f32_16x16x32_bf16 v[50:53], v[174:177], v[208:211], 0
	v_mfma_f32_16x16x32_bf16 v[42:45], v[182:185], v[208:211], 0
	v_mfma_f32_16x16x32_bf16 v[34:37], v[174:177], v[216:219], 0
	v_mfma_f32_16x16x32_bf16 v[26:29], v[182:185], v[216:219], 0
	v_mfma_f32_16x16x32_bf16 v[18:21], v[174:177], v[224:227], 0
	v_mfma_f32_16x16x32_bf16 v[10:13], v[182:185], v[224:227], 0
	v_mfma_f32_16x16x32_bf16 v[74:77], v[178:181], v[204:207], v[74:77]
	v_mfma_f32_16x16x32_bf16 v[66:69], v[192:195], v[204:207], v[66:69]
	v_mfma_f32_16x16x32_bf16 v[50:53], v[178:181], v[212:215], v[50:53]
	v_mfma_f32_16x16x32_bf16 v[42:45], v[192:195], v[212:215], v[42:45]
	v_mfma_f32_16x16x32_bf16 v[34:37], v[178:181], v[220:223], v[34:37]
	v_mfma_f32_16x16x32_bf16 v[26:29], v[192:195], v[220:223], v[26:29]
	s_setprio 2
	s_barrier
	v_mfma_f32_16x16x32_bf16 v[18:21], v[178:181], v[228:231], v[18:21]
	v_mfma_f32_16x16x32_bf16 v[10:13], v[192:195], v[228:231], v[10:13]
	s_setprio 0
	v_add_u32_e32 v160, s45, v1
	ds_read_b128 v[156:159], v160
	ds_read_b128 v[162:165], v160 offset:1024
	ds_read_b128 v[166:169], v160 offset:2048
	ds_read_b128 v[170:173], v160 offset:3072
	v_add_u32_e32 v160, s46, v1
	ds_read_b128 v[174:177], v160
	ds_read_b128 v[178:181], v160 offset:1024
	ds_read_b128 v[182:185], v160 offset:2048
	ds_read_b128 v[192:195], v160 offset:3072
	s_add_u32 s30, s64, 0x4000
	s_addc_u32 s31, s65, 0
	s_mov_b32 m0, s38
	ds_read_b128 v[200:203], v155 offset:32768
	ds_read_b128 v[204:207], v155 offset:33792
	ds_read_b128 v[208:211], v155 offset:34816
	ds_read_b128 v[212:215], v155 offset:35840
	ds_read_b128 v[216:219], v155 offset:36864
	ds_read_b128 v[220:223], v155 offset:37888
	ds_read_b128 v[224:227], v155 offset:38912
	ds_read_b128 v[228:231], v155 offset:39936
	global_load_lds_dwordx4 v132, s[30:31] sc1
	s_mov_b32 m0, s39
	s_nop 0
	global_load_lds_dwordx4 v130, s[30:31] sc1
	s_waitcnt vmcnt(8)
	s_waitcnt lgkmcnt(0)
	s_setprio 1
	s_barrier
	v_mfma_f32_16x16x32_bf16 v[118:121], v[156:159], v[200:203], v[118:121]
	v_mfma_f32_16x16x32_bf16 v[110:113], v[166:169], v[200:203], v[110:113]
	v_mfma_f32_16x16x32_bf16 v[102:105], v[156:159], v[208:211], v[102:105]
	v_mfma_f32_16x16x32_bf16 v[94:97], v[166:169], v[208:211], v[94:97]
	v_mfma_f32_16x16x32_bf16 v[86:89], v[156:159], v[216:219], v[86:89]
	v_mfma_f32_16x16x32_bf16 v[78:81], v[166:169], v[216:219], v[78:81]
	v_mfma_f32_16x16x32_bf16 v[62:65], v[156:159], v[224:227], v[62:65]
	v_mfma_f32_16x16x32_bf16 v[54:57], v[166:169], v[224:227], v[54:57]
	v_mfma_f32_16x16x32_bf16 v[118:121], v[162:165], v[204:207], v[118:121]
	v_mfma_f32_16x16x32_bf16 v[110:113], v[170:173], v[204:207], v[110:113]
	v_mfma_f32_16x16x32_bf16 v[102:105], v[162:165], v[212:215], v[102:105]
	v_mfma_f32_16x16x32_bf16 v[94:97], v[170:173], v[212:215], v[94:97]
	v_mfma_f32_16x16x32_bf16 v[86:89], v[162:165], v[220:223], v[86:89]
	v_mfma_f32_16x16x32_bf16 v[78:81], v[170:173], v[220:223], v[78:81]
	v_mfma_f32_16x16x32_bf16 v[62:65], v[162:165], v[228:231], v[62:65]
	v_mfma_f32_16x16x32_bf16 v[54:57], v[170:173], v[228:231], v[54:57]
	v_mfma_f32_16x16x32_bf16 v[126:129], v[174:177], v[200:203], v[126:129]
	v_mfma_f32_16x16x32_bf16 v[122:125], v[182:185], v[200:203], v[122:125]
	v_mfma_f32_16x16x32_bf16 v[114:117], v[174:177], v[208:211], v[114:117]
	v_mfma_f32_16x16x32_bf16 v[106:109], v[182:185], v[208:211], v[106:109]
	v_mfma_f32_16x16x32_bf16 v[98:101], v[174:177], v[216:219], v[98:101]
	v_mfma_f32_16x16x32_bf16 v[90:93], v[182:185], v[216:219], v[90:93]
	v_mfma_f32_16x16x32_bf16 v[82:85], v[174:177], v[224:227], v[82:85]
	v_mfma_f32_16x16x32_bf16 v[70:73], v[182:185], v[224:227], v[70:73]
	v_mfma_f32_16x16x32_bf16 v[126:129], v[178:181], v[204:207], v[126:129]
	v_mfma_f32_16x16x32_bf16 v[122:125], v[192:195], v[204:207], v[122:125]
	v_mfma_f32_16x16x32_bf16 v[114:117], v[178:181], v[212:215], v[114:117]
	v_mfma_f32_16x16x32_bf16 v[106:109], v[192:195], v[212:215], v[106:109]
	v_mfma_f32_16x16x32_bf16 v[98:101], v[178:181], v[220:223], v[98:101]
	v_mfma_f32_16x16x32_bf16 v[90:93], v[192:195], v[220:223], v[90:93]
	s_setprio 2
	s_barrier
	v_mfma_f32_16x16x32_bf16 v[82:85], v[178:181], v[228:231], v[82:85]
	v_mfma_f32_16x16x32_bf16 v[70:73], v[192:195], v[228:231], v[70:73]
	s_setprio 0
	s_add_u32 s30, s62, 0x8000
	s_addc_u32 s31, s63, 0
	s_add_i32 s64, s45, s5
	s_mov_b32 m0, s64
	ds_read_b128 v[200:203], v155 offset:49152
	ds_read_b128 v[204:207], v155 offset:50176
	ds_read_b128 v[208:211], v155 offset:51200
	ds_read_b128 v[212:215], v155 offset:52224
	ds_read_b128 v[216:219], v155 offset:53248
	ds_read_b128 v[220:223], v155 offset:54272
	ds_read_b128 v[224:227], v155 offset:55296
	ds_read_b128 v[228:231], v155 offset:56320
	global_load_lds_dwordx4 v134, s[30:31] sc1
	s_add_i32 m0, s64, 0x2000
	s_nop 0
	global_load_lds_dwordx4 v136, s[30:31] sc1
	s_add_u32 s30, s62, 0xc000
	s_addc_u32 s31, s63, 0
	s_add_i32 s62, s46, s5
	s_mov_b32 m0, s62
	s_nop 0
	global_load_lds_dwordx4 v134, s[30:31] sc1
	s_add_i32 m0, s62, 0x2000
	s_nop 0
	global_load_lds_dwordx4 v136, s[30:31] sc1
	s_mov_b32 m0, s40
	s_nop 0
	global_load_lds_dwordx4 v132, s[56:57] sc1
	s_mov_b32 m0, s41
	s_nop 0
	global_load_lds_dwordx4 v130, s[56:57] sc1
	s_waitcnt vmcnt(8)
	s_waitcnt lgkmcnt(0)
	s_setprio 1
	s_barrier
	v_mfma_f32_16x16x32_bf16 v[58:61], v[156:159], v[200:203], v[58:61]
	v_mfma_f32_16x16x32_bf16 v[46:49], v[166:169], v[200:203], v[46:49]
	v_mfma_f32_16x16x32_bf16 v[38:41], v[156:159], v[208:211], v[38:41]
	v_mfma_f32_16x16x32_bf16 v[30:33], v[166:169], v[208:211], v[30:33]
	v_mfma_f32_16x16x32_bf16 v[22:25], v[156:159], v[216:219], v[22:25]
	v_mfma_f32_16x16x32_bf16 v[14:17], v[166:169], v[216:219], v[14:17]
	v_mfma_f32_16x16x32_bf16 v[6:9], v[156:159], v[224:227], v[6:9]
	v_mfma_f32_16x16x32_bf16 v[2:5], v[166:169], v[224:227], v[2:5]
	v_mfma_f32_16x16x32_bf16 v[58:61], v[162:165], v[204:207], v[58:61]
	v_mfma_f32_16x16x32_bf16 v[46:49], v[170:173], v[204:207], v[46:49]
	v_mfma_f32_16x16x32_bf16 v[38:41], v[162:165], v[212:215], v[38:41]
	v_mfma_f32_16x16x32_bf16 v[30:33], v[170:173], v[212:215], v[30:33]
	v_mfma_f32_16x16x32_bf16 v[22:25], v[162:165], v[220:223], v[22:25]
	v_mfma_f32_16x16x32_bf16 v[14:17], v[170:173], v[220:223], v[14:17]
	v_mfma_f32_16x16x32_bf16 v[6:9], v[162:165], v[228:231], v[6:9]
	v_mfma_f32_16x16x32_bf16 v[2:5], v[170:173], v[228:231], v[2:5]
	v_mfma_f32_16x16x32_bf16 v[74:77], v[174:177], v[200:203], v[74:77]
	v_mfma_f32_16x16x32_bf16 v[66:69], v[182:185], v[200:203], v[66:69]
	v_mfma_f32_16x16x32_bf16 v[50:53], v[174:177], v[208:211], v[50:53]
	v_mfma_f32_16x16x32_bf16 v[42:45], v[182:185], v[208:211], v[42:45]
	v_mfma_f32_16x16x32_bf16 v[34:37], v[174:177], v[216:219], v[34:37]
	v_mfma_f32_16x16x32_bf16 v[26:29], v[182:185], v[216:219], v[26:29]
	v_mfma_f32_16x16x32_bf16 v[18:21], v[174:177], v[224:227], v[18:21]
	v_mfma_f32_16x16x32_bf16 v[10:13], v[182:185], v[224:227], v[10:13]
	v_mfma_f32_16x16x32_bf16 v[74:77], v[178:181], v[204:207], v[74:77]
	v_mfma_f32_16x16x32_bf16 v[66:69], v[192:195], v[204:207], v[66:69]
	v_mfma_f32_16x16x32_bf16 v[50:53], v[178:181], v[212:215], v[50:53]
	v_mfma_f32_16x16x32_bf16 v[42:45], v[192:195], v[212:215], v[42:45]
	v_mfma_f32_16x16x32_bf16 v[34:37], v[178:181], v[220:223], v[34:37]
	v_mfma_f32_16x16x32_bf16 v[26:29], v[192:195], v[220:223], v[26:29]
	s_setprio 2
	s_barrier
	v_mfma_f32_16x16x32_bf16 v[18:21], v[178:181], v[228:231], v[18:21]
	v_mfma_f32_16x16x32_bf16 v[10:13], v[192:195], v[228:231], v[10:13]
	s_setprio 0
	s_add_i32 s67, s67, 2
	s_add_u32 s61, s61, 0x10000
	s_addc_u32 s66, s66, 0
	s_cmp_gt_u32 s67, 13
	s_mov_b64 s[30:31], s[52:53]

.LBB0_271:
	v_lshl_add_u32 v156, s49, 10, v154
	ds_read_b32 v157, v156
	s_add_i32 s30, s49, s4
	s_lshl_b32 s30, s30, 15
	s_or_b32 s30, s30, s47
	s_and_b32 s30, s30, 0xffffc000
	s_waitcnt lgkmcnt(0)
	v_mul_f32_e32 v158, 0xbfb8aa3b, v157
	v_mul_f32_e32 v157, v157, v157
	v_pk_mul_f32 v[164:165], v[118:119], v[158:159] op_sel_hi:[1,0]
	v_rcp_f32_e32 v157, v157
	v_pk_mul_f32 v[162:163], v[120:121], v[158:159] op_sel_hi:[1,0]
	v_exp_f32_e32 v159, v164
	v_exp_f32_e32 v160, v165
	v_exp_f32_e32 v164, v162
	v_pk_mul_f32 v[120:121], v[120:121], v[128:129]
	v_fma_f32 v159, v159, v157, v157
	v_rcp_f32_e32 v162, v159
	v_fma_f32 v159, v160, v157, v157
	v_pk_mul_f32 v[118:119], v[118:119], v[126:127]
	v_pk_mul_f32 v[126:127], v[112:113], v[158:159] op_sel_hi:[1,0]
	v_pk_mul_f32 v[128:129], v[110:111], v[158:159] op_sel_hi:[1,0]
	v_exp_f32_e32 v163, v163
	v_exp_f32_e32 v128, v128
	v_exp_f32_e32 v129, v129
	v_exp_f32_e32 v158, v126
	v_exp_f32_e32 v127, v127
	v_fma_f32 v160, v164, v157, v157
	v_rcp_f32_e32 v164, v160
	v_fma_f32 v160, v163, v157, v157
	v_rcp_f32_e32 v163, v159
	v_fma_f32 v126, v128, v157, v157
	v_fma_f32 v159, v129, v157, v157
	v_fma_f32 v128, v158, v157, v157
	v_fmac_f32_e32 v157, v127, v157
	v_rcp_f32_e32 v165, v160
	v_rcp_f32_e32 v126, v126
	v_rcp_f32_e32 v128, v128
	v_rcp_f32_e32 v129, v157
	v_rcp_f32_e32 v127, v159
	v_pk_mul_f32 v[118:119], v[118:119], v[162:163]
	v_pk_mul_f32 v[112:113], v[112:113], v[124:125]
	v_pk_mul_f32 v[110:111], v[110:111], v[122:123]
	v_pk_mul_f32 v[120:121], v[120:121], v[164:165]
	v_pk_mul_f32 v[122:123], v[112:113], v[128:129]
	v_pk_mul_f32 v[124:125], v[110:111], v[126:127]
	s_add_i32 s31, s30, s42
	s_nop 0
	v_cvt_pk_bf16_f32 v110, v118, v119
	v_cvt_pk_bf16_f32 v111, v120, v121
	v_cvt_pk_bf16_f32 v112, v124, v125
	v_cvt_pk_bf16_f32 v113, v122, v123
	ds_read_b32 v118, v156 offset:64
	v_or_b32_e32 v119, s31, v139
	v_lshlrev_b32_e32 v119, 1, v119
	buffer_store_dwordx4 v[110:113], v119, s[72:75], 0 offen sc1
	s_cmp_eq_u32 s49, s59
	s_waitcnt lgkmcnt(0)
	v_mul_f32_e32 v110, 0xbfb8aa3b, v118
	v_mul_f32_e32 v111, v118, v118
	v_pk_mul_f32 v[118:119], v[102:103], v[110:111] op_sel_hi:[1,0]
	v_rcp_f32_e32 v120, v111
	v_pk_mul_f32 v[112:113], v[104:105], v[110:111] op_sel_hi:[1,0]
	v_exp_f32_e32 v111, v118
	v_exp_f32_e32 v118, v119
	v_exp_f32_e32 v113, v113
	v_exp_f32_e32 v119, v112
	v_fma_f32 v111, v111, v120, v120
	v_rcp_f32_e32 v112, v111
	v_fma_f32 v111, v118, v120, v120
	v_fma_f32 v113, v113, v120, v120
	v_fma_f32 v118, v119, v120, v120
	v_rcp_f32_e32 v119, v113
	v_rcp_f32_e32 v113, v111
	v_pk_mul_f32 v[102:103], v[102:103], v[114:115]
	v_rcp_f32_e32 v118, v118
	v_pk_mul_f32 v[104:105], v[104:105], v[116:117]
	v_pk_mul_f32 v[102:103], v[102:103], v[112:113]
	v_pk_mul_f32 v[112:113], v[96:97], v[110:111] op_sel_hi:[1,0]
	v_pk_mul_f32 v[110:111], v[94:95], v[110:111] op_sel_hi:[1,0]
	v_exp_f32_e32 v112, v112
	v_exp_f32_e32 v110, v110
	v_exp_f32_e32 v111, v111
	v_exp_f32_e32 v113, v113
	v_fma_f32 v112, v112, v120, v120
	v_fma_f32 v110, v110, v120, v120
	v_fma_f32 v111, v111, v120, v120
	v_fmac_f32_e32 v120, v113, v120
	v_rcp_f32_e32 v110, v110
	v_rcp_f32_e32 v112, v112
	v_rcp_f32_e32 v113, v120
	v_rcp_f32_e32 v111, v111
	v_pk_mul_f32 v[96:97], v[96:97], v[108:109]
	v_pk_mul_f32 v[94:95], v[94:95], v[106:107]
	v_pk_mul_f32 v[104:105], v[104:105], v[118:119]
	v_pk_mul_f32 v[106:107], v[96:97], v[112:113]
	v_pk_mul_f32 v[108:109], v[94:95], v[110:111]
	s_nop 0
	s_nop 0
	v_cvt_pk_bf16_f32 v94, v102, v103
	v_cvt_pk_bf16_f32 v95, v104, v105
	v_cvt_pk_bf16_f32 v96, v108, v109
	v_cvt_pk_bf16_f32 v97, v106, v107
	ds_read_b32 v102, v156 offset:128
	v_or_b32_e32 v103, s31, v141
	v_lshlrev_b32_e32 v103, 1, v103
	buffer_store_dwordx4 v[94:97], v103, s[72:75], 0 offen sc1
	s_waitcnt lgkmcnt(0)
	s_nop 0
	v_mul_f32_e32 v94, 0xbfb8aa3b, v102
	v_mul_f32_e32 v95, v102, v102
	v_pk_mul_f32 v[102:103], v[86:87], v[94:95] op_sel_hi:[1,0]
	v_rcp_f32_e32 v104, v95
	v_pk_mul_f32 v[96:97], v[88:89], v[94:95] op_sel_hi:[1,0]
	v_exp_f32_e32 v95, v102
	v_exp_f32_e32 v102, v103
	v_exp_f32_e32 v97, v97
	v_exp_f32_e32 v103, v96
	v_fma_f32 v95, v95, v104, v104
	v_rcp_f32_e32 v96, v95
	v_fma_f32 v95, v102, v104, v104
	v_fma_f32 v97, v97, v104, v104
	v_fma_f32 v102, v103, v104, v104
	v_rcp_f32_e32 v103, v97
	v_rcp_f32_e32 v97, v95
	v_pk_mul_f32 v[86:87], v[86:87], v[98:99]
	v_rcp_f32_e32 v102, v102
	v_pk_mul_f32 v[88:89], v[88:89], v[100:101]
	v_pk_mul_f32 v[86:87], v[86:87], v[96:97]
	v_pk_mul_f32 v[96:97], v[80:81], v[94:95] op_sel_hi:[1,0]
	v_pk_mul_f32 v[94:95], v[78:79], v[94:95] op_sel_hi:[1,0]
	v_exp_f32_e32 v96, v96
	v_exp_f32_e32 v94, v94
	v_exp_f32_e32 v95, v95
	v_exp_f32_e32 v97, v97
	v_fma_f32 v96, v96, v104, v104
	v_fma_f32 v94, v94, v104, v104
	v_fma_f32 v95, v95, v104, v104
	v_fmac_f32_e32 v104, v97, v104
	v_rcp_f32_e32 v94, v94
	v_rcp_f32_e32 v96, v96
	v_rcp_f32_e32 v97, v104
	v_rcp_f32_e32 v95, v95
	v_pk_mul_f32 v[80:81], v[80:81], v[92:93]
	v_pk_mul_f32 v[78:79], v[78:79], v[90:91]
	v_pk_mul_f32 v[88:89], v[88:89], v[102:103]
	v_pk_mul_f32 v[90:91], v[80:81], v[96:97]
	v_pk_mul_f32 v[92:93], v[78:79], v[94:95]
	s_nop 0
	s_nop 0
	v_cvt_pk_bf16_f32 v78, v86, v87
	v_cvt_pk_bf16_f32 v79, v88, v89
	v_cvt_pk_bf16_f32 v80, v92, v93
	v_cvt_pk_bf16_f32 v81, v90, v91
	ds_read_b32 v86, v156 offset:192
	v_or_b32_e32 v87, s31, v143
	v_lshlrev_b32_e32 v87, 1, v87
	buffer_store_dwordx4 v[78:81], v87, s[72:75], 0 offen sc1
	s_waitcnt lgkmcnt(0)
	s_nop 0
	v_mul_f32_e32 v78, 0xbfb8aa3b, v86
	v_mul_f32_e32 v79, v86, v86
	v_pk_mul_f32 v[86:87], v[62:63], v[78:79] op_sel_hi:[1,0]
	v_rcp_f32_e32 v88, v79
	v_pk_mul_f32 v[80:81], v[64:65], v[78:79] op_sel_hi:[1,0]
	v_exp_f32_e32 v79, v86
	v_exp_f32_e32 v86, v87
	v_exp_f32_e32 v81, v81
	v_exp_f32_e32 v87, v80
	v_fma_f32 v79, v79, v88, v88
	v_rcp_f32_e32 v80, v79
	v_fma_f32 v79, v86, v88, v88
	v_fma_f32 v81, v81, v88, v88
	v_fma_f32 v86, v87, v88, v88
	v_rcp_f32_e32 v87, v81
	v_rcp_f32_e32 v81, v79
	v_pk_mul_f32 v[62:63], v[62:63], v[82:83]
	v_rcp_f32_e32 v86, v86
	v_pk_mul_f32 v[64:65], v[64:65], v[84:85]
	v_pk_mul_f32 v[62:63], v[62:63], v[80:81]
	v_pk_mul_f32 v[80:81], v[56:57], v[78:79] op_sel_hi:[1,0]
	v_pk_mul_f32 v[78:79], v[54:55], v[78:79] op_sel_hi:[1,0]
	v_exp_f32_e32 v80, v80
	v_exp_f32_e32 v78, v78
	v_exp_f32_e32 v79, v79
	v_exp_f32_e32 v81, v81
	v_fma_f32 v80, v80, v88, v88
	v_fma_f32 v78, v78, v88, v88
	v_fma_f32 v79, v79, v88, v88
	v_fmac_f32_e32 v88, v81, v88
	v_rcp_f32_e32 v78, v78
	v_rcp_f32_e32 v80, v80
	v_rcp_f32_e32 v81, v88
	v_rcp_f32_e32 v79, v79
	v_pk_mul_f32 v[56:57], v[56:57], v[72:73]
	v_pk_mul_f32 v[54:55], v[54:55], v[70:71]
	v_pk_mul_f32 v[64:65], v[64:65], v[86:87]
	v_pk_mul_f32 v[70:71], v[56:57], v[80:81]
	v_pk_mul_f32 v[72:73], v[54:55], v[78:79]
	s_nop 0
	s_nop 0
	v_cvt_pk_bf16_f32 v54, v62, v63
	v_cvt_pk_bf16_f32 v55, v64, v65
	v_cvt_pk_bf16_f32 v56, v72, v73
	v_cvt_pk_bf16_f32 v57, v70, v71
	ds_read_b32 v62, v156 offset:512
	v_or_b32_e32 v63, s31, v145
	v_lshlrev_b32_e32 v63, 1, v63
	buffer_store_dwordx4 v[54:57], v63, s[72:75], 0 offen sc1
	s_waitcnt lgkmcnt(0)
	s_nop 0
	v_mul_f32_e32 v54, 0xbfb8aa3b, v62
	v_mul_f32_e32 v55, v62, v62
	v_pk_mul_f32 v[62:63], v[58:59], v[54:55] op_sel_hi:[1,0]
	v_rcp_f32_e32 v64, v55
	v_pk_mul_f32 v[56:57], v[60:61], v[54:55] op_sel_hi:[1,0]
	v_exp_f32_e32 v55, v62
	v_exp_f32_e32 v62, v63
	v_exp_f32_e32 v57, v57
	v_exp_f32_e32 v63, v56
	v_fma_f32 v55, v55, v64, v64
	v_rcp_f32_e32 v56, v55
	v_fma_f32 v55, v62, v64, v64
	v_fma_f32 v57, v57, v64, v64
	v_fma_f32 v62, v63, v64, v64
	v_rcp_f32_e32 v63, v57
	v_rcp_f32_e32 v57, v55
	v_pk_mul_f32 v[58:59], v[58:59], v[74:75]
	v_rcp_f32_e32 v62, v62
	v_pk_mul_f32 v[60:61], v[60:61], v[76:77]
	v_pk_mul_f32 v[56:57], v[58:59], v[56:57]
	v_pk_mul_f32 v[58:59], v[48:49], v[54:55] op_sel_hi:[1,0]
	v_pk_mul_f32 v[54:55], v[46:47], v[54:55] op_sel_hi:[1,0]
	v_exp_f32_e32 v58, v58
	v_exp_f32_e32 v54, v54
	v_exp_f32_e32 v55, v55
	v_exp_f32_e32 v59, v59
	v_fma_f32 v58, v58, v64, v64
	v_fma_f32 v54, v54, v64, v64
	v_fma_f32 v55, v55, v64, v64
	v_rcp_f32_e32 v54, v54
	v_fmac_f32_e32 v64, v59, v64
	v_rcp_f32_e32 v55, v55
	v_rcp_f32_e32 v58, v58
	v_rcp_f32_e32 v59, v64
	v_pk_mul_f32 v[46:47], v[46:47], v[66:67]
	v_pk_mul_f32 v[48:49], v[48:49], v[68:69]
	v_pk_mul_f32 v[54:55], v[46:47], v[54:55]
	v_pk_mul_f32 v[60:61], v[60:61], v[62:63]
	v_pk_mul_f32 v[58:59], v[48:49], v[58:59]
	s_nop 0
	s_nop 0
	v_cvt_pk_bf16_f32 v46, v56, v57
	v_cvt_pk_bf16_f32 v47, v60, v61
	v_cvt_pk_bf16_f32 v48, v54, v55
	v_cvt_pk_bf16_f32 v49, v58, v59
	ds_read_b32 v54, v156 offset:576
	v_add_u32_e32 v55, s30, v138
	v_or_b32_e32 v55, v55, v150
	v_lshlrev_b32_e32 v55, 1, v55
	buffer_store_dwordx4 v[46:49], v55, s[72:75], 0 offen sc1
	s_waitcnt lgkmcnt(0)
	s_nop 0
	v_mul_f32_e32 v46, 0xbfb8aa3b, v54
	v_mul_f32_e32 v47, v54, v54
	v_pk_mul_f32 v[54:55], v[38:39], v[46:47] op_sel_hi:[1,0]
	v_rcp_f32_e32 v56, v47
	v_pk_mul_f32 v[48:49], v[40:41], v[46:47] op_sel_hi:[1,0]
	v_exp_f32_e32 v47, v54
	v_exp_f32_e32 v54, v55
	v_exp_f32_e32 v49, v49
	v_exp_f32_e32 v55, v48
	v_fma_f32 v47, v47, v56, v56
	v_rcp_f32_e32 v48, v47
	v_fma_f32 v47, v54, v56, v56
	v_fma_f32 v49, v49, v56, v56
	v_fma_f32 v54, v55, v56, v56
	v_rcp_f32_e32 v55, v49
	v_rcp_f32_e32 v49, v47
	v_pk_mul_f32 v[38:39], v[38:39], v[50:51]
	v_rcp_f32_e32 v54, v54
	v_pk_mul_f32 v[40:41], v[40:41], v[52:53]
	v_pk_mul_f32 v[38:39], v[38:39], v[48:49]
	v_pk_mul_f32 v[48:49], v[32:33], v[46:47] op_sel_hi:[1,0]
	v_pk_mul_f32 v[46:47], v[30:31], v[46:47] op_sel_hi:[1,0]
	v_exp_f32_e32 v48, v48
	v_exp_f32_e32 v46, v46
	v_exp_f32_e32 v47, v47
	v_exp_f32_e32 v49, v49
	v_fma_f32 v48, v48, v56, v56
	v_fma_f32 v46, v46, v56, v56
	v_fma_f32 v47, v47, v56, v56
	v_fmac_f32_e32 v56, v49, v56
	v_rcp_f32_e32 v46, v46
	v_rcp_f32_e32 v48, v48
	v_rcp_f32_e32 v49, v56
	v_rcp_f32_e32 v47, v47
	v_pk_mul_f32 v[32:33], v[32:33], v[44:45]
	v_pk_mul_f32 v[30:31], v[30:31], v[42:43]
	v_pk_mul_f32 v[40:41], v[40:41], v[54:55]
	v_pk_mul_f32 v[42:43], v[32:33], v[48:49]
	v_pk_mul_f32 v[44:45], v[30:31], v[46:47]
	s_nop 0
	s_nop 0
	v_cvt_pk_bf16_f32 v30, v38, v39
	v_cvt_pk_bf16_f32 v31, v40, v41
	v_cvt_pk_bf16_f32 v32, v44, v45
	v_cvt_pk_bf16_f32 v33, v42, v43
	ds_read_b32 v38, v156 offset:640
	v_add_u32_e32 v39, s30, v140
	v_or_b32_e32 v39, v39, v151
	v_lshlrev_b32_e32 v39, 1, v39
	buffer_store_dwordx4 v[30:33], v39, s[72:75], 0 offen sc1
	s_waitcnt lgkmcnt(0)
	s_nop 0
	v_mul_f32_e32 v30, 0xbfb8aa3b, v38
	v_mul_f32_e32 v31, v38, v38
	v_pk_mul_f32 v[38:39], v[22:23], v[30:31] op_sel_hi:[1,0]
	v_rcp_f32_e32 v40, v31
	v_pk_mul_f32 v[32:33], v[24:25], v[30:31] op_sel_hi:[1,0]
	v_exp_f32_e32 v31, v38
	v_exp_f32_e32 v38, v39
	v_exp_f32_e32 v33, v33
	v_exp_f32_e32 v39, v32
	v_fma_f32 v31, v31, v40, v40
	v_rcp_f32_e32 v32, v31
	v_fma_f32 v31, v38, v40, v40
	v_fma_f32 v33, v33, v40, v40
	v_fma_f32 v38, v39, v40, v40
	v_rcp_f32_e32 v39, v33
	v_rcp_f32_e32 v33, v31
	v_pk_mul_f32 v[22:23], v[22:23], v[34:35]
	v_rcp_f32_e32 v38, v38
	v_pk_mul_f32 v[24:25], v[24:25], v[36:37]
	v_pk_mul_f32 v[22:23], v[22:23], v[32:33]
	v_pk_mul_f32 v[32:33], v[16:17], v[30:31] op_sel_hi:[1,0]
	v_pk_mul_f32 v[30:31], v[14:15], v[30:31] op_sel_hi:[1,0]
	v_exp_f32_e32 v32, v32
	v_exp_f32_e32 v30, v30
	v_exp_f32_e32 v31, v31
	v_exp_f32_e32 v33, v33
	v_fma_f32 v32, v32, v40, v40
	v_fma_f32 v30, v30, v40, v40
	v_fma_f32 v31, v31, v40, v40
	v_fmac_f32_e32 v40, v33, v40
	v_rcp_f32_e32 v30, v30
	v_rcp_f32_e32 v32, v32
	v_rcp_f32_e32 v33, v40
	v_rcp_f32_e32 v31, v31
	v_pk_mul_f32 v[16:17], v[16:17], v[28:29]
	v_pk_mul_f32 v[14:15], v[14:15], v[26:27]
	v_pk_mul_f32 v[24:25], v[24:25], v[38:39]
	v_pk_mul_f32 v[26:27], v[16:17], v[32:33]
	v_pk_mul_f32 v[28:29], v[14:15], v[30:31]
	s_nop 0
	s_nop 0
	v_cvt_pk_bf16_f32 v14, v22, v23
	v_cvt_pk_bf16_f32 v15, v24, v25
	v_cvt_pk_bf16_f32 v16, v28, v29
	v_cvt_pk_bf16_f32 v17, v26, v27
	ds_read_b32 v22, v156 offset:704
	v_add_u32_e32 v23, s30, v142
	v_or_b32_e32 v23, v23, v152
	v_lshlrev_b32_e32 v23, 1, v23
	buffer_store_dwordx4 v[14:17], v23, s[72:75], 0 offen sc1
	s_waitcnt lgkmcnt(0)
	s_nop 0
	v_mul_f32_e32 v14, 0xbfb8aa3b, v22
	v_mul_f32_e32 v15, v22, v22
	v_pk_mul_f32 v[22:23], v[6:7], v[14:15] op_sel_hi:[1,0]
	v_rcp_f32_e32 v24, v15
	v_pk_mul_f32 v[16:17], v[8:9], v[14:15] op_sel_hi:[1,0]
	v_exp_f32_e32 v15, v22
	v_exp_f32_e32 v22, v23
	v_exp_f32_e32 v17, v17
	v_exp_f32_e32 v23, v16
	v_fma_f32 v15, v15, v24, v24
	v_rcp_f32_e32 v16, v15
	v_fma_f32 v15, v22, v24, v24
	v_fma_f32 v17, v17, v24, v24
	v_fma_f32 v22, v23, v24, v24
	v_rcp_f32_e32 v23, v17
	v_rcp_f32_e32 v17, v15
	v_pk_mul_f32 v[6:7], v[6:7], v[18:19]
	v_rcp_f32_e32 v22, v22
	v_pk_mul_f32 v[8:9], v[8:9], v[20:21]
	v_pk_mul_f32 v[6:7], v[6:7], v[16:17]
	v_pk_mul_f32 v[16:17], v[4:5], v[14:15] op_sel_hi:[1,0]
	v_pk_mul_f32 v[14:15], v[2:3], v[14:15] op_sel_hi:[1,0]
	v_exp_f32_e32 v16, v16
	v_exp_f32_e32 v14, v14
	v_exp_f32_e32 v15, v15
	v_exp_f32_e32 v17, v17
	v_fma_f32 v16, v16, v24, v24
	v_fma_f32 v14, v14, v24, v24
	v_fma_f32 v15, v15, v24, v24
	v_rcp_f32_e32 v14, v14
	v_fmac_f32_e32 v24, v17, v24
	v_rcp_f32_e32 v15, v15
	v_rcp_f32_e32 v16, v16
	v_rcp_f32_e32 v17, v24
	v_pk_mul_f32 v[2:3], v[2:3], v[10:11]
	v_pk_mul_f32 v[4:5], v[4:5], v[12:13]
	v_pk_mul_f32 v[12:13], v[2:3], v[14:15]
	v_add_u32_e32 v14, s30, v144
	v_pk_mul_f32 v[8:9], v[8:9], v[22:23]
	v_pk_mul_f32 v[10:11], v[4:5], v[16:17]
	s_mov_b64 s[30:31], -1
	s_nop 0
	v_cvt_pk_bf16_f32 v2, v6, v7
	v_cvt_pk_bf16_f32 v3, v8, v9
	v_cvt_pk_bf16_f32 v4, v12, v13
	v_cvt_pk_bf16_f32 v5, v10, v11
	v_or_b32_e32 v6, v14, v153
	v_lshlrev_b32_e32 v6, 1, v6
	buffer_store_dwordx4 v[2:5], v6, s[72:75], 0 offen sc1
	s_cbranch_scc1 .LBB0_266
	s_andn2_b64 vcc, exec, s[8:9]
	s_cbranch_vccnz .LBB0_265
	s_barrier
	s_branch .LBB0_265

.LBB0_388:
	v_bfe_i32 v3, v150, 27, 1
	v_lshlrev_b32_e32 v1, 4, v150
	v_lshrrev_b32_e32 v3, 22, v3
	v_add_u32_e32 v3, v1, v3
	v_and_b32_e32 v3, 0xfffffc00, v3
	v_sub_u32_e32 v3, v1, v3
	v_ashrrev_i32_e32 v2, 31, v150
	v_lshrrev_b32_e32 v4, 4, v3
	v_lshrrev_b32_e32 v2, 26, v2
	v_bitop3_b32 v3, v4, v3, 32 bitop3:0x6c
	v_add_u32_e32 v2, v150, v2
	v_ashrrev_i32_e32 v5, 31, v3
	v_ashrrev_i32_e32 v2, 6, v2
	v_lshrrev_b32_e32 v5, 26, v5
	v_lshlrev_b32_e32 v4, 3, v2
	v_add_u32_e32 v5, v3, v5
	v_and_b32_e32 v4, -16, v4
	v_ashrrev_i32_e32 v6, 6, v5
	v_add_u32_e32 v138, v6, v4
	v_and_b32_e32 v4, 0xc0, v5
	v_lshlrev_b32_e32 v2, 5, v2
	v_sub_u32_e32 v3, v3, v4
	v_mov_b32_e32 v4, 1
	v_and_b32_e32 v2, 32, v2
	v_ashrrev_i16_sdwa v3, v4, sext(v3) dst_sel:DWORD dst_unused:UNUSED_PAD src0_sel:DWORD src1_sel:BYTE_0
	v_add_u32_sdwa v2, v2, sext(v3) dst_sel:DWORD dst_unused:UNUSED_PAD src0_sel:DWORD src1_sel:WORD_0
	v_and_b32_e32 v9, 0x1fffffe, v138
	v_lshrrev_b32_e32 v139, 5, v2
	v_add_lshl_u32 v2, v139, v9, 6
	v_lshlrev_b32_e32 v9, 5, v138
	v_and_b32_e32 v140, 32, v9
	v_mov_b32_e32 v9, 31
	v_lshlrev_b32_e32 v5, 1, v138
	v_lshrrev_b32_e32 v7, 2, v138
	v_and_b32_e32 v8, 2, v6
	s_mov_b32 s7, 0x1ffffe0
	v_and_b32_sdwa v141, sext(v3), v9 dst_sel:DWORD dst_unused:UNUSED_PAD src0_sel:WORD_0 src1_sel:DWORD
	v_and_b32_e32 v5, 24, v5
	v_and_b32_e32 v7, 4, v7
	v_and_or_b32 v8, v138, s7, v8
	v_or3_b32 v2, v2, v140, v141
	v_lshlrev_b32_e32 v130, 1, v2
	v_or3_b32 v2, v7, v8, v5
	v_lshlrev_b32_e32 v3, 5, v6
	v_add_lshl_u32 v2, v2, v139, 6
	v_and_b32_e32 v3, 32, v3
	v_or3_b32 v2, v2, v3, v141
	v_add_u32_e32 v1, 0x2000, v1
	v_lshlrev_b32_e32 v132, 1, v2
	v_ashrrev_i32_e32 v2, 31, v1
	v_lshrrev_b32_e32 v2, 22, v2
	v_add_u32_e32 v2, v1, v2
	v_ashrrev_i32_e32 v2, 10, v2
	v_mul_i32_i24_e32 v3, 0x400, v2
	v_sub_u32_e32 v1, v1, v3
	v_lshrrev_b32_e32 v3, 4, v1
	v_bitop3_b32 v1, v3, v1, 32 bitop3:0x6c
	v_ashrrev_i32_e32 v5, 31, v1
	v_lshrrev_b32_e32 v5, 26, v5
	v_lshlrev_b32_e32 v3, 3, v2
	v_add_u32_e32 v5, v1, v5
	v_and_b32_e32 v3, -16, v3
	v_ashrrev_i32_e32 v6, 6, v5
	v_add_u32_e32 v142, v6, v3
	v_and_b32_e32 v3, 0xc0, v5
	v_and_b32_e32 v5, 2, v6
	v_and_or_b32 v5, v142, s7, v5
	v_readlane_b32 s7, v252, 7
	s_add_i32 s6, s6, s7
	s_ashr_i32 s7, s6, 31
	v_lshlrev_b32_e32 v2, 5, v2
	v_sub_u32_e32 v1, v1, v3
	s_lshr_b32 s7, s7, 27
	v_and_b32_e32 v2, 32, v2
	v_ashrrev_i16_sdwa v1, v4, sext(v1) dst_sel:DWORD dst_unused:UNUSED_PAD src0_sel:DWORD src1_sel:BYTE_0
	s_add_i32 s7, s6, s7
	v_add_u32_sdwa v2, v2, sext(v1) dst_sel:DWORD dst_unused:UNUSED_PAD src0_sel:DWORD src1_sel:WORD_0
	s_ashr_i32 s8, s7, 5
	v_and_b32_e32 v7, 0x1fffffe, v142
	v_lshrrev_b32_e32 v143, 5, v2
	s_lshl_b32 s8, s8, 3
	v_add_lshl_u32 v2, v143, v7, 6
	v_lshlrev_b32_e32 v7, 5, v142
	s_sub_i32 s9, 64, s8
	v_lshlrev_b32_e32 v3, 1, v142
	v_lshrrev_b32_e32 v4, 2, v142
	v_and_b32_e32 v144, 32, v7
	v_and_b32_sdwa v145, sext(v1), v9 dst_sel:DWORD dst_unused:UNUSED_PAD src0_sel:WORD_0 src1_sel:DWORD
	s_min_i32 s9, s9, 8
	v_and_b32_e32 v3, 24, v3
	v_and_b32_e32 v4, 4, v4
	v_or3_b32 v1, v2, v144, v145
	s_abs_i32 s10, s9
	v_lshlrev_b32_e32 v134, 1, v1
	v_or3_b32 v1, v4, v5, v3
	v_cvt_f32_u32_e32 v3, s10
	v_lshlrev_b32_e32 v2, 5, v6
	v_add_lshl_u32 v1, v1, v143, 6
	v_and_b32_e32 v2, 32, v2
	v_or3_b32 v1, v1, v2, v145
	v_lshlrev_b32_e32 v136, 1, v1
	v_rcp_iflag_f32_e32 v1, v3
	s_sub_i32 s29, 0, s10
	s_andn2_b32 s7, s7, 31
	s_sub_i32 s6, s6, s7
	v_mul_f32_e32 v1, 0x4f7ffffe, v1
	v_cvt_u32_f32_e32 v1, v1
	s_abs_i32 s28, s6
	s_ashr_i32 s5, s11, 6
	s_xor_b32 s7, s6, s9
	v_readfirstlane_b32 s30, v1
	s_mul_i32 s29, s29, s30
	s_mul_hi_u32 s29, s30, s29
	s_add_i32 s30, s30, s29
	s_mul_hi_u32 s29, s28, s30
	s_mul_i32 s30, s29, s10
	s_sub_i32 s28, s28, s30
	s_ashr_i32 s4, s11, 8
	s_lshl_b32 s35, s5, 10
	s_ashr_i32 s7, s7, 31
	s_add_i32 s30, s29, 1
	s_sub_i32 s31, s28, s10
	s_cmp_ge_u32 s28, s10
	s_cselect_b32 s29, s30, s29
	s_cselect_b32 s28, s31, s28
	s_add_i32 s30, s29, 1
	s_cmp_ge_u32 s28, s10
	s_cselect_b32 s10, s30, s29
	s_xor_b32 s10, s10, s7
	s_sub_i32 s10, s10, s7
	s_mul_i32 s7, s10, s9
	s_sub_i32 s6, s6, s7
	s_add_i32 s28, s8, s6
	s_mul_i32 s7, s10, 0x160000
	s_mul_hi_i32 s6, s10, 0x160000
	s_add_u32 s62, s16, s7
	s_addc_u32 s63, s17, s6
	s_add_i32 s37, s35, 0x100
	s_add_i32 m0, s37, 0x10000
	s_nop 0
	global_load_lds_dwordx4 v132, s[62:63] sc1
	s_add_i32 m0, s37, 0x12000
	s_add_u32 s6, s62, 0x4000
	global_load_lds_dwordx4 v136, s[62:63] sc1
	s_addc_u32 s7, s63, 0
	s_add_i32 m0, s37, 0x14000
	s_mul_i32 s9, s28, 0x180000
	global_load_lds_dwordx4 v132, s[6:7] sc1
	s_add_i32 m0, s37, 0x16000
	s_mul_hi_i32 s8, s28, 0x180000
	s_add_u32 s30, s12, s9
	s_addc_u32 s31, s13, s8
	s_add_i32 s39, s37, 0x2000
	global_load_lds_dwordx4 v136, s[6:7] sc1
	s_mov_b32 m0, s37
	s_add_u32 s6, s30, 0x4000
	global_load_lds_dwordx4 v130, s[30:31] sc1
	s_mov_b32 m0, s39
	s_addc_u32 s7, s31, 0
	s_add_i32 s40, s37, 0x4000
	global_load_lds_dwordx4 v134, s[30:31] sc1
	s_mov_b32 m0, s40
	s_add_i32 s41, s37, 0x6000
	global_load_lds_dwordx4 v130, s[6:7] sc1
	s_mov_b32 m0, s41
	v_mov_b32_e32 v133, 0
	global_load_lds_dwordx4 v134, s[6:7] sc1
	s_mov_b32 s46, 0
	v_mov_b32_e32 v137, v133
	v_mov_b32_e32 v131, v133
	s_cmp_lg_u32 s4, 1
	v_mov_b32_e32 v135, v133
	s_cbranch_scc1 .LBB0_390
	s_barrier

.LBB0_403:
	s_add_u32 s61, s62, 0x10000
	s_addc_u32 s69, s63, 0
	s_lshl_b32 s62, s10, 2
	s_ashr_i32 s29, s28, 31
	s_ashr_i32 s63, s62, 31
	s_lshl_b64 s[64:65], s[28:29], 19
	s_lshl_b64 s[62:63], s[62:63], 15
	s_add_u32 s29, s60, s62
	s_addc_u32 s55, s33, s63
	s_add_u32 s29, s29, s64
	s_addc_u32 s55, s55, s65
	s_add_u32 s62, s29, 0x10000
	s_addc_u32 s63, s55, 0
	s_and_b64 s[8:9], s[8:9], exec
	s_cselect_b32 s70, s57, s63
	s_cselect_b32 s71, s56, s62
	s_cselect_b32 s78, s53, s55
	s_cselect_b32 s79, s52, s29
	v_lshl_add_u64 v[146:147], s[30:31], 0, v[138:139]
	v_lshl_add_u64 v[148:149], s[30:31], 0, v[140:141]
	s_mov_b32 s80, -2
	s_mov_b64 s[8:9], 0
	s_add_u32 s29, s30, s8
	v_add_u32_e32 v157, s45, v153
	s_addc_u32 s55, s31, s9
	ds_read_b128 v[162:165], v157
	ds_read_b128 v[166:169], v157 offset:1024
	ds_read_b128 v[170:173], v157 offset:2048
	ds_read_b128 v[174:177], v157 offset:3072
	v_add_u32_e32 v157, s47, v153
	s_add_u32 s29, s29, 0x10000
	ds_read_b128 v[178:181], v157
	ds_read_b128 v[182:185], v157 offset:1024
	ds_read_b128 v[192:195], v157 offset:2048
	ds_read_b128 v[200:203], v157 offset:3072
	s_addc_u32 s55, s55, 0
	s_add_u32 s62, s61, s8
	s_addc_u32 s63, s69, s9
	s_cmp_eq_u32 s8, 0x150000
	s_cselect_b32 s66, s71, s29
	s_cselect_b32 s67, s70, s55
	s_cselect_b32 s64, s79, s62
	s_cselect_b32 s65, s78, s63
	s_add_u32 s62, s66, 0x8000
	s_addc_u32 s63, s67, 0
	s_add_i32 s29, s37, 0xc000
	v_lshl_add_u64 v[158:159], v[146:147], 0, s[8:9]
	s_mov_b32 m0, s29
	s_add_i32 s55, s37, 0xe000
	ds_read_b128 v[204:207], v155
	ds_read_b128 v[208:211], v155 offset:1024
	ds_read_b128 v[212:215], v155 offset:2048
	ds_read_b128 v[216:219], v155 offset:3072
	ds_read_b128 v[220:223], v155 offset:4096
	ds_read_b128 v[224:227], v155 offset:5120
	ds_read_b128 v[228:231], v155 offset:6144
	ds_read_b128 v[232:235], v155 offset:7168
	global_load_lds_dwordx4 v[158:159], off sc1
	v_lshl_add_u64 v[158:159], v[148:149], 0, s[8:9]
	s_mov_b32 m0, s55
	s_nop 0
	global_load_lds_dwordx4 v[158:159], off sc1
	s_waitcnt vmcnt(8)
	s_waitcnt lgkmcnt(0)
	s_setprio 1
	s_barrier
	v_mfma_f32_16x16x32_bf16 v[114:117], v[162:165], v[204:207], 0
	v_mfma_f32_16x16x32_bf16 v[118:121], v[170:173], v[204:207], 0
	v_mfma_f32_16x16x32_bf16 v[98:101], v[162:165], v[212:215], 0
	v_mfma_f32_16x16x32_bf16 v[102:105], v[170:173], v[212:215], 0
	v_mfma_f32_16x16x32_bf16 v[82:85], v[162:165], v[220:223], 0
	v_mfma_f32_16x16x32_bf16 v[86:89], v[170:173], v[220:223], 0
	v_mfma_f32_16x16x32_bf16 v[66:69], v[162:165], v[228:231], 0
	v_mfma_f32_16x16x32_bf16 v[70:73], v[170:173], v[228:231], 0
	v_mfma_f32_16x16x32_bf16 v[114:117], v[166:169], v[208:211], v[114:117]
	v_mfma_f32_16x16x32_bf16 v[118:121], v[174:177], v[208:211], v[118:121]
	v_mfma_f32_16x16x32_bf16 v[98:101], v[166:169], v[216:219], v[98:101]
	v_mfma_f32_16x16x32_bf16 v[102:105], v[174:177], v[216:219], v[102:105]
	v_mfma_f32_16x16x32_bf16 v[82:85], v[166:169], v[224:227], v[82:85]
	v_mfma_f32_16x16x32_bf16 v[86:89], v[174:177], v[224:227], v[86:89]
	v_mfma_f32_16x16x32_bf16 v[66:69], v[166:169], v[232:235], v[66:69]
	v_mfma_f32_16x16x32_bf16 v[70:73], v[174:177], v[232:235], v[70:73]
	v_mfma_f32_16x16x32_bf16 v[122:125], v[178:181], v[204:207], 0
	v_mfma_f32_16x16x32_bf16 v[126:129], v[192:195], v[204:207], 0
	v_mfma_f32_16x16x32_bf16 v[106:109], v[178:181], v[212:215], 0
	v_mfma_f32_16x16x32_bf16 v[110:113], v[192:195], v[212:215], 0
	v_mfma_f32_16x16x32_bf16 v[90:93], v[178:181], v[220:223], 0
	v_mfma_f32_16x16x32_bf16 v[94:97], v[192:195], v[220:223], 0
	v_mfma_f32_16x16x32_bf16 v[74:77], v[178:181], v[228:231], 0
	v_mfma_f32_16x16x32_bf16 v[78:81], v[192:195], v[228:231], 0
	v_mfma_f32_16x16x32_bf16 v[122:125], v[182:185], v[208:211], v[122:125]
	v_mfma_f32_16x16x32_bf16 v[126:129], v[200:203], v[208:211], v[126:129]
	v_mfma_f32_16x16x32_bf16 v[106:109], v[182:185], v[216:219], v[106:109]
	v_mfma_f32_16x16x32_bf16 v[110:113], v[200:203], v[216:219], v[110:113]
	v_mfma_f32_16x16x32_bf16 v[90:93], v[182:185], v[224:227], v[90:93]
	v_mfma_f32_16x16x32_bf16 v[94:97], v[200:203], v[224:227], v[94:97]
	s_setprio 2
	s_barrier
	v_mfma_f32_16x16x32_bf16 v[74:77], v[182:185], v[232:235], v[74:77]
	v_mfma_f32_16x16x32_bf16 v[78:81], v[200:203], v[232:235], v[78:81]
	s_setprio 0
	s_add_i32 s81, s45, s35
	s_mov_b32 m0, s81
	ds_read_b128 v[204:207], v155 offset:16384
	ds_read_b128 v[208:211], v155 offset:17408
	ds_read_b128 v[212:215], v155 offset:18432
	ds_read_b128 v[216:219], v155 offset:19456
	ds_read_b128 v[220:223], v155 offset:20480
	ds_read_b128 v[224:227], v155 offset:21504
	ds_read_b128 v[228:231], v155 offset:22528
	ds_read_b128 v[232:235], v155 offset:23552
	global_load_lds_dwordx4 v132, s[64:65] sc1
	s_add_i32 m0, s81, 0x2000
	s_add_u32 s82, s64, 0x4000
	s_addc_u32 s83, s65, 0
	s_add_i32 s81, s47, s35
	global_load_lds_dwordx4 v136, s[64:65] sc1
	s_mov_b32 m0, s81
	s_nop 0
	global_load_lds_dwordx4 v132, s[82:83] sc1
	s_add_i32 m0, s81, 0x2000
	s_nop 0
	global_load_lds_dwordx4 v136, s[82:83] sc1
	s_mov_b32 m0, s37
	s_nop 0
	global_load_lds_dwordx4 v130, s[66:67] sc1
	s_mov_b32 m0, s39
	s_nop 0
	global_load_lds_dwordx4 v134, s[66:67] sc1
	s_waitcnt vmcnt(8)
	s_waitcnt lgkmcnt(0)
	s_setprio 1
	s_barrier
	v_mfma_f32_16x16x32_bf16 v[50:53], v[162:165], v[204:207], 0
	v_mfma_f32_16x16x32_bf16 v[54:57], v[170:173], v[204:207], 0
	v_mfma_f32_16x16x32_bf16 v[34:37], v[162:165], v[212:215], 0
	v_mfma_f32_16x16x32_bf16 v[38:41], v[170:173], v[212:215], 0
	v_mfma_f32_16x16x32_bf16 v[18:21], v[162:165], v[220:223], 0
	v_mfma_f32_16x16x32_bf16 v[22:25], v[170:173], v[220:223], 0
	v_mfma_f32_16x16x32_bf16 v[2:5], v[162:165], v[228:231], 0
	v_mfma_f32_16x16x32_bf16 v[6:9], v[170:173], v[228:231], 0
	v_mfma_f32_16x16x32_bf16 v[50:53], v[166:169], v[208:211], v[50:53]
	v_mfma_f32_16x16x32_bf16 v[54:57], v[174:177], v[208:211], v[54:57]
	v_mfma_f32_16x16x32_bf16 v[34:37], v[166:169], v[216:219], v[34:37]
	v_mfma_f32_16x16x32_bf16 v[38:41], v[174:177], v[216:219], v[38:41]
	v_mfma_f32_16x16x32_bf16 v[18:21], v[166:169], v[224:227], v[18:21]
	v_mfma_f32_16x16x32_bf16 v[22:25], v[174:177], v[224:227], v[22:25]
	v_mfma_f32_16x16x32_bf16 v[2:5], v[166:169], v[232:235], v[2:5]
	v_mfma_f32_16x16x32_bf16 v[6:9], v[174:177], v[232:235], v[6:9]
	v_mfma_f32_16x16x32_bf16 v[58:61], v[178:181], v[204:207], 0
	v_mfma_f32_16x16x32_bf16 v[62:65], v[192:195], v[204:207], 0
	v_mfma_f32_16x16x32_bf16 v[42:45], v[178:181], v[212:215], 0
	v_mfma_f32_16x16x32_bf16 v[46:49], v[192:195], v[212:215], 0
	v_mfma_f32_16x16x32_bf16 v[26:29], v[178:181], v[220:223], 0
	v_mfma_f32_16x16x32_bf16 v[30:33], v[192:195], v[220:223], 0
	v_mfma_f32_16x16x32_bf16 v[10:13], v[178:181], v[228:231], 0
	v_mfma_f32_16x16x32_bf16 v[14:17], v[192:195], v[228:231], 0
	v_mfma_f32_16x16x32_bf16 v[58:61], v[182:185], v[208:211], v[58:61]
	v_mfma_f32_16x16x32_bf16 v[62:65], v[200:203], v[208:211], v[62:65]
	v_mfma_f32_16x16x32_bf16 v[42:45], v[182:185], v[216:219], v[42:45]
	v_mfma_f32_16x16x32_bf16 v[46:49], v[200:203], v[216:219], v[46:49]
	v_mfma_f32_16x16x32_bf16 v[26:29], v[182:185], v[224:227], v[26:29]
	v_mfma_f32_16x16x32_bf16 v[30:33], v[200:203], v[224:227], v[30:33]
	s_setprio 2
	s_barrier
	v_mfma_f32_16x16x32_bf16 v[10:13], v[182:185], v[232:235], v[10:13]
	v_mfma_f32_16x16x32_bf16 v[14:17], v[200:203], v[232:235], v[14:17]
	s_setprio 0
	v_add_u32_e32 v157, s48, v153
	ds_read_b128 v[162:165], v157
	ds_read_b128 v[166:169], v157 offset:1024
	ds_read_b128 v[170:173], v157 offset:2048
	ds_read_b128 v[174:177], v157 offset:3072
	v_add_u32_e32 v157, s49, v153
	ds_read_b128 v[178:181], v157
	ds_read_b128 v[182:185], v157 offset:1024
	ds_read_b128 v[192:195], v157 offset:2048
	ds_read_b128 v[200:203], v157 offset:3072
	s_add_u32 s66, s66, 0x4000
	s_addc_u32 s67, s67, 0
	s_mov_b32 m0, s40
	ds_read_b128 v[204:207], v155 offset:32768
	ds_read_b128 v[208:211], v155 offset:33792
	ds_read_b128 v[212:215], v155 offset:34816
	ds_read_b128 v[216:219], v155 offset:35840
	ds_read_b128 v[220:223], v155 offset:36864
	ds_read_b128 v[224:227], v155 offset:37888
	ds_read_b128 v[228:231], v155 offset:38912
	ds_read_b128 v[232:235], v155 offset:39936
	global_load_lds_dwordx4 v130, s[66:67] sc1
	s_mov_b32 m0, s41
	s_nop 0
	global_load_lds_dwordx4 v134, s[66:67] sc1
	s_waitcnt vmcnt(8)
	s_waitcnt lgkmcnt(0)
	s_setprio 1
	s_barrier
	v_mfma_f32_16x16x32_bf16 v[114:117], v[162:165], v[204:207], v[114:117]
	v_mfma_f32_16x16x32_bf16 v[118:121], v[170:173], v[204:207], v[118:121]
	v_mfma_f32_16x16x32_bf16 v[98:101], v[162:165], v[212:215], v[98:101]
	v_mfma_f32_16x16x32_bf16 v[102:105], v[170:173], v[212:215], v[102:105]
	v_mfma_f32_16x16x32_bf16 v[82:85], v[162:165], v[220:223], v[82:85]
	v_mfma_f32_16x16x32_bf16 v[86:89], v[170:173], v[220:223], v[86:89]
	v_mfma_f32_16x16x32_bf16 v[66:69], v[162:165], v[228:231], v[66:69]
	v_mfma_f32_16x16x32_bf16 v[70:73], v[170:173], v[228:231], v[70:73]
	v_mfma_f32_16x16x32_bf16 v[114:117], v[166:169], v[208:211], v[114:117]
	v_mfma_f32_16x16x32_bf16 v[118:121], v[174:177], v[208:211], v[118:121]
	v_mfma_f32_16x16x32_bf16 v[98:101], v[166:169], v[216:219], v[98:101]
	v_mfma_f32_16x16x32_bf16 v[102:105], v[174:177], v[216:219], v[102:105]
	v_mfma_f32_16x16x32_bf16 v[82:85], v[166:169], v[224:227], v[82:85]
	v_mfma_f32_16x16x32_bf16 v[86:89], v[174:177], v[224:227], v[86:89]
	v_mfma_f32_16x16x32_bf16 v[66:69], v[166:169], v[232:235], v[66:69]
	v_mfma_f32_16x16x32_bf16 v[70:73], v[174:177], v[232:235], v[70:73]
	v_mfma_f32_16x16x32_bf16 v[122:125], v[178:181], v[204:207], v[122:125]
	v_mfma_f32_16x16x32_bf16 v[126:129], v[192:195], v[204:207], v[126:129]
	v_mfma_f32_16x16x32_bf16 v[106:109], v[178:181], v[212:215], v[106:109]
	v_mfma_f32_16x16x32_bf16 v[110:113], v[192:195], v[212:215], v[110:113]
	v_mfma_f32_16x16x32_bf16 v[90:93], v[178:181], v[220:223], v[90:93]
	v_mfma_f32_16x16x32_bf16 v[94:97], v[192:195], v[220:223], v[94:97]
	v_mfma_f32_16x16x32_bf16 v[74:77], v[178:181], v[228:231], v[74:77]
	v_mfma_f32_16x16x32_bf16 v[78:81], v[192:195], v[228:231], v[78:81]
	v_mfma_f32_16x16x32_bf16 v[122:125], v[182:185], v[208:211], v[122:125]
	v_mfma_f32_16x16x32_bf16 v[126:129], v[200:203], v[208:211], v[126:129]
	v_mfma_f32_16x16x32_bf16 v[106:109], v[182:185], v[216:219], v[106:109]
	v_mfma_f32_16x16x32_bf16 v[110:113], v[200:203], v[216:219], v[110:113]
	v_mfma_f32_16x16x32_bf16 v[90:93], v[182:185], v[224:227], v[90:93]
	v_mfma_f32_16x16x32_bf16 v[94:97], v[200:203], v[224:227], v[94:97]
	s_setprio 2
	s_barrier
	v_mfma_f32_16x16x32_bf16 v[74:77], v[182:185], v[232:235], v[74:77]
	v_mfma_f32_16x16x32_bf16 v[78:81], v[200:203], v[232:235], v[78:81]
	s_setprio 0
	s_add_u32 s66, s64, 0x8000
	s_addc_u32 s67, s65, 0
	s_add_i32 s81, s48, s35
	s_mov_b32 m0, s81
	ds_read_b128 v[204:207], v155 offset:49152
	ds_read_b128 v[208:211], v155 offset:50176
	ds_read_b128 v[212:215], v155 offset:51200
	ds_read_b128 v[216:219], v155 offset:52224
	ds_read_b128 v[220:223], v155 offset:53248
	ds_read_b128 v[224:227], v155 offset:54272
	ds_read_b128 v[228:231], v155 offset:55296
	ds_read_b128 v[232:235], v155 offset:56320
	global_load_lds_dwordx4 v132, s[66:67] sc1
	s_add_i32 m0, s81, 0x2000
	s_add_u32 s64, s64, 0xc000
	global_load_lds_dwordx4 v136, s[66:67] sc1
	s_addc_u32 s65, s65, 0
	s_add_i32 s66, s49, s35
	s_mov_b32 m0, s66
	s_nop 0
	global_load_lds_dwordx4 v132, s[64:65] sc1
	s_add_i32 m0, s66, 0x2000
	s_nop 0
	global_load_lds_dwordx4 v136, s[64:65] sc1
	s_mov_b32 m0, s43
	s_nop 0
	global_load_lds_dwordx4 v130, s[62:63] sc1
	s_mov_b32 m0, s44
	s_nop 0
	global_load_lds_dwordx4 v134, s[62:63] sc1
	s_waitcnt vmcnt(8)
	s_waitcnt lgkmcnt(0)
	s_setprio 1
	s_barrier
	v_mfma_f32_16x16x32_bf16 v[50:53], v[162:165], v[204:207], v[50:53]
	v_mfma_f32_16x16x32_bf16 v[54:57], v[170:173], v[204:207], v[54:57]
	v_mfma_f32_16x16x32_bf16 v[34:37], v[162:165], v[212:215], v[34:37]
	v_mfma_f32_16x16x32_bf16 v[38:41], v[170:173], v[212:215], v[38:41]
	v_mfma_f32_16x16x32_bf16 v[18:21], v[162:165], v[220:223], v[18:21]
	v_mfma_f32_16x16x32_bf16 v[22:25], v[170:173], v[220:223], v[22:25]
	v_mfma_f32_16x16x32_bf16 v[2:5], v[162:165], v[228:231], v[2:5]
	v_mfma_f32_16x16x32_bf16 v[6:9], v[170:173], v[228:231], v[6:9]
	v_mfma_f32_16x16x32_bf16 v[50:53], v[166:169], v[208:211], v[50:53]
	v_mfma_f32_16x16x32_bf16 v[54:57], v[174:177], v[208:211], v[54:57]
	v_mfma_f32_16x16x32_bf16 v[34:37], v[166:169], v[216:219], v[34:37]
	v_mfma_f32_16x16x32_bf16 v[38:41], v[174:177], v[216:219], v[38:41]
	v_mfma_f32_16x16x32_bf16 v[18:21], v[166:169], v[224:227], v[18:21]
	v_mfma_f32_16x16x32_bf16 v[22:25], v[174:177], v[224:227], v[22:25]
	v_mfma_f32_16x16x32_bf16 v[2:5], v[166:169], v[232:235], v[2:5]
	v_mfma_f32_16x16x32_bf16 v[6:9], v[174:177], v[232:235], v[6:9]
	v_mfma_f32_16x16x32_bf16 v[58:61], v[178:181], v[204:207], v[58:61]
	v_mfma_f32_16x16x32_bf16 v[62:65], v[192:195], v[204:207], v[62:65]
	v_mfma_f32_16x16x32_bf16 v[42:45], v[178:181], v[212:215], v[42:45]
	v_mfma_f32_16x16x32_bf16 v[46:49], v[192:195], v[212:215], v[46:49]
	v_mfma_f32_16x16x32_bf16 v[26:29], v[178:181], v[220:223], v[26:29]
	v_mfma_f32_16x16x32_bf16 v[30:33], v[192:195], v[220:223], v[30:33]
	v_mfma_f32_16x16x32_bf16 v[10:13], v[178:181], v[228:231], v[10:13]
	v_mfma_f32_16x16x32_bf16 v[14:17], v[192:195], v[228:231], v[14:17]
	v_mfma_f32_16x16x32_bf16 v[58:61], v[182:185], v[208:211], v[58:61]
	v_mfma_f32_16x16x32_bf16 v[62:65], v[200:203], v[208:211], v[62:65]
	v_mfma_f32_16x16x32_bf16 v[42:45], v[182:185], v[216:219], v[42:45]
	v_mfma_f32_16x16x32_bf16 v[46:49], v[200:203], v[216:219], v[46:49]
	v_mfma_f32_16x16x32_bf16 v[26:29], v[182:185], v[224:227], v[26:29]
	v_mfma_f32_16x16x32_bf16 v[30:33], v[200:203], v[224:227], v[30:33]
	s_setprio 2
	s_barrier
	v_mfma_f32_16x16x32_bf16 v[10:13], v[182:185], v[232:235], v[10:13]
	v_mfma_f32_16x16x32_bf16 v[14:17], v[200:203], v[232:235], v[14:17]
	s_setprio 0
	s_add_i32 s80, s80, 2
	s_add_u32 s8, s8, 0x10000
	s_addc_u32 s9, s9, 0
	s_cmp_gt_u32 s80, 41
.LBB0_404:
	s_add_u32 s29, s30, s8
	v_add_u32_e32 v157, s45, v153
	s_addc_u32 s55, s31, s9
	ds_read_b128 v[162:165], v157
	ds_read_b128 v[166:169], v157 offset:1024
	ds_read_b128 v[170:173], v157 offset:2048
	ds_read_b128 v[174:177], v157 offset:3072
	v_add_u32_e32 v157, s47, v153
	s_add_u32 s29, s29, 0x10000
	ds_read_b128 v[178:181], v157
	ds_read_b128 v[182:185], v157 offset:1024
	ds_read_b128 v[192:195], v157 offset:2048
	ds_read_b128 v[200:203], v157 offset:3072
	s_addc_u32 s55, s55, 0
	s_add_u32 s62, s61, s8
	s_addc_u32 s63, s69, s9
	s_cmp_eq_u32 s8, 0x150000
	s_cselect_b32 s66, s71, s29
	s_cselect_b32 s67, s70, s55
	s_cselect_b32 s64, s79, s62
	s_cselect_b32 s65, s78, s63
	s_add_u32 s62, s66, 0x8000
	s_addc_u32 s63, s67, 0
	s_add_i32 s29, s37, 0xc000
	v_lshl_add_u64 v[158:159], v[146:147], 0, s[8:9]
	s_mov_b32 m0, s29
	s_add_i32 s55, s37, 0xe000
	ds_read_b128 v[204:207], v155
	ds_read_b128 v[208:211], v155 offset:1024
	ds_read_b128 v[212:215], v155 offset:2048
	ds_read_b128 v[216:219], v155 offset:3072
	ds_read_b128 v[220:223], v155 offset:4096
	ds_read_b128 v[224:227], v155 offset:5120
	ds_read_b128 v[228:231], v155 offset:6144
	ds_read_b128 v[232:235], v155 offset:7168
	global_load_lds_dwordx4 v[158:159], off sc1
	v_lshl_add_u64 v[158:159], v[148:149], 0, s[8:9]
	s_mov_b32 m0, s55
	s_nop 0
	global_load_lds_dwordx4 v[158:159], off sc1
	s_waitcnt vmcnt(8)
	s_waitcnt lgkmcnt(0)
	s_setprio 1
	s_barrier
	v_mfma_f32_16x16x32_bf16 v[114:117], v[162:165], v[204:207], v[114:117]
	v_mfma_f32_16x16x32_bf16 v[118:121], v[170:173], v[204:207], v[118:121]
	v_mfma_f32_16x16x32_bf16 v[98:101], v[162:165], v[212:215], v[98:101]
	v_mfma_f32_16x16x32_bf16 v[102:105], v[170:173], v[212:215], v[102:105]
	v_mfma_f32_16x16x32_bf16 v[82:85], v[162:165], v[220:223], v[82:85]
	v_mfma_f32_16x16x32_bf16 v[86:89], v[170:173], v[220:223], v[86:89]
	v_mfma_f32_16x16x32_bf16 v[66:69], v[162:165], v[228:231], v[66:69]
	v_mfma_f32_16x16x32_bf16 v[70:73], v[170:173], v[228:231], v[70:73]
	v_mfma_f32_16x16x32_bf16 v[114:117], v[166:169], v[208:211], v[114:117]
	v_mfma_f32_16x16x32_bf16 v[118:121], v[174:177], v[208:211], v[118:121]
	v_mfma_f32_16x16x32_bf16 v[98:101], v[166:169], v[216:219], v[98:101]
	v_mfma_f32_16x16x32_bf16 v[102:105], v[174:177], v[216:219], v[102:105]
	v_mfma_f32_16x16x32_bf16 v[82:85], v[166:169], v[224:227], v[82:85]
	v_mfma_f32_16x16x32_bf16 v[86:89], v[174:177], v[224:227], v[86:89]
	v_mfma_f32_16x16x32_bf16 v[66:69], v[166:169], v[232:235], v[66:69]
	v_mfma_f32_16x16x32_bf16 v[70:73], v[174:177], v[232:235], v[70:73]
	v_mfma_f32_16x16x32_bf16 v[122:125], v[178:181], v[204:207], v[122:125]
	v_mfma_f32_16x16x32_bf16 v[126:129], v[192:195], v[204:207], v[126:129]
	v_mfma_f32_16x16x32_bf16 v[106:109], v[178:181], v[212:215], v[106:109]
	v_mfma_f32_16x16x32_bf16 v[110:113], v[192:195], v[212:215], v[110:113]
	v_mfma_f32_16x16x32_bf16 v[90:93], v[178:181], v[220:223], v[90:93]
	v_mfma_f32_16x16x32_bf16 v[94:97], v[192:195], v[220:223], v[94:97]
	v_mfma_f32_16x16x32_bf16 v[74:77], v[178:181], v[228:231], v[74:77]
	v_mfma_f32_16x16x32_bf16 v[78:81], v[192:195], v[228:231], v[78:81]
	v_mfma_f32_16x16x32_bf16 v[122:125], v[182:185], v[208:211], v[122:125]
	v_mfma_f32_16x16x32_bf16 v[126:129], v[200:203], v[208:211], v[126:129]
	v_mfma_f32_16x16x32_bf16 v[106:109], v[182:185], v[216:219], v[106:109]
	v_mfma_f32_16x16x32_bf16 v[110:113], v[200:203], v[216:219], v[110:113]
	v_mfma_f32_16x16x32_bf16 v[90:93], v[182:185], v[224:227], v[90:93]
	v_mfma_f32_16x16x32_bf16 v[94:97], v[200:203], v[224:227], v[94:97]
	s_setprio 2
	s_barrier
	v_mfma_f32_16x16x32_bf16 v[74:77], v[182:185], v[232:235], v[74:77]
	v_mfma_f32_16x16x32_bf16 v[78:81], v[200:203], v[232:235], v[78:81]
	s_setprio 0
	s_add_i32 s81, s45, s35
	s_mov_b32 m0, s81
	ds_read_b128 v[204:207], v155 offset:16384
	ds_read_b128 v[208:211], v155 offset:17408
	ds_read_b128 v[212:215], v155 offset:18432
	ds_read_b128 v[216:219], v155 offset:19456
	ds_read_b128 v[220:223], v155 offset:20480
	ds_read_b128 v[224:227], v155 offset:21504
	ds_read_b128 v[228:231], v155 offset:22528
	ds_read_b128 v[232:235], v155 offset:23552
	global_load_lds_dwordx4 v132, s[64:65] sc1
	s_add_i32 m0, s81, 0x2000
	s_add_u32 s82, s64, 0x4000
	s_addc_u32 s83, s65, 0
	s_add_i32 s81, s47, s35
	global_load_lds_dwordx4 v136, s[64:65] sc1
	s_mov_b32 m0, s81
	s_nop 0
	global_load_lds_dwordx4 v132, s[82:83] sc1
	s_add_i32 m0, s81, 0x2000
	s_nop 0
	global_load_lds_dwordx4 v136, s[82:83] sc1
	s_mov_b32 m0, s37
	s_nop 0
	global_load_lds_dwordx4 v130, s[66:67] sc1
	s_mov_b32 m0, s39
	s_nop 0
	global_load_lds_dwordx4 v134, s[66:67] sc1
	s_waitcnt vmcnt(8)
	s_waitcnt lgkmcnt(0)
	s_setprio 1
	s_barrier
	v_mfma_f32_16x16x32_bf16 v[50:53], v[162:165], v[204:207], v[50:53]
	v_mfma_f32_16x16x32_bf16 v[54:57], v[170:173], v[204:207], v[54:57]
	v_mfma_f32_16x16x32_bf16 v[34:37], v[162:165], v[212:215], v[34:37]
	v_mfma_f32_16x16x32_bf16 v[38:41], v[170:173], v[212:215], v[38:41]
	v_mfma_f32_16x16x32_bf16 v[18:21], v[162:165], v[220:223], v[18:21]
	v_mfma_f32_16x16x32_bf16 v[22:25], v[170:173], v[220:223], v[22:25]
	v_mfma_f32_16x16x32_bf16 v[2:5], v[162:165], v[228:231], v[2:5]
	v_mfma_f32_16x16x32_bf16 v[6:9], v[170:173], v[228:231], v[6:9]
	v_mfma_f32_16x16x32_bf16 v[50:53], v[166:169], v[208:211], v[50:53]
	v_mfma_f32_16x16x32_bf16 v[54:57], v[174:177], v[208:211], v[54:57]
	v_mfma_f32_16x16x32_bf16 v[34:37], v[166:169], v[216:219], v[34:37]
	v_mfma_f32_16x16x32_bf16 v[38:41], v[174:177], v[216:219], v[38:41]
	v_mfma_f32_16x16x32_bf16 v[18:21], v[166:169], v[224:227], v[18:21]
	v_mfma_f32_16x16x32_bf16 v[22:25], v[174:177], v[224:227], v[22:25]
	v_mfma_f32_16x16x32_bf16 v[2:5], v[166:169], v[232:235], v[2:5]
	v_mfma_f32_16x16x32_bf16 v[6:9], v[174:177], v[232:235], v[6:9]
	v_mfma_f32_16x16x32_bf16 v[58:61], v[178:181], v[204:207], v[58:61]
	v_mfma_f32_16x16x32_bf16 v[62:65], v[192:195], v[204:207], v[62:65]
	v_mfma_f32_16x16x32_bf16 v[42:45], v[178:181], v[212:215], v[42:45]
	v_mfma_f32_16x16x32_bf16 v[46:49], v[192:195], v[212:215], v[46:49]
	v_mfma_f32_16x16x32_bf16 v[26:29], v[178:181], v[220:223], v[26:29]
	v_mfma_f32_16x16x32_bf16 v[30:33], v[192:195], v[220:223], v[30:33]
	v_mfma_f32_16x16x32_bf16 v[10:13], v[178:181], v[228:231], v[10:13]
	v_mfma_f32_16x16x32_bf16 v[14:17], v[192:195], v[228:231], v[14:17]
	v_mfma_f32_16x16x32_bf16 v[58:61], v[182:185], v[208:211], v[58:61]
	v_mfma_f32_16x16x32_bf16 v[62:65], v[200:203], v[208:211], v[62:65]
	v_mfma_f32_16x16x32_bf16 v[42:45], v[182:185], v[216:219], v[42:45]
	v_mfma_f32_16x16x32_bf16 v[46:49], v[200:203], v[216:219], v[46:49]
	v_mfma_f32_16x16x32_bf16 v[26:29], v[182:185], v[224:227], v[26:29]
	v_mfma_f32_16x16x32_bf16 v[30:33], v[200:203], v[224:227], v[30:33]
	s_setprio 2
	s_barrier
	v_mfma_f32_16x16x32_bf16 v[10:13], v[182:185], v[232:235], v[10:13]
	v_mfma_f32_16x16x32_bf16 v[14:17], v[200:203], v[232:235], v[14:17]
	s_setprio 0
	v_add_u32_e32 v157, s48, v153
	ds_read_b128 v[162:165], v157
	ds_read_b128 v[166:169], v157 offset:1024
	ds_read_b128 v[170:173], v157 offset:2048
	ds_read_b128 v[174:177], v157 offset:3072
	v_add_u32_e32 v157, s49, v153
	ds_read_b128 v[178:181], v157
	ds_read_b128 v[182:185], v157 offset:1024
	ds_read_b128 v[192:195], v157 offset:2048
	ds_read_b128 v[200:203], v157 offset:3072
	s_add_u32 s66, s66, 0x4000
	s_addc_u32 s67, s67, 0
	s_mov_b32 m0, s40
	ds_read_b128 v[204:207], v155 offset:32768
	ds_read_b128 v[208:211], v155 offset:33792
	ds_read_b128 v[212:215], v155 offset:34816
	ds_read_b128 v[216:219], v155 offset:35840
	ds_read_b128 v[220:223], v155 offset:36864
	ds_read_b128 v[224:227], v155 offset:37888
	ds_read_b128 v[228:231], v155 offset:38912
	ds_read_b128 v[232:235], v155 offset:39936
	global_load_lds_dwordx4 v130, s[66:67] sc1
	s_mov_b32 m0, s41
	s_nop 0
	global_load_lds_dwordx4 v134, s[66:67] sc1
	s_waitcnt vmcnt(8)
	s_waitcnt lgkmcnt(0)
	s_setprio 1
	s_barrier
	v_mfma_f32_16x16x32_bf16 v[114:117], v[162:165], v[204:207], v[114:117]
	v_mfma_f32_16x16x32_bf16 v[118:121], v[170:173], v[204:207], v[118:121]
	v_mfma_f32_16x16x32_bf16 v[98:101], v[162:165], v[212:215], v[98:101]
	v_mfma_f32_16x16x32_bf16 v[102:105], v[170:173], v[212:215], v[102:105]
	v_mfma_f32_16x16x32_bf16 v[82:85], v[162:165], v[220:223], v[82:85]
	v_mfma_f32_16x16x32_bf16 v[86:89], v[170:173], v[220:223], v[86:89]
	v_mfma_f32_16x16x32_bf16 v[66:69], v[162:165], v[228:231], v[66:69]
	v_mfma_f32_16x16x32_bf16 v[70:73], v[170:173], v[228:231], v[70:73]
	v_mfma_f32_16x16x32_bf16 v[114:117], v[166:169], v[208:211], v[114:117]
	v_mfma_f32_16x16x32_bf16 v[118:121], v[174:177], v[208:211], v[118:121]
	v_mfma_f32_16x16x32_bf16 v[98:101], v[166:169], v[216:219], v[98:101]
	v_mfma_f32_16x16x32_bf16 v[102:105], v[174:177], v[216:219], v[102:105]
	v_mfma_f32_16x16x32_bf16 v[82:85], v[166:169], v[224:227], v[82:85]
	v_mfma_f32_16x16x32_bf16 v[86:89], v[174:177], v[224:227], v[86:89]
	v_mfma_f32_16x16x32_bf16 v[66:69], v[166:169], v[232:235], v[66:69]
	v_mfma_f32_16x16x32_bf16 v[70:73], v[174:177], v[232:235], v[70:73]
	v_mfma_f32_16x16x32_bf16 v[122:125], v[178:181], v[204:207], v[122:125]
	v_mfma_f32_16x16x32_bf16 v[126:129], v[192:195], v[204:207], v[126:129]
	v_mfma_f32_16x16x32_bf16 v[106:109], v[178:181], v[212:215], v[106:109]
	v_mfma_f32_16x16x32_bf16 v[110:113], v[192:195], v[212:215], v[110:113]
	v_mfma_f32_16x16x32_bf16 v[90:93], v[178:181], v[220:223], v[90:93]
	v_mfma_f32_16x16x32_bf16 v[94:97], v[192:195], v[220:223], v[94:97]
	v_mfma_f32_16x16x32_bf16 v[74:77], v[178:181], v[228:231], v[74:77]
	v_mfma_f32_16x16x32_bf16 v[78:81], v[192:195], v[228:231], v[78:81]
	v_mfma_f32_16x16x32_bf16 v[122:125], v[182:185], v[208:211], v[122:125]
	v_mfma_f32_16x16x32_bf16 v[126:129], v[200:203], v[208:211], v[126:129]
	v_mfma_f32_16x16x32_bf16 v[106:109], v[182:185], v[216:219], v[106:109]
	v_mfma_f32_16x16x32_bf16 v[110:113], v[200:203], v[216:219], v[110:113]
	v_mfma_f32_16x16x32_bf16 v[90:93], v[182:185], v[224:227], v[90:93]
	v_mfma_f32_16x16x32_bf16 v[94:97], v[200:203], v[224:227], v[94:97]
	s_setprio 2
	s_barrier
	v_mfma_f32_16x16x32_bf16 v[74:77], v[182:185], v[232:235], v[74:77]
	v_mfma_f32_16x16x32_bf16 v[78:81], v[200:203], v[232:235], v[78:81]
	s_setprio 0
	s_add_u32 s66, s64, 0x8000
	s_addc_u32 s67, s65, 0
	s_add_i32 s81, s48, s35
	s_mov_b32 m0, s81
	ds_read_b128 v[204:207], v155 offset:49152
	ds_read_b128 v[208:211], v155 offset:50176
	ds_read_b128 v[212:215], v155 offset:51200
	ds_read_b128 v[216:219], v155 offset:52224
	ds_read_b128 v[220:223], v155 offset:53248
	ds_read_b128 v[224:227], v155 offset:54272
	ds_read_b128 v[228:231], v155 offset:55296
	ds_read_b128 v[232:235], v155 offset:56320
	global_load_lds_dwordx4 v132, s[66:67] sc1
	s_add_i32 m0, s81, 0x2000
	s_add_u32 s64, s64, 0xc000
	global_load_lds_dwordx4 v136, s[66:67] sc1
	s_addc_u32 s65, s65, 0
	s_add_i32 s66, s49, s35
	s_mov_b32 m0, s66
	s_nop 0
	global_load_lds_dwordx4 v132, s[64:65] sc1
	s_add_i32 m0, s66, 0x2000
	s_nop 0
	global_load_lds_dwordx4 v136, s[64:65] sc1
	s_mov_b32 m0, s43
	s_nop 0
	global_load_lds_dwordx4 v130, s[62:63] sc1
	s_mov_b32 m0, s44
	s_nop 0
	global_load_lds_dwordx4 v134, s[62:63] sc1
	s_waitcnt vmcnt(8)
	s_waitcnt lgkmcnt(0)
	s_setprio 1
	s_barrier
	v_mfma_f32_16x16x32_bf16 v[50:53], v[162:165], v[204:207], v[50:53]
	v_mfma_f32_16x16x32_bf16 v[54:57], v[170:173], v[204:207], v[54:57]
	v_mfma_f32_16x16x32_bf16 v[34:37], v[162:165], v[212:215], v[34:37]
	v_mfma_f32_16x16x32_bf16 v[38:41], v[170:173], v[212:215], v[38:41]
	v_mfma_f32_16x16x32_bf16 v[18:21], v[162:165], v[220:223], v[18:21]
	v_mfma_f32_16x16x32_bf16 v[22:25], v[170:173], v[220:223], v[22:25]
	v_mfma_f32_16x16x32_bf16 v[2:5], v[162:165], v[228:231], v[2:5]
	v_mfma_f32_16x16x32_bf16 v[6:9], v[170:173], v[228:231], v[6:9]
	v_mfma_f32_16x16x32_bf16 v[50:53], v[166:169], v[208:211], v[50:53]
	v_mfma_f32_16x16x32_bf16 v[54:57], v[174:177], v[208:211], v[54:57]
	v_mfma_f32_16x16x32_bf16 v[34:37], v[166:169], v[216:219], v[34:37]
	v_mfma_f32_16x16x32_bf16 v[38:41], v[174:177], v[216:219], v[38:41]
	v_mfma_f32_16x16x32_bf16 v[18:21], v[166:169], v[224:227], v[18:21]
	v_mfma_f32_16x16x32_bf16 v[22:25], v[174:177], v[224:227], v[22:25]
	v_mfma_f32_16x16x32_bf16 v[2:5], v[166:169], v[232:235], v[2:5]
	v_mfma_f32_16x16x32_bf16 v[6:9], v[174:177], v[232:235], v[6:9]
	v_mfma_f32_16x16x32_bf16 v[58:61], v[178:181], v[204:207], v[58:61]
	v_mfma_f32_16x16x32_bf16 v[62:65], v[192:195], v[204:207], v[62:65]
	v_mfma_f32_16x16x32_bf16 v[42:45], v[178:181], v[212:215], v[42:45]
	v_mfma_f32_16x16x32_bf16 v[46:49], v[192:195], v[212:215], v[46:49]
	v_mfma_f32_16x16x32_bf16 v[26:29], v[178:181], v[220:223], v[26:29]
	v_mfma_f32_16x16x32_bf16 v[30:33], v[192:195], v[220:223], v[30:33]
	v_mfma_f32_16x16x32_bf16 v[10:13], v[178:181], v[228:231], v[10:13]
	v_mfma_f32_16x16x32_bf16 v[14:17], v[192:195], v[228:231], v[14:17]
	v_mfma_f32_16x16x32_bf16 v[58:61], v[182:185], v[208:211], v[58:61]
	v_mfma_f32_16x16x32_bf16 v[62:65], v[200:203], v[208:211], v[62:65]
	v_mfma_f32_16x16x32_bf16 v[42:45], v[182:185], v[216:219], v[42:45]
	v_mfma_f32_16x16x32_bf16 v[46:49], v[200:203], v[216:219], v[46:49]
	v_mfma_f32_16x16x32_bf16 v[26:29], v[182:185], v[224:227], v[26:29]
	v_mfma_f32_16x16x32_bf16 v[30:33], v[200:203], v[224:227], v[30:33]
	s_setprio 2
	s_barrier
	v_mfma_f32_16x16x32_bf16 v[10:13], v[182:185], v[232:235], v[10:13]
	v_mfma_f32_16x16x32_bf16 v[14:17], v[200:203], v[232:235], v[14:17]
	s_setprio 0
	s_add_i32 s80, s80, 2
	s_add_u32 s8, s8, 0x10000
	s_addc_u32 s9, s9, 0
	s_cmp_gt_u32 s80, 41
	s_cbranch_scc0 .LBB0_404
	s_add_u32 s8, s61, 0xffff0000
	s_addc_u32 s9, s69, -1
	s_and_b64 vcc, exec, s[6:7]
	s_cbranch_vccnz .LBB0_391
	s_mov_b32 s10, s50
	s_mov_b32 s28, s51
	s_mov_b64 s[30:31], s[56:57]
	s_mov_b32 s46, s54
	s_andn2_b64 vcc, exec, s[4:5]
	s_cbranch_vccnz .LBB0_392

.LBB0_454:
	v_writelane_b32 v252, s86, 3
	s_nop 1
	v_writelane_b32 v252, s87, 4
	s_or_b64 exec, exec, s[4:5]
	v_mov_b32_e32 v139, v188
	s_waitcnt lgkmcnt(0)
	s_barrier
	v_writelane_b32 v252, s16, 27
	v_ashrrev_i32_e32 v1, 31, v139
	v_lshrrev_b32_e32 v1, 26, v1
	v_add_u32_e32 v1, v139, v1
	v_ashrrev_i32_e32 v3, 6, v1
	v_bfe_i32 v1, v139, 27, 1
	v_lshlrev_b32_e32 v2, 4, v139
	v_lshrrev_b32_e32 v1, 22, v1
	v_add_u32_e32 v1, v2, v1
	v_and_b32_e32 v1, 0xfffffc00, v1
	v_sub_u32_e32 v1, v2, v1
	v_lshrrev_b32_e32 v4, 4, v1
	v_bitop3_b32 v4, v4, v1, 32 bitop3:0x6c
	v_lshlrev_b32_e32 v1, 3, v3
	v_and_b32_e32 v5, -16, v1
	v_ashrrev_i32_e32 v1, 31, v4
	v_lshrrev_b32_e32 v1, 26, v1
	v_add_u32_e32 v6, v4, v1
	v_ashrrev_i32_e32 v1, 6, v6
	v_add_u32_e32 v130, v1, v5
	v_and_b32_e32 v5, 0xc0, v6
	v_lshlrev_b32_e32 v3, 5, v3
	v_sub_u32_e32 v4, v4, v5
	v_mov_b32_e32 v5, 1
	v_and_b32_e32 v3, 32, v3
	v_ashrrev_i16_sdwa v4, v5, sext(v4) dst_sel:DWORD dst_unused:UNUSED_PAD src0_sel:DWORD src1_sel:BYTE_0
	v_add_u32_sdwa v3, v3, sext(v4) dst_sel:DWORD dst_unused:UNUSED_PAD src0_sel:DWORD src1_sel:WORD_0
	v_lshrrev_b32_e32 v131, 5, v3
	v_mov_b32_e32 v3, 31
	v_add_u32_e32 v2, 0x2000, v2
	v_and_b32_sdwa v132, sext(v4), v3 dst_sel:DWORD dst_unused:UNUSED_PAD src0_sel:WORD_0 src1_sel:DWORD
	v_ashrrev_i32_e32 v4, 31, v2
	v_lshrrev_b32_e32 v4, 22, v4
	v_add_u32_e32 v4, v2, v4
	v_ashrrev_i32_e32 v4, 10, v4
	v_mul_i32_i24_e32 v6, 0x400, v4
	v_sub_u32_e32 v2, v2, v6
	v_lshrrev_b32_e32 v6, 4, v2
	v_bitop3_b32 v2, v6, v2, 32 bitop3:0x6c
	v_ashrrev_i32_e32 v7, 31, v2
	v_lshrrev_b32_e32 v7, 26, v7
	v_lshlrev_b32_e32 v6, 3, v4
	v_add_u32_e32 v7, v2, v7
	v_and_b32_e32 v6, -16, v6
	v_ashrrev_i32_e32 v140, 6, v7
	v_add_u32_e32 v133, v140, v6
	v_and_b32_e32 v6, 0xc0, v7
	v_lshlrev_b32_e32 v4, 5, v4
	v_sub_u32_e32 v2, v2, v6
	v_and_b32_e32 v4, 32, v4
	v_ashrrev_i16_sdwa v2, v5, sext(v2) dst_sel:DWORD dst_unused:UNUSED_PAD src0_sel:DWORD src1_sel:BYTE_0
	v_add_u32_sdwa v4, v4, sext(v2) dst_sel:DWORD dst_unused:UNUSED_PAD src0_sel:DWORD src1_sel:WORD_0
	v_lshrrev_b32_e32 v137, 5, v4
	v_and_b32_sdwa v136, sext(v2), v3 dst_sel:DWORD dst_unused:UNUSED_PAD src0_sel:WORD_0 src1_sel:DWORD
	v_and_b32_e32 v2, 0x1fffffe, v133
	v_lshlrev_b32_e32 v3, 5, v133
	v_add_lshl_u32 v2, v137, v2, 6
	v_and_b32_e32 v138, 32, v3
	v_readfirstlane_b32 s4, v139
	v_or3_b32 v2, v2, v138, v136
	v_writelane_b32 v252, s17, 28
	s_ashr_i32 s5, s4, 6
	v_lshlrev_b32_e32 v148, 1, v2
	v_and_b32_e32 v2, 0x1fffffe, v130
	v_lshlrev_b32_e32 v3, 5, v130
	v_writelane_b32 v253, s88, 63
	s_lshl_b32 s61, s5, 10
	v_add_lshl_u32 v2, v131, v2, 6
	v_writelane_b32 v252, s89, 0
	v_and_b32_e32 v134, 32, v3
	v_writelane_b32 v252, s90, 1
	v_or3_b32 v2, v2, v134, v132
	s_add_i32 s69, s61, 0x100
	v_writelane_b32 v252, s91, 2
	v_lshlrev_b32_e32 v150, 1, v2
	s_mov_b32 m0, s69
	s_add_i32 s77, s69, 0x2000
	global_load_lds_dwordx4 v150, s[0:1] sc1
	s_mov_b32 m0, s77
	s_add_i32 s86, s69, 0x4000
	v_readlane_b32 s8, v252, 17
	global_load_lds_dwordx4 v148, s[0:1] sc1
	s_mov_b32 m0, s86
	v_readlane_b32 s9, v252, 18
	s_add_i32 s87, s69, 0x6000
	v_mov_b32_e32 v135, 0
	v_mov_b32_e32 v151, v135
	v_mov_b32_e32 v149, v135
	s_nop 0
	global_load_lds_dwordx4 v150, s[8:9] sc1
	s_mov_b32 m0, s87
	s_nop 0
	global_load_lds_dwordx4 v148, s[8:9] sc1
	s_ashr_i32 s8, s4, 8
	s_cmp_eq_u32 s8, 1
	s_cselect_b64 s[66:67], -1, 0
	s_cmp_lg_u32 s8, 1
	s_cbranch_scc1 .LBB0_456
	s_barrier

.LBB0_459:
	s_mov_b32 s40, s38
	s_add_i32 s38, s38, 1
	s_cmp_lt_u32 s38, s7
	s_mov_b32 s35, s39
	s_cselect_b64 s[42:43], -1, 0
	s_add_i32 s39, s38, s6
	s_and_b64 s[44:45], s[42:43], exec
	s_cselect_b32 s46, s58, s58
	s_cselect_b32 s44, s39, s35
	s_ashr_i32 s47, s46, 31
	s_lshl_b64 s[46:47], s[46:47], 19
	s_mov_b64 s[4:5], s[82:83]
	s_add_u32 s82, s60, s46
	s_addc_u32 s83, s33, s47
	s_and_b64 s[46:47], s[42:43], exec
	s_cselect_b32 s35, s83, s5
	s_cselect_b32 s41, s82, s4
	s_ashr_i32 s45, s44, 31
	s_lshl_b64 s[44:45], s[44:45], 19
	v_readlane_b32 s12, v253, 61
	s_mov_b64 s[8:9], s[62:63]
	v_readlane_b32 s13, v253, 62
	s_add_u32 s62, s12, s44
	s_addc_u32 s63, s13, s45
	s_and_b64 s[42:43], s[42:43], exec
	s_cselect_b32 s42, s63, s9
	s_cselect_b32 s43, s62, s8
	s_add_u32 s44, s8, 0x10000
	s_addc_u32 s45, s9, 0
	s_mov_b32 s46, -2
	v_add_u32_e32 v134, s95, v1
	ds_read_b128 v[130:133], v134
	ds_read_b128 v[136:139], v134 offset:1024
	ds_read_b128 v[140:143], v134 offset:2048
	ds_read_b128 v[144:147], v134 offset:3072
	v_add_u32_e32 v134, s93, v1
	ds_read_b128 v[170:173], v134
	ds_read_b128 v[200:203], v134 offset:1024
	ds_read_b128 v[204:207], v134 offset:2048
	ds_read_b128 v[208:211], v134 offset:3072
	s_add_u32 s8, s4, 0x10000
	s_addc_u32 s9, s5, 0
	s_cmp_eq_u32 s46, 12
	s_cselect_b32 s84, s41, s8
	s_cselect_b32 s85, s35, s9
	s_cselect_b32 s64, s43, s44
	s_cselect_b32 s65, s42, s45
	s_add_u32 s56, s84, 0x8000
	s_addc_u32 s57, s85, 0
	s_add_i32 m0, s69, 0xc000
	ds_read_b128 v[212:215], v194
	ds_read_b128 v[216:219], v194 offset:1024
	ds_read_b128 v[220:223], v194 offset:2048
	ds_read_b128 v[224:227], v194 offset:3072
	ds_read_b128 v[228:231], v194 offset:4096
	ds_read_b128 v[232:235], v194 offset:5120
	ds_read_b128 v[236:239], v194 offset:6144
	ds_read_b128 v[240:243], v194 offset:7168
	global_load_lds_dwordx4 v166, s[4:5] sc1
	s_add_i32 m0, s69, 0xe000
	s_nop 0
	global_load_lds_dwordx4 v168, s[4:5] sc1
	s_waitcnt vmcnt(8)
	s_waitcnt lgkmcnt(0)
	s_setprio 1
	s_barrier
	v_mfma_f32_16x16x32_bf16 v[122:125], v[130:133], v[212:215], 0
	v_mfma_f32_16x16x32_bf16 v[126:129], v[140:143], v[212:215], 0
	v_mfma_f32_16x16x32_bf16 v[106:109], v[130:133], v[220:223], 0
	v_mfma_f32_16x16x32_bf16 v[110:113], v[140:143], v[220:223], 0
	v_mfma_f32_16x16x32_bf16 v[90:93], v[130:133], v[228:231], 0
	v_mfma_f32_16x16x32_bf16 v[94:97], v[140:143], v[228:231], 0
	v_mfma_f32_16x16x32_bf16 v[74:77], v[130:133], v[236:239], 0
	v_mfma_f32_16x16x32_bf16 v[78:81], v[140:143], v[236:239], 0
	v_mfma_f32_16x16x32_bf16 v[122:125], v[136:139], v[216:219], v[122:125]
	v_mfma_f32_16x16x32_bf16 v[126:129], v[144:147], v[216:219], v[126:129]
	v_mfma_f32_16x16x32_bf16 v[106:109], v[136:139], v[224:227], v[106:109]
	v_mfma_f32_16x16x32_bf16 v[110:113], v[144:147], v[224:227], v[110:113]
	v_mfma_f32_16x16x32_bf16 v[90:93], v[136:139], v[232:235], v[90:93]
	v_mfma_f32_16x16x32_bf16 v[94:97], v[144:147], v[232:235], v[94:97]
	v_mfma_f32_16x16x32_bf16 v[74:77], v[136:139], v[240:243], v[74:77]
	v_mfma_f32_16x16x32_bf16 v[78:81], v[144:147], v[240:243], v[78:81]
	v_mfma_f32_16x16x32_bf16 v[114:117], v[170:173], v[212:215], 0
	v_mfma_f32_16x16x32_bf16 v[118:121], v[204:207], v[212:215], 0
	v_mfma_f32_16x16x32_bf16 v[98:101], v[170:173], v[220:223], 0
	v_mfma_f32_16x16x32_bf16 v[102:105], v[204:207], v[220:223], 0
	v_mfma_f32_16x16x32_bf16 v[82:85], v[170:173], v[228:231], 0
	v_mfma_f32_16x16x32_bf16 v[86:89], v[204:207], v[228:231], 0
	v_mfma_f32_16x16x32_bf16 v[66:69], v[170:173], v[236:239], 0
	v_mfma_f32_16x16x32_bf16 v[70:73], v[204:207], v[236:239], 0
	v_mfma_f32_16x16x32_bf16 v[114:117], v[200:203], v[216:219], v[114:117]
	v_mfma_f32_16x16x32_bf16 v[118:121], v[208:211], v[216:219], v[118:121]
	v_mfma_f32_16x16x32_bf16 v[98:101], v[200:203], v[224:227], v[98:101]
	v_mfma_f32_16x16x32_bf16 v[102:105], v[208:211], v[224:227], v[102:105]
	v_mfma_f32_16x16x32_bf16 v[82:85], v[200:203], v[232:235], v[82:85]
	v_mfma_f32_16x16x32_bf16 v[86:89], v[208:211], v[232:235], v[86:89]
	s_setprio 2
	s_barrier
	v_mfma_f32_16x16x32_bf16 v[66:69], v[200:203], v[240:243], v[66:69]
	v_mfma_f32_16x16x32_bf16 v[70:73], v[208:211], v[240:243], v[70:73]
	s_setprio 0
	s_add_i32 s4, s95, s61
	s_mov_b32 m0, s4
	ds_read_b128 v[212:215], v194 offset:16384
	ds_read_b128 v[216:219], v194 offset:17408
	ds_read_b128 v[220:223], v194 offset:18432
	ds_read_b128 v[224:227], v194 offset:19456
	ds_read_b128 v[228:231], v194 offset:20480
	ds_read_b128 v[232:235], v194 offset:21504
	ds_read_b128 v[236:239], v194 offset:22528
	ds_read_b128 v[240:243], v194 offset:23552
	global_load_lds_dwordx4 v152, s[64:65] sc1
	s_add_i32 m0, s4, 0x2000
	s_add_u32 s4, s64, 0x4000
	s_addc_u32 s5, s65, 0
	s_add_i32 s47, s93, s61
	global_load_lds_dwordx4 v154, s[64:65] sc1
	s_mov_b32 m0, s47
	s_nop 0
	global_load_lds_dwordx4 v152, s[4:5] sc1
	s_add_i32 m0, s47, 0x2000
	s_nop 0
	global_load_lds_dwordx4 v154, s[4:5] sc1
	s_mov_b32 m0, s69
	s_nop 0
	global_load_lds_dwordx4 v150, s[84:85] sc1
	s_mov_b32 m0, s77
	s_nop 0
	global_load_lds_dwordx4 v148, s[84:85] sc1
	s_waitcnt vmcnt(8)
	s_waitcnt lgkmcnt(0)
	s_setprio 1
	s_barrier
	v_mfma_f32_16x16x32_bf16 v[58:61], v[130:133], v[212:215], 0
	v_mfma_f32_16x16x32_bf16 v[62:65], v[140:143], v[212:215], 0
	v_mfma_f32_16x16x32_bf16 v[42:45], v[130:133], v[220:223], 0
	v_mfma_f32_16x16x32_bf16 v[46:49], v[140:143], v[220:223], 0
	v_mfma_f32_16x16x32_bf16 v[26:29], v[130:133], v[228:231], 0
	v_mfma_f32_16x16x32_bf16 v[30:33], v[140:143], v[228:231], 0
	v_mfma_f32_16x16x32_bf16 v[10:13], v[130:133], v[236:239], 0
	v_mfma_f32_16x16x32_bf16 v[14:17], v[140:143], v[236:239], 0
	v_mfma_f32_16x16x32_bf16 v[58:61], v[136:139], v[216:219], v[58:61]
	v_mfma_f32_16x16x32_bf16 v[62:65], v[144:147], v[216:219], v[62:65]
	v_mfma_f32_16x16x32_bf16 v[42:45], v[136:139], v[224:227], v[42:45]
	v_mfma_f32_16x16x32_bf16 v[46:49], v[144:147], v[224:227], v[46:49]
	v_mfma_f32_16x16x32_bf16 v[26:29], v[136:139], v[232:235], v[26:29]
	v_mfma_f32_16x16x32_bf16 v[30:33], v[144:147], v[232:235], v[30:33]
	v_mfma_f32_16x16x32_bf16 v[10:13], v[136:139], v[240:243], v[10:13]
	v_mfma_f32_16x16x32_bf16 v[14:17], v[144:147], v[240:243], v[14:17]
	v_mfma_f32_16x16x32_bf16 v[50:53], v[170:173], v[212:215], 0
	v_mfma_f32_16x16x32_bf16 v[54:57], v[204:207], v[212:215], 0
	v_mfma_f32_16x16x32_bf16 v[34:37], v[170:173], v[220:223], 0
	v_mfma_f32_16x16x32_bf16 v[38:41], v[204:207], v[220:223], 0
	v_mfma_f32_16x16x32_bf16 v[18:21], v[170:173], v[228:231], 0
	v_mfma_f32_16x16x32_bf16 v[22:25], v[204:207], v[228:231], 0
	v_mfma_f32_16x16x32_bf16 v[2:5], v[170:173], v[236:239], 0
	v_mfma_f32_16x16x32_bf16 v[6:9], v[204:207], v[236:239], 0
	v_mfma_f32_16x16x32_bf16 v[50:53], v[200:203], v[216:219], v[50:53]
	v_mfma_f32_16x16x32_bf16 v[54:57], v[208:211], v[216:219], v[54:57]
	v_mfma_f32_16x16x32_bf16 v[34:37], v[200:203], v[224:227], v[34:37]
	v_mfma_f32_16x16x32_bf16 v[38:41], v[208:211], v[224:227], v[38:41]
	v_mfma_f32_16x16x32_bf16 v[18:21], v[200:203], v[232:235], v[18:21]
	v_mfma_f32_16x16x32_bf16 v[22:25], v[208:211], v[232:235], v[22:25]
	s_setprio 2
	s_barrier
	v_mfma_f32_16x16x32_bf16 v[2:5], v[200:203], v[240:243], v[2:5]
	v_mfma_f32_16x16x32_bf16 v[6:9], v[208:211], v[240:243], v[6:9]
	s_setprio 0
	v_add_u32_e32 v134, s36, v1
	ds_read_b128 v[130:133], v134
	ds_read_b128 v[136:139], v134 offset:1024
	ds_read_b128 v[140:143], v134 offset:2048
	ds_read_b128 v[144:147], v134 offset:3072
	v_add_u32_e32 v134, s37, v1
	ds_read_b128 v[170:173], v134
	ds_read_b128 v[200:203], v134 offset:1024
	ds_read_b128 v[204:207], v134 offset:2048
	ds_read_b128 v[208:211], v134 offset:3072
	s_add_u32 s4, s84, 0x4000
	s_addc_u32 s5, s85, 0
	s_mov_b32 m0, s86
	ds_read_b128 v[212:215], v194 offset:32768
	ds_read_b128 v[216:219], v194 offset:33792
	ds_read_b128 v[220:223], v194 offset:34816
	ds_read_b128 v[224:227], v194 offset:35840
	ds_read_b128 v[228:231], v194 offset:36864
	ds_read_b128 v[232:235], v194 offset:37888
	ds_read_b128 v[236:239], v194 offset:38912
	ds_read_b128 v[240:243], v194 offset:39936
	global_load_lds_dwordx4 v150, s[4:5] sc1
	s_mov_b32 m0, s87
	s_nop 0
	global_load_lds_dwordx4 v148, s[4:5] sc1
	s_waitcnt vmcnt(8)
	s_waitcnt lgkmcnt(0)
	s_setprio 1
	s_barrier
	v_mfma_f32_16x16x32_bf16 v[122:125], v[130:133], v[212:215], v[122:125]
	v_mfma_f32_16x16x32_bf16 v[126:129], v[140:143], v[212:215], v[126:129]
	v_mfma_f32_16x16x32_bf16 v[106:109], v[130:133], v[220:223], v[106:109]
	v_mfma_f32_16x16x32_bf16 v[110:113], v[140:143], v[220:223], v[110:113]
	v_mfma_f32_16x16x32_bf16 v[90:93], v[130:133], v[228:231], v[90:93]
	v_mfma_f32_16x16x32_bf16 v[94:97], v[140:143], v[228:231], v[94:97]
	v_mfma_f32_16x16x32_bf16 v[74:77], v[130:133], v[236:239], v[74:77]
	v_mfma_f32_16x16x32_bf16 v[78:81], v[140:143], v[236:239], v[78:81]
	v_mfma_f32_16x16x32_bf16 v[122:125], v[136:139], v[216:219], v[122:125]
	v_mfma_f32_16x16x32_bf16 v[126:129], v[144:147], v[216:219], v[126:129]
	v_mfma_f32_16x16x32_bf16 v[106:109], v[136:139], v[224:227], v[106:109]
	v_mfma_f32_16x16x32_bf16 v[110:113], v[144:147], v[224:227], v[110:113]
	v_mfma_f32_16x16x32_bf16 v[90:93], v[136:139], v[232:235], v[90:93]
	v_mfma_f32_16x16x32_bf16 v[94:97], v[144:147], v[232:235], v[94:97]
	v_mfma_f32_16x16x32_bf16 v[74:77], v[136:139], v[240:243], v[74:77]
	v_mfma_f32_16x16x32_bf16 v[78:81], v[144:147], v[240:243], v[78:81]
	v_mfma_f32_16x16x32_bf16 v[114:117], v[170:173], v[212:215], v[114:117]
	v_mfma_f32_16x16x32_bf16 v[118:121], v[204:207], v[212:215], v[118:121]
	v_mfma_f32_16x16x32_bf16 v[98:101], v[170:173], v[220:223], v[98:101]
	v_mfma_f32_16x16x32_bf16 v[102:105], v[204:207], v[220:223], v[102:105]
	v_mfma_f32_16x16x32_bf16 v[82:85], v[170:173], v[228:231], v[82:85]
	v_mfma_f32_16x16x32_bf16 v[86:89], v[204:207], v[228:231], v[86:89]
	v_mfma_f32_16x16x32_bf16 v[66:69], v[170:173], v[236:239], v[66:69]
	v_mfma_f32_16x16x32_bf16 v[70:73], v[204:207], v[236:239], v[70:73]
	v_mfma_f32_16x16x32_bf16 v[114:117], v[200:203], v[216:219], v[114:117]
	v_mfma_f32_16x16x32_bf16 v[118:121], v[208:211], v[216:219], v[118:121]
	v_mfma_f32_16x16x32_bf16 v[98:101], v[200:203], v[224:227], v[98:101]
	v_mfma_f32_16x16x32_bf16 v[102:105], v[208:211], v[224:227], v[102:105]
	v_mfma_f32_16x16x32_bf16 v[82:85], v[200:203], v[232:235], v[82:85]
	v_mfma_f32_16x16x32_bf16 v[86:89], v[208:211], v[232:235], v[86:89]
	s_setprio 2
	s_barrier
	v_mfma_f32_16x16x32_bf16 v[66:69], v[200:203], v[240:243], v[66:69]
	v_mfma_f32_16x16x32_bf16 v[70:73], v[208:211], v[240:243], v[70:73]
	s_setprio 0
	s_add_u32 s4, s64, 0x8000
	s_addc_u32 s5, s65, 0
	s_add_i32 s47, s36, s61
	s_mov_b32 m0, s47
	ds_read_b128 v[212:215], v194 offset:49152
	ds_read_b128 v[216:219], v194 offset:50176
	ds_read_b128 v[220:223], v194 offset:51200
	ds_read_b128 v[224:227], v194 offset:52224
	ds_read_b128 v[228:231], v194 offset:53248
	ds_read_b128 v[232:235], v194 offset:54272
	ds_read_b128 v[236:239], v194 offset:55296
	ds_read_b128 v[240:243], v194 offset:56320
	global_load_lds_dwordx4 v152, s[4:5] sc1
	s_add_i32 m0, s47, 0x2000
	s_nop 0
	global_load_lds_dwordx4 v154, s[4:5] sc1
	s_add_u32 s4, s64, 0xc000
	s_addc_u32 s5, s65, 0
	s_add_i32 s47, s37, s61
	s_mov_b32 m0, s47
	s_nop 0
	global_load_lds_dwordx4 v152, s[4:5] sc1
	s_add_i32 m0, s47, 0x2000
	s_nop 0
	global_load_lds_dwordx4 v154, s[4:5] sc1
	s_mov_b32 m0, s91
	s_nop 0
	global_load_lds_dwordx4 v150, s[56:57] sc1
	s_mov_b32 m0, s92
	s_nop 0
	global_load_lds_dwordx4 v148, s[56:57] sc1
	s_waitcnt vmcnt(8)
	s_waitcnt lgkmcnt(0)
	s_setprio 1
	s_barrier
	v_mfma_f32_16x16x32_bf16 v[58:61], v[130:133], v[212:215], v[58:61]
	v_mfma_f32_16x16x32_bf16 v[62:65], v[140:143], v[212:215], v[62:65]
	v_mfma_f32_16x16x32_bf16 v[42:45], v[130:133], v[220:223], v[42:45]
	v_mfma_f32_16x16x32_bf16 v[46:49], v[140:143], v[220:223], v[46:49]
	v_mfma_f32_16x16x32_bf16 v[26:29], v[130:133], v[228:231], v[26:29]
	v_mfma_f32_16x16x32_bf16 v[30:33], v[140:143], v[228:231], v[30:33]
	v_mfma_f32_16x16x32_bf16 v[10:13], v[130:133], v[236:239], v[10:13]
	v_mfma_f32_16x16x32_bf16 v[14:17], v[140:143], v[236:239], v[14:17]
	v_mfma_f32_16x16x32_bf16 v[58:61], v[136:139], v[216:219], v[58:61]
	v_mfma_f32_16x16x32_bf16 v[62:65], v[144:147], v[216:219], v[62:65]
	v_mfma_f32_16x16x32_bf16 v[42:45], v[136:139], v[224:227], v[42:45]
	v_mfma_f32_16x16x32_bf16 v[46:49], v[144:147], v[224:227], v[46:49]
	v_mfma_f32_16x16x32_bf16 v[26:29], v[136:139], v[232:235], v[26:29]
	v_mfma_f32_16x16x32_bf16 v[30:33], v[144:147], v[232:235], v[30:33]
	v_mfma_f32_16x16x32_bf16 v[10:13], v[136:139], v[240:243], v[10:13]
	v_mfma_f32_16x16x32_bf16 v[14:17], v[144:147], v[240:243], v[14:17]
	v_mfma_f32_16x16x32_bf16 v[50:53], v[170:173], v[212:215], v[50:53]
	v_mfma_f32_16x16x32_bf16 v[54:57], v[204:207], v[212:215], v[54:57]
	v_mfma_f32_16x16x32_bf16 v[34:37], v[170:173], v[220:223], v[34:37]
	v_mfma_f32_16x16x32_bf16 v[38:41], v[204:207], v[220:223], v[38:41]
	v_mfma_f32_16x16x32_bf16 v[18:21], v[170:173], v[228:231], v[18:21]
	v_mfma_f32_16x16x32_bf16 v[22:25], v[204:207], v[228:231], v[22:25]
	v_mfma_f32_16x16x32_bf16 v[2:5], v[170:173], v[236:239], v[2:5]
	v_mfma_f32_16x16x32_bf16 v[6:9], v[204:207], v[236:239], v[6:9]
	v_mfma_f32_16x16x32_bf16 v[50:53], v[200:203], v[216:219], v[50:53]
	v_mfma_f32_16x16x32_bf16 v[54:57], v[208:211], v[216:219], v[54:57]
	v_mfma_f32_16x16x32_bf16 v[34:37], v[200:203], v[224:227], v[34:37]
	v_mfma_f32_16x16x32_bf16 v[38:41], v[208:211], v[224:227], v[38:41]
	v_mfma_f32_16x16x32_bf16 v[18:21], v[200:203], v[232:235], v[18:21]
	v_mfma_f32_16x16x32_bf16 v[22:25], v[208:211], v[232:235], v[22:25]
	s_setprio 2
	s_barrier
	v_mfma_f32_16x16x32_bf16 v[2:5], v[200:203], v[240:243], v[2:5]
	v_mfma_f32_16x16x32_bf16 v[6:9], v[208:211], v[240:243], v[6:9]
	s_setprio 0
	s_add_i32 s46, s46, 2
	s_add_u32 s44, s44, 0x10000
	s_addc_u32 s45, s45, 0
	s_cmp_gt_u32 s46, 13
	s_mov_b64 s[4:5], s[8:9]

.LBB0_604:
	s_cmp_eq_u32 s40, s94
	s_mov_b64 s[4:5], -1
	s_cbranch_scc1 .LBB0_458
	s_andn2_b64 vcc, exec, s[66:67]
	s_cbranch_vccnz .LBB0_457
	s_barrier
	s_branch .LBB0_457

.LBB0_609:
	s_add_u32 s84, s96, 0x500000
	s_waitcnt vmcnt(0)
	s_addc_u32 s4, s97, 0
	s_cmpk_lt_i32 s2, 0xe0
	v_writelane_b32 v252, s4, 29
	s_barrier
	s_cbranch_scc0 .LBB0_629
	s_mov_b64 s[6:7], 0
	s_cmpk_gt_i32 s2, 0xbf
	s_mov_b64 s[4:5], 0
	s_cbranch_scc0 .LBB0_630
	v_mov_b32_e32 v139, v188
	s_mov_b32 s4, 0x1ffffe0
	v_bfe_i32 v3, v139, 27, 1
	v_lshlrev_b32_e32 v1, 4, v139
	v_lshrrev_b32_e32 v3, 22, v3
	v_add_u32_e32 v3, v1, v3
	v_and_b32_e32 v3, 0xfffffc00, v3
	v_sub_u32_e32 v3, v1, v3
	v_ashrrev_i32_e32 v2, 31, v139
	v_lshrrev_b32_e32 v4, 4, v3
	v_lshrrev_b32_e32 v2, 26, v2
	v_bitop3_b32 v3, v4, v3, 32 bitop3:0x6c
	v_add_u32_e32 v2, v139, v2
	v_ashrrev_i32_e32 v5, 31, v3
	v_ashrrev_i32_e32 v2, 6, v2
	v_lshrrev_b32_e32 v5, 26, v5
	v_lshlrev_b32_e32 v4, 3, v2
	v_add_u32_e32 v5, v3, v5
	v_and_b32_e32 v4, -16, v4
	v_ashrrev_i32_e32 v6, 6, v5
	v_add_u32_e32 v138, v6, v4
	v_and_b32_e32 v4, 0xc0, v5
	v_lshlrev_b32_e32 v2, 5, v2
	v_sub_u32_e32 v3, v3, v4
	v_mov_b32_e32 v4, 1
	v_and_b32_e32 v2, 32, v2
	v_ashrrev_i16_sdwa v3, v4, sext(v3) dst_sel:DWORD dst_unused:UNUSED_PAD src0_sel:DWORD src1_sel:BYTE_0
	v_add_u32_sdwa v2, v2, sext(v3) dst_sel:DWORD dst_unused:UNUSED_PAD src0_sel:DWORD src1_sel:WORD_0
	v_and_b32_e32 v9, 0x1fffffe, v138
	v_lshrrev_b32_e32 v140, 5, v2
	v_add_lshl_u32 v2, v140, v9, 6
	v_lshlrev_b32_e32 v9, 5, v138
	v_and_b32_e32 v141, 32, v9
	v_mov_b32_e32 v9, 31
	v_lshlrev_b32_e32 v5, 1, v138
	v_lshrrev_b32_e32 v7, 2, v138
	v_and_b32_e32 v8, 2, v6
	v_and_b32_sdwa v150, sext(v3), v9 dst_sel:DWORD dst_unused:UNUSED_PAD src0_sel:WORD_0 src1_sel:DWORD
	v_and_b32_e32 v5, 24, v5
	v_and_b32_e32 v7, 4, v7
	v_and_or_b32 v8, v138, s4, v8
	v_or3_b32 v2, v2, v141, v150
	v_lshlrev_b32_e32 v130, 1, v2
	v_or3_b32 v2, v7, v8, v5
	v_lshlrev_b32_e32 v3, 5, v6
	v_add_lshl_u32 v2, v2, v140, 6
	v_and_b32_e32 v3, 32, v3
	v_or3_b32 v2, v2, v3, v150
	v_add_u32_e32 v1, 0x2000, v1
	v_lshlrev_b32_e32 v132, 1, v2
	v_ashrrev_i32_e32 v2, 31, v1
	v_lshrrev_b32_e32 v2, 22, v2
	v_add_u32_e32 v2, v1, v2
	v_ashrrev_i32_e32 v2, 10, v2
	v_mul_i32_i24_e32 v3, 0x400, v2
	v_sub_u32_e32 v1, v1, v3
	v_lshrrev_b32_e32 v3, 4, v1
	v_bitop3_b32 v1, v3, v1, 32 bitop3:0x6c
	v_ashrrev_i32_e32 v5, 31, v1
	v_lshrrev_b32_e32 v5, 26, v5
	v_lshlrev_b32_e32 v3, 3, v2
	v_add_u32_e32 v5, v1, v5
	v_and_b32_e32 v3, -16, v3
	v_ashrrev_i32_e32 v6, 6, v5
	v_add_u32_e32 v151, v6, v3
	v_and_b32_e32 v3, 0xc0, v5
	v_lshlrev_b32_e32 v2, 5, v2
	v_sub_u32_e32 v1, v1, v3
	v_and_b32_e32 v2, 32, v2
	v_ashrrev_i16_sdwa v1, v4, sext(v1) dst_sel:DWORD dst_unused:UNUSED_PAD src0_sel:DWORD src1_sel:BYTE_0
	s_add_u32 s37, s96, 0x2a80000
	v_add_u32_sdwa v2, v2, sext(v1) dst_sel:DWORD dst_unused:UNUSED_PAD src0_sel:DWORD src1_sel:WORD_0
	v_and_b32_e32 v5, 2, v6
	s_addc_u32 s38, s97, 0
	s_add_i32 s36, s2, 0xffffff40
	v_readfirstlane_b32 s8, v139
	v_and_or_b32 v5, v151, s4, v5
	v_and_b32_e32 v7, 0x1fffffe, v151
	v_lshrrev_b32_e32 v152, 5, v2
	s_lshl_b32 s4, s2, 2
	v_add_lshl_u32 v2, v152, v7, 6
	v_lshlrev_b32_e32 v7, 5, v151
	s_ashr_i32 s10, s8, 6
	s_lshr_b32 s51, s36, 3
	s_and_b32 s11, s4, 28
	s_ashr_i32 s9, s8, 8
	v_lshlrev_b32_e32 v3, 1, v151
	v_lshrrev_b32_e32 v4, 2, v151
	v_and_b32_e32 v153, 32, v7
	v_and_b32_sdwa v154, sext(v1), v9 dst_sel:DWORD dst_unused:UNUSED_PAD src0_sel:WORD_0 src1_sel:DWORD
	s_lshl_b32 s35, s10, 10
	s_lshl_b32 s40, s51, 19
	s_lshl_b32 s4, s11, 17
	v_and_b32_e32 v3, 24, v3
	v_and_b32_e32 v4, 4, v4
	v_or3_b32 v1, v2, v153, v154
	s_add_u32 s78, s37, s4
	v_lshlrev_b32_e32 v134, 1, v1
	v_or3_b32 v1, v4, v5, v3
	v_lshlrev_b32_e32 v2, 5, v6
	s_addc_u32 s79, s38, 0
	s_add_i32 s39, s35, 0x100
	v_add_lshl_u32 v1, v1, v152, 6
	v_and_b32_e32 v2, 32, v2
	s_add_i32 m0, s39, 0x10000
	v_or3_b32 v1, v1, v2, v154
	global_load_lds_dwordx4 v132, s[78:79] sc1
	s_add_i32 m0, s39, 0x12000
	v_lshlrev_b32_e32 v136, 1, v1
	s_add_u32 s4, s78, 0x4000
	global_load_lds_dwordx4 v136, s[78:79] sc1
	s_addc_u32 s5, s79, 0
	s_add_i32 m0, s39, 0x14000
	v_mov_b32_e32 v133, 0
	global_load_lds_dwordx4 v132, s[4:5] sc1
	s_add_i32 m0, s39, 0x16000
	s_add_u32 s70, s68, s40
	global_load_lds_dwordx4 v136, s[4:5] sc1
	v_readlane_b32 s4, v253, 33
	s_addc_u32 s71, s4, 0
	s_add_i32 s40, s39, 0x2000
	s_mov_b32 m0, s39
	s_add_u32 s4, s70, 0x4000
	global_load_lds_dwordx4 v130, s[70:71] sc1
	s_mov_b32 m0, s40
	s_addc_u32 s5, s71, 0
	s_add_i32 s41, s39, 0x4000
	global_load_lds_dwordx4 v134, s[70:71] sc1
	s_mov_b32 m0, s41
	s_add_i32 s42, s39, 0x6000
	global_load_lds_dwordx4 v130, s[4:5] sc1
	s_mov_b32 m0, s42
	s_cmp_eq_u32 s9, 1
	global_load_lds_dwordx4 v134, s[4:5] sc1
	s_mov_b32 s43, 0
	v_mov_b32_e32 v137, v133
	v_mov_b32_e32 v131, v133
	s_cselect_b64 s[4:5], -1, 0
	s_cmp_lg_u32 s9, 1
	v_mov_b32_e32 v135, v133
	s_cbranch_scc1 .LBB0_613
	s_barrier

.LBB0_622:
	s_ashr_i32 s57, s56, 31
	s_lshl_b64 s[62:63], s[56:57], 19
	s_add_u32 s62, s68, s62
	v_readlane_b32 s11, v253, 33
	s_addc_u32 s63, s11, s63
	s_and_b64 s[64:65], s[66:67], exec
	s_cselect_b32 s55, s63, s71
	s_cselect_b32 s57, s62, s70
	s_ashr_i32 s11, s10, 31
	s_lshl_b64 s[64:65], s[10:11], 19
	s_add_u32 s64, s37, s64
	s_addc_u32 s65, s38, s65
	s_and_b64 s[82:83], s[66:67], exec
	s_cselect_b32 s11, s65, s79
	s_cselect_b32 s61, s64, s78
	s_add_u32 s69, s78, 0x10000
	s_addc_u32 s77, s79, 0
	s_mov_b32 s94, -2
	v_add_u32_e32 v160, s47, v142
	ds_read_b128 v[152:155], v160
	ds_read_b128 v[156:159], v160 offset:1024
	ds_read_b128 v[162:165], v160 offset:2048
	ds_read_b128 v[166:169], v160 offset:3072
	v_add_u32_e32 v160, s48, v142
	ds_read_b128 v[170:173], v160
	ds_read_b128 v[174:177], v160 offset:1024
	ds_read_b128 v[178:181], v160 offset:2048
	ds_read_b128 v[182:185], v160 offset:3072
	s_add_u32 s78, s70, 0x10000
	s_addc_u32 s79, s71, 0
	s_cmp_eq_u32 s94, 12
	s_cselect_b32 s92, s57, s78
	s_cselect_b32 s93, s55, s79
	s_cselect_b32 s90, s61, s69
	s_cselect_b32 s91, s11, s77
	s_add_u32 s82, s92, 0x8000
	s_addc_u32 s83, s93, 0
	s_add_i32 m0, s39, 0xc000
	ds_read_b128 v[192:195], v150
	ds_read_b128 v[200:203], v150 offset:1024
	ds_read_b128 v[204:207], v150 offset:2048
	ds_read_b128 v[208:211], v150 offset:3072
	ds_read_b128 v[212:215], v150 offset:4096
	ds_read_b128 v[216:219], v150 offset:5120
	ds_read_b128 v[220:223], v150 offset:6144
	ds_read_b128 v[224:227], v150 offset:7168
	global_load_lds_dwordx4 v138, s[70:71] sc1
	s_add_i32 m0, s39, 0xe000
	s_nop 0
	global_load_lds_dwordx4 v140, s[70:71] sc1
	s_waitcnt vmcnt(8)
	s_waitcnt lgkmcnt(0)
	s_setprio 1
	s_barrier
	v_mfma_f32_16x16x32_bf16 v[98:101], v[152:155], v[192:195], 0
	v_mfma_f32_16x16x32_bf16 v[102:105], v[162:165], v[192:195], 0
	v_mfma_f32_16x16x32_bf16 v[62:65], v[152:155], v[204:207], 0
	v_mfma_f32_16x16x32_bf16 v[78:81], v[162:165], v[204:207], 0
	v_mfma_f32_16x16x32_bf16 v[34:37], v[152:155], v[212:215], 0
	v_mfma_f32_16x16x32_bf16 v[46:49], v[162:165], v[212:215], 0
	v_mfma_f32_16x16x32_bf16 v[14:17], v[152:155], v[220:223], 0
	v_mfma_f32_16x16x32_bf16 v[22:25], v[162:165], v[220:223], 0
	v_mfma_f32_16x16x32_bf16 v[98:101], v[156:159], v[200:203], v[98:101]
	v_mfma_f32_16x16x32_bf16 v[102:105], v[166:169], v[200:203], v[102:105]
	v_mfma_f32_16x16x32_bf16 v[62:65], v[156:159], v[208:211], v[62:65]
	v_mfma_f32_16x16x32_bf16 v[78:81], v[166:169], v[208:211], v[78:81]
	v_mfma_f32_16x16x32_bf16 v[34:37], v[156:159], v[216:219], v[34:37]
	v_mfma_f32_16x16x32_bf16 v[46:49], v[166:169], v[216:219], v[46:49]
	v_mfma_f32_16x16x32_bf16 v[14:17], v[156:159], v[224:227], v[14:17]
	v_mfma_f32_16x16x32_bf16 v[22:25], v[166:169], v[224:227], v[22:25]
	v_mfma_f32_16x16x32_bf16 v[122:125], v[170:173], v[192:195], 0
	v_mfma_f32_16x16x32_bf16 v[126:129], v[178:181], v[192:195], 0
	v_mfma_f32_16x16x32_bf16 v[110:113], v[170:173], v[204:207], 0
	v_mfma_f32_16x16x32_bf16 v[118:121], v[178:181], v[204:207], 0
	v_mfma_f32_16x16x32_bf16 v[86:89], v[170:173], v[212:215], 0
	v_mfma_f32_16x16x32_bf16 v[94:97], v[178:181], v[212:215], 0
	v_mfma_f32_16x16x32_bf16 v[54:57], v[170:173], v[220:223], 0
	v_mfma_f32_16x16x32_bf16 v[70:73], v[178:181], v[220:223], 0
	v_mfma_f32_16x16x32_bf16 v[122:125], v[174:177], v[200:203], v[122:125]
	v_mfma_f32_16x16x32_bf16 v[126:129], v[182:185], v[200:203], v[126:129]
	v_mfma_f32_16x16x32_bf16 v[110:113], v[174:177], v[208:211], v[110:113]
	v_mfma_f32_16x16x32_bf16 v[118:121], v[182:185], v[208:211], v[118:121]
	v_mfma_f32_16x16x32_bf16 v[86:89], v[174:177], v[216:219], v[86:89]
	v_mfma_f32_16x16x32_bf16 v[94:97], v[182:185], v[216:219], v[94:97]
	s_setprio 2
	s_barrier
	v_mfma_f32_16x16x32_bf16 v[54:57], v[174:177], v[224:227], v[54:57]
	v_mfma_f32_16x16x32_bf16 v[70:73], v[182:185], v[224:227], v[70:73]
	s_setprio 0
	s_add_i32 s70, s47, s35
	s_mov_b32 m0, s70
	ds_read_b128 v[192:195], v150 offset:16384
	ds_read_b128 v[200:203], v150 offset:17408
	ds_read_b128 v[204:207], v150 offset:18432
	ds_read_b128 v[208:211], v150 offset:19456
	ds_read_b128 v[212:215], v150 offset:20480
	ds_read_b128 v[216:219], v150 offset:21504
	ds_read_b128 v[220:223], v150 offset:22528
	ds_read_b128 v[224:227], v150 offset:23552
	global_load_lds_dwordx4 v132, s[90:91] sc1
	s_add_i32 m0, s70, 0x2000
	s_add_u32 s70, s90, 0x4000
	s_addc_u32 s71, s91, 0
	s_add_i32 s95, s48, s35
	global_load_lds_dwordx4 v136, s[90:91] sc1
	s_mov_b32 m0, s95
	s_nop 0
	global_load_lds_dwordx4 v132, s[70:71] sc1
	s_add_i32 m0, s95, 0x2000
	s_nop 0
	global_load_lds_dwordx4 v136, s[70:71] sc1
	s_mov_b32 m0, s39
	s_nop 0
	global_load_lds_dwordx4 v130, s[92:93] sc1
	s_mov_b32 m0, s40
	s_nop 0
	global_load_lds_dwordx4 v134, s[92:93] sc1
	s_waitcnt vmcnt(8)
	s_waitcnt lgkmcnt(0)
	s_setprio 1
	s_barrier
	v_mfma_f32_16x16x32_bf16 v[58:61], v[152:155], v[192:195], 0
	v_mfma_f32_16x16x32_bf16 v[74:77], v[162:165], v[192:195], 0
	v_mfma_f32_16x16x32_bf16 v[30:33], v[152:155], v[204:207], 0
	v_mfma_f32_16x16x32_bf16 v[42:45], v[162:165], v[204:207], 0
	v_mfma_f32_16x16x32_bf16 v[10:13], v[152:155], v[212:215], 0
	v_mfma_f32_16x16x32_bf16 v[18:21], v[162:165], v[212:215], 0
	v_mfma_f32_16x16x32_bf16 v[2:5], v[152:155], v[220:223], 0
	v_mfma_f32_16x16x32_bf16 v[6:9], v[162:165], v[220:223], 0
	v_mfma_f32_16x16x32_bf16 v[58:61], v[156:159], v[200:203], v[58:61]
	v_mfma_f32_16x16x32_bf16 v[74:77], v[166:169], v[200:203], v[74:77]
	v_mfma_f32_16x16x32_bf16 v[30:33], v[156:159], v[208:211], v[30:33]
	v_mfma_f32_16x16x32_bf16 v[42:45], v[166:169], v[208:211], v[42:45]
	v_mfma_f32_16x16x32_bf16 v[10:13], v[156:159], v[216:219], v[10:13]
	v_mfma_f32_16x16x32_bf16 v[18:21], v[166:169], v[216:219], v[18:21]
	v_mfma_f32_16x16x32_bf16 v[2:5], v[156:159], v[224:227], v[2:5]
	v_mfma_f32_16x16x32_bf16 v[6:9], v[166:169], v[224:227], v[6:9]
	v_mfma_f32_16x16x32_bf16 v[106:109], v[170:173], v[192:195], 0
	v_mfma_f32_16x16x32_bf16 v[114:117], v[178:181], v[192:195], 0
	v_mfma_f32_16x16x32_bf16 v[82:85], v[170:173], v[204:207], 0
	v_mfma_f32_16x16x32_bf16 v[90:93], v[178:181], v[204:207], 0
	v_mfma_f32_16x16x32_bf16 v[50:53], v[170:173], v[212:215], 0
	v_mfma_f32_16x16x32_bf16 v[66:69], v[178:181], v[212:215], 0
	v_mfma_f32_16x16x32_bf16 v[26:29], v[170:173], v[220:223], 0
	v_mfma_f32_16x16x32_bf16 v[38:41], v[178:181], v[220:223], 0
	v_mfma_f32_16x16x32_bf16 v[106:109], v[174:177], v[200:203], v[106:109]
	v_mfma_f32_16x16x32_bf16 v[114:117], v[182:185], v[200:203], v[114:117]
	v_mfma_f32_16x16x32_bf16 v[82:85], v[174:177], v[208:211], v[82:85]
	v_mfma_f32_16x16x32_bf16 v[90:93], v[182:185], v[208:211], v[90:93]
	v_mfma_f32_16x16x32_bf16 v[50:53], v[174:177], v[216:219], v[50:53]
	v_mfma_f32_16x16x32_bf16 v[66:69], v[182:185], v[216:219], v[66:69]
	s_setprio 2
	s_barrier
	v_mfma_f32_16x16x32_bf16 v[26:29], v[174:177], v[224:227], v[26:29]
	v_mfma_f32_16x16x32_bf16 v[38:41], v[182:185], v[224:227], v[38:41]
	s_setprio 0
	v_add_u32_e32 v160, s49, v142
	ds_read_b128 v[152:155], v160
	ds_read_b128 v[156:159], v160 offset:1024
	ds_read_b128 v[162:165], v160 offset:2048
	ds_read_b128 v[166:169], v160 offset:3072
	v_add_u32_e32 v160, s50, v142
	ds_read_b128 v[170:173], v160
	ds_read_b128 v[174:177], v160 offset:1024
	ds_read_b128 v[178:181], v160 offset:2048
	ds_read_b128 v[182:185], v160 offset:3072
	s_add_u32 s70, s92, 0x4000
	s_addc_u32 s71, s93, 0
	s_mov_b32 m0, s41
	ds_read_b128 v[192:195], v150 offset:32768
	ds_read_b128 v[200:203], v150 offset:33792
	ds_read_b128 v[204:207], v150 offset:34816
	ds_read_b128 v[208:211], v150 offset:35840
	ds_read_b128 v[212:215], v150 offset:36864
	ds_read_b128 v[216:219], v150 offset:37888
	ds_read_b128 v[220:223], v150 offset:38912
	ds_read_b128 v[224:227], v150 offset:39936
	global_load_lds_dwordx4 v130, s[70:71] sc1
	s_mov_b32 m0, s42
	s_nop 0
	global_load_lds_dwordx4 v134, s[70:71] sc1
	s_waitcnt vmcnt(8)
	s_waitcnt lgkmcnt(0)
	s_setprio 1
	s_barrier
	v_mfma_f32_16x16x32_bf16 v[98:101], v[152:155], v[192:195], v[98:101]
	v_mfma_f32_16x16x32_bf16 v[102:105], v[162:165], v[192:195], v[102:105]
	v_mfma_f32_16x16x32_bf16 v[62:65], v[152:155], v[204:207], v[62:65]
	v_mfma_f32_16x16x32_bf16 v[78:81], v[162:165], v[204:207], v[78:81]
	v_mfma_f32_16x16x32_bf16 v[34:37], v[152:155], v[212:215], v[34:37]
	v_mfma_f32_16x16x32_bf16 v[46:49], v[162:165], v[212:215], v[46:49]
	v_mfma_f32_16x16x32_bf16 v[14:17], v[152:155], v[220:223], v[14:17]
	v_mfma_f32_16x16x32_bf16 v[22:25], v[162:165], v[220:223], v[22:25]
	v_mfma_f32_16x16x32_bf16 v[98:101], v[156:159], v[200:203], v[98:101]
	v_mfma_f32_16x16x32_bf16 v[102:105], v[166:169], v[200:203], v[102:105]
	v_mfma_f32_16x16x32_bf16 v[62:65], v[156:159], v[208:211], v[62:65]
	v_mfma_f32_16x16x32_bf16 v[78:81], v[166:169], v[208:211], v[78:81]
	v_mfma_f32_16x16x32_bf16 v[34:37], v[156:159], v[216:219], v[34:37]
	v_mfma_f32_16x16x32_bf16 v[46:49], v[166:169], v[216:219], v[46:49]
	v_mfma_f32_16x16x32_bf16 v[14:17], v[156:159], v[224:227], v[14:17]
	v_mfma_f32_16x16x32_bf16 v[22:25], v[166:169], v[224:227], v[22:25]
	v_mfma_f32_16x16x32_bf16 v[122:125], v[170:173], v[192:195], v[122:125]
	v_mfma_f32_16x16x32_bf16 v[126:129], v[178:181], v[192:195], v[126:129]
	v_mfma_f32_16x16x32_bf16 v[110:113], v[170:173], v[204:207], v[110:113]
	v_mfma_f32_16x16x32_bf16 v[118:121], v[178:181], v[204:207], v[118:121]
	v_mfma_f32_16x16x32_bf16 v[86:89], v[170:173], v[212:215], v[86:89]
	v_mfma_f32_16x16x32_bf16 v[94:97], v[178:181], v[212:215], v[94:97]
	v_mfma_f32_16x16x32_bf16 v[54:57], v[170:173], v[220:223], v[54:57]
	v_mfma_f32_16x16x32_bf16 v[70:73], v[178:181], v[220:223], v[70:73]
	v_mfma_f32_16x16x32_bf16 v[122:125], v[174:177], v[200:203], v[122:125]
	v_mfma_f32_16x16x32_bf16 v[126:129], v[182:185], v[200:203], v[126:129]
	v_mfma_f32_16x16x32_bf16 v[110:113], v[174:177], v[208:211], v[110:113]
	v_mfma_f32_16x16x32_bf16 v[118:121], v[182:185], v[208:211], v[118:121]
	v_mfma_f32_16x16x32_bf16 v[86:89], v[174:177], v[216:219], v[86:89]
	v_mfma_f32_16x16x32_bf16 v[94:97], v[182:185], v[216:219], v[94:97]
	s_setprio 2
	s_barrier
	v_mfma_f32_16x16x32_bf16 v[54:57], v[174:177], v[224:227], v[54:57]
	v_mfma_f32_16x16x32_bf16 v[70:73], v[182:185], v[224:227], v[70:73]
	s_setprio 0
	s_add_u32 s70, s90, 0x8000
	s_addc_u32 s71, s91, 0
	s_add_i32 s92, s49, s35
	s_mov_b32 m0, s92
	ds_read_b128 v[192:195], v150 offset:49152
	ds_read_b128 v[200:203], v150 offset:50176
	ds_read_b128 v[204:207], v150 offset:51200
	ds_read_b128 v[208:211], v150 offset:52224
	ds_read_b128 v[212:215], v150 offset:53248
	ds_read_b128 v[216:219], v150 offset:54272
	ds_read_b128 v[220:223], v150 offset:55296
	ds_read_b128 v[224:227], v150 offset:56320
	global_load_lds_dwordx4 v132, s[70:71] sc1
	s_add_i32 m0, s92, 0x2000
	s_nop 0
	global_load_lds_dwordx4 v136, s[70:71] sc1
	s_add_u32 s70, s90, 0xc000
	s_addc_u32 s71, s91, 0
	s_add_i32 s90, s50, s35
	s_mov_b32 m0, s90
	s_nop 0
	global_load_lds_dwordx4 v132, s[70:71] sc1
	s_add_i32 m0, s90, 0x2000
	s_nop 0
	global_load_lds_dwordx4 v136, s[70:71] sc1
	s_mov_b32 m0, s44
	s_nop 0
	global_load_lds_dwordx4 v130, s[82:83] sc1
	s_mov_b32 m0, s45
	s_nop 0
	global_load_lds_dwordx4 v134, s[82:83] sc1
	s_waitcnt vmcnt(8)
	s_waitcnt lgkmcnt(0)
	s_setprio 1
	s_barrier
	v_mfma_f32_16x16x32_bf16 v[58:61], v[152:155], v[192:195], v[58:61]
	v_mfma_f32_16x16x32_bf16 v[74:77], v[162:165], v[192:195], v[74:77]
	v_mfma_f32_16x16x32_bf16 v[30:33], v[152:155], v[204:207], v[30:33]
	v_mfma_f32_16x16x32_bf16 v[42:45], v[162:165], v[204:207], v[42:45]
	v_mfma_f32_16x16x32_bf16 v[10:13], v[152:155], v[212:215], v[10:13]
	v_mfma_f32_16x16x32_bf16 v[18:21], v[162:165], v[212:215], v[18:21]
	v_mfma_f32_16x16x32_bf16 v[2:5], v[152:155], v[220:223], v[2:5]
	v_mfma_f32_16x16x32_bf16 v[6:9], v[162:165], v[220:223], v[6:9]
	v_mfma_f32_16x16x32_bf16 v[58:61], v[156:159], v[200:203], v[58:61]
	v_mfma_f32_16x16x32_bf16 v[74:77], v[166:169], v[200:203], v[74:77]
	v_mfma_f32_16x16x32_bf16 v[30:33], v[156:159], v[208:211], v[30:33]
	v_mfma_f32_16x16x32_bf16 v[42:45], v[166:169], v[208:211], v[42:45]
	v_mfma_f32_16x16x32_bf16 v[10:13], v[156:159], v[216:219], v[10:13]
	v_mfma_f32_16x16x32_bf16 v[18:21], v[166:169], v[216:219], v[18:21]
	v_mfma_f32_16x16x32_bf16 v[2:5], v[156:159], v[224:227], v[2:5]
	v_mfma_f32_16x16x32_bf16 v[6:9], v[166:169], v[224:227], v[6:9]
	v_mfma_f32_16x16x32_bf16 v[106:109], v[170:173], v[192:195], v[106:109]
	v_mfma_f32_16x16x32_bf16 v[114:117], v[178:181], v[192:195], v[114:117]
	v_mfma_f32_16x16x32_bf16 v[82:85], v[170:173], v[204:207], v[82:85]
	v_mfma_f32_16x16x32_bf16 v[90:93], v[178:181], v[204:207], v[90:93]
	v_mfma_f32_16x16x32_bf16 v[50:53], v[170:173], v[212:215], v[50:53]
	v_mfma_f32_16x16x32_bf16 v[66:69], v[178:181], v[212:215], v[66:69]
	v_mfma_f32_16x16x32_bf16 v[26:29], v[170:173], v[220:223], v[26:29]
	v_mfma_f32_16x16x32_bf16 v[38:41], v[178:181], v[220:223], v[38:41]
	v_mfma_f32_16x16x32_bf16 v[106:109], v[174:177], v[200:203], v[106:109]
	v_mfma_f32_16x16x32_bf16 v[114:117], v[182:185], v[200:203], v[114:117]
	v_mfma_f32_16x16x32_bf16 v[82:85], v[174:177], v[208:211], v[82:85]
	v_mfma_f32_16x16x32_bf16 v[90:93], v[182:185], v[208:211], v[90:93]
	v_mfma_f32_16x16x32_bf16 v[50:53], v[174:177], v[216:219], v[50:53]
	v_mfma_f32_16x16x32_bf16 v[66:69], v[182:185], v[216:219], v[66:69]
	s_setprio 2
	s_barrier
	v_mfma_f32_16x16x32_bf16 v[26:29], v[174:177], v[224:227], v[26:29]
	v_mfma_f32_16x16x32_bf16 v[38:41], v[182:185], v[224:227], v[38:41]
	s_setprio 0
	s_add_i32 s94, s94, 2
	s_add_u32 s69, s69, 0x10000
	s_addc_u32 s77, s77, 0
	s_cmp_gt_u32 s94, 13
	s_mov_b64 s[70:71], s[78:79]

.LBB0_626:
	s_lshl_b32 s11, s51, 8
	v_add_u32_e32 v156, s11, v1
	s_nop 0
	v_cvt_pk_bf16_f32 v152, v98, v99
	v_cvt_pk_bf16_f32 v153, v100, v101
	v_cvt_pk_bf16_f32 v154, v102, v103
	v_cvt_pk_bf16_f32 v155, v104, v105
	v_lshl_or_b32 v102, s54, 9, v151
	v_lshl_add_u32 v103, v156, 12, v102
	buffer_store_dwordx4 v[152:155], v103, s[84:87], 0 offen sc1
	s_nop 0
	v_cvt_pk_bf16_f32 v98, v122, v123
	v_cvt_pk_bf16_f32 v99, v124, v125
	v_cvt_pk_bf16_f32 v100, v126, v127
	v_cvt_pk_bf16_f32 v101, v128, v129
	buffer_store_dwordx4 v[98:101], v103, s[84:87], 0 offen offset:256 sc1
	v_add_u32_e32 v103, s11, v143
	s_andn2_b64 vcc, exec, s[66:67]
	s_nop 0
	v_cvt_pk_bf16_f32 v98, v62, v63
	v_cvt_pk_bf16_f32 v99, v64, v65
	v_cvt_pk_bf16_f32 v100, v78, v79
	v_cvt_pk_bf16_f32 v101, v80, v81
	v_lshl_add_u32 v78, v103, 12, v102
	buffer_store_dwordx4 v[98:101], v78, s[84:87], 0 offen sc1
	s_nop 0
	v_cvt_pk_bf16_f32 v62, v110, v111
	v_cvt_pk_bf16_f32 v63, v112, v113
	v_cvt_pk_bf16_f32 v64, v118, v119
	v_cvt_pk_bf16_f32 v65, v120, v121
	buffer_store_dwordx4 v[62:65], v78, s[84:87], 0 offen offset:256 sc1
	v_add_u32_e32 v78, s11, v144
	s_mov_b64 s[66:67], -1
	s_nop 0
	v_cvt_pk_bf16_f32 v62, v34, v35
	v_cvt_pk_bf16_f32 v63, v36, v37
	v_cvt_pk_bf16_f32 v64, v46, v47
	v_cvt_pk_bf16_f32 v65, v48, v49
	v_lshl_add_u32 v46, v78, 12, v102
	buffer_store_dwordx4 v[62:65], v46, s[84:87], 0 offen sc1
	s_nop 0
	v_cvt_pk_bf16_f32 v34, v86, v87
	v_cvt_pk_bf16_f32 v35, v88, v89
	v_cvt_pk_bf16_f32 v36, v94, v95
	v_cvt_pk_bf16_f32 v37, v96, v97
	buffer_store_dwordx4 v[34:37], v46, s[84:87], 0 offen offset:256 sc1
	v_add_u32_e32 v46, s11, v145
	s_nop 0
	s_nop 0
	v_cvt_pk_bf16_f32 v34, v14, v15
	v_cvt_pk_bf16_f32 v35, v16, v17
	v_cvt_pk_bf16_f32 v36, v22, v23
	v_cvt_pk_bf16_f32 v37, v24, v25
	v_lshl_add_u32 v22, v46, 12, v102
	buffer_store_dwordx4 v[34:37], v22, s[84:87], 0 offen sc1
	s_nop 0
	v_cvt_pk_bf16_f32 v14, v54, v55
	v_cvt_pk_bf16_f32 v15, v56, v57
	v_cvt_pk_bf16_f32 v16, v70, v71
	v_cvt_pk_bf16_f32 v17, v72, v73
	buffer_store_dwordx4 v[14:17], v22, s[84:87], 0 offen offset:256 sc1
	v_add_u32_e32 v22, s11, v146
	v_lshl_add_u32 v22, v22, 12, v102
	s_nop 0
	v_cvt_pk_bf16_f32 v14, v58, v59
	v_cvt_pk_bf16_f32 v15, v60, v61
	v_cvt_pk_bf16_f32 v16, v74, v75
	v_cvt_pk_bf16_f32 v17, v76, v77
	buffer_store_dwordx4 v[14:17], v22, s[84:87], 0 offen sc1
	s_nop 1
	s_nop 0
	v_cvt_pk_bf16_f32 v14, v106, v107
	v_cvt_pk_bf16_f32 v15, v108, v109
	v_cvt_pk_bf16_f32 v16, v114, v115
	v_cvt_pk_bf16_f32 v17, v116, v117
	buffer_store_dwordx4 v[14:17], v22, s[84:87], 0 offen offset:256 sc1
	v_add_u32_e32 v22, s11, v147
	v_lshl_add_u32 v22, v22, 12, v102
	s_nop 0
	v_cvt_pk_bf16_f32 v14, v30, v31
	v_cvt_pk_bf16_f32 v15, v32, v33
	v_cvt_pk_bf16_f32 v16, v42, v43
	v_cvt_pk_bf16_f32 v17, v44, v45
	buffer_store_dwordx4 v[14:17], v22, s[84:87], 0 offen sc1
	s_nop 1
	s_nop 0
	v_cvt_pk_bf16_f32 v14, v82, v83
	v_cvt_pk_bf16_f32 v15, v84, v85
	v_cvt_pk_bf16_f32 v16, v90, v91
	v_cvt_pk_bf16_f32 v17, v92, v93
	buffer_store_dwordx4 v[14:17], v22, s[84:87], 0 offen offset:256 sc1
	v_add_u32_e32 v22, s11, v148
	s_nop 0
	s_nop 0
	v_cvt_pk_bf16_f32 v14, v10, v11
	v_cvt_pk_bf16_f32 v15, v12, v13
	v_cvt_pk_bf16_f32 v16, v18, v19
	v_cvt_pk_bf16_f32 v17, v20, v21
	v_lshl_add_u32 v18, v22, 12, v102
	buffer_store_dwordx4 v[14:17], v18, s[84:87], 0 offen sc1
	s_nop 0
	v_cvt_pk_bf16_f32 v10, v50, v51
	v_cvt_pk_bf16_f32 v11, v52, v53
	v_cvt_pk_bf16_f32 v12, v66, v67
	v_cvt_pk_bf16_f32 v13, v68, v69
	buffer_store_dwordx4 v[10:13], v18, s[84:87], 0 offen offset:256 sc1
	s_nop 0
	v_add_u32_e32 v14, s11, v149
	s_nop 0
	v_cvt_pk_bf16_f32 v10, v2, v3
	v_cvt_pk_bf16_f32 v11, v4, v5
	v_cvt_pk_bf16_f32 v12, v6, v7
	v_cvt_pk_bf16_f32 v13, v8, v9
	v_lshl_add_u32 v6, v14, 12, v102
	buffer_store_dwordx4 v[10:13], v6, s[84:87], 0 offen sc1
	s_nop 0
	v_cvt_pk_bf16_f32 v2, v26, v27
	v_cvt_pk_bf16_f32 v3, v28, v29
	v_cvt_pk_bf16_f32 v4, v38, v39
	v_cvt_pk_bf16_f32 v5, v40, v41
	buffer_store_dwordx4 v[2:5], v6, s[84:87], 0 offen offset:256 sc1
	s_cbranch_vccnz .LBB0_615
	s_andn2_b64 vcc, exec, s[4:5]
	s_cbranch_vccnz .LBB0_614
	s_barrier
	s_branch .LBB0_614

.LBB0_873:
	v_bfe_i32 v2, v148, 27, 1
	v_lshlrev_b32_e32 v0, 4, v148
	v_lshrrev_b32_e32 v2, 22, v2
	v_add_u32_e32 v2, v0, v2
	v_and_b32_e32 v2, 0xfffffc00, v2
	v_sub_u32_e32 v2, v0, v2
	v_ashrrev_i32_e32 v1, 31, v148
	v_lshrrev_b32_e32 v3, 4, v2
	v_lshrrev_b32_e32 v1, 26, v1
	v_bitop3_b32 v2, v3, v2, 32 bitop3:0x6c
	v_add_u32_e32 v1, v148, v1
	v_ashrrev_i32_e32 v4, 31, v2
	v_ashrrev_i32_e32 v1, 6, v1
	v_lshrrev_b32_e32 v4, 26, v4
	v_lshlrev_b32_e32 v3, 3, v1
	v_add_u32_e32 v4, v2, v4
	v_and_b32_e32 v3, -16, v3
	v_ashrrev_i32_e32 v5, 6, v4
	v_add_u32_e32 v136, v5, v3
	v_and_b32_e32 v3, 0xc0, v4
	v_lshlrev_b32_e32 v1, 5, v1
	v_sub_u32_e32 v2, v2, v3
	v_mov_b32_e32 v3, 1
	v_and_b32_e32 v1, 32, v1
	v_ashrrev_i16_sdwa v2, v3, sext(v2) dst_sel:DWORD dst_unused:UNUSED_PAD src0_sel:DWORD src1_sel:BYTE_0
	v_add_u32_sdwa v1, v1, sext(v2) dst_sel:DWORD dst_unused:UNUSED_PAD src0_sel:DWORD src1_sel:WORD_0
	v_and_b32_e32 v8, 0x1fffffe, v136
	v_lshrrev_b32_e32 v137, 5, v1
	v_add_lshl_u32 v1, v137, v8, 6
	v_lshlrev_b32_e32 v8, 5, v136
	v_and_b32_e32 v138, 32, v8
	v_mov_b32_e32 v8, 31
	v_lshlrev_b32_e32 v4, 1, v136
	v_lshrrev_b32_e32 v6, 2, v136
	v_and_b32_e32 v7, 2, v5
	s_mov_b32 s9, 0x1ffffe0
	v_and_b32_sdwa v139, sext(v2), v8 dst_sel:DWORD dst_unused:UNUSED_PAD src0_sel:WORD_0 src1_sel:DWORD
	v_and_b32_e32 v4, 24, v4
	v_and_b32_e32 v6, 4, v6
	v_and_or_b32 v7, v136, s9, v7
	v_or3_b32 v1, v1, v138, v139
	v_lshlrev_b32_e32 v128, 1, v1
	v_or3_b32 v1, v6, v7, v4
	v_lshlrev_b32_e32 v2, 5, v5
	v_add_lshl_u32 v1, v1, v137, 6
	v_and_b32_e32 v2, 32, v2
	v_or3_b32 v1, v1, v2, v139
	v_add_u32_e32 v0, 0x2000, v0
	v_lshlrev_b32_e32 v130, 1, v1
	v_ashrrev_i32_e32 v1, 31, v0
	v_lshrrev_b32_e32 v1, 22, v1
	v_add_u32_e32 v1, v0, v1
	v_ashrrev_i32_e32 v1, 10, v1
	v_mul_i32_i24_e32 v2, 0x400, v1
	v_sub_u32_e32 v0, v0, v2
	v_lshrrev_b32_e32 v2, 4, v0
	v_bitop3_b32 v0, v2, v0, 32 bitop3:0x6c
	v_ashrrev_i32_e32 v4, 31, v0
	v_lshrrev_b32_e32 v4, 26, v4
	v_lshlrev_b32_e32 v2, 3, v1
	v_add_u32_e32 v4, v0, v4
	v_and_b32_e32 v2, -16, v2
	v_ashrrev_i32_e32 v5, 6, v4
	v_add_u32_e32 v140, v5, v2
	v_and_b32_e32 v2, 0xc0, v4
	v_and_b32_e32 v4, 2, v5
	v_and_or_b32 v4, v140, s9, v4
	v_readlane_b32 s9, v252, 7
	s_add_i32 s8, s8, s9
	s_ashr_i32 s9, s8, 31
	v_lshlrev_b32_e32 v1, 5, v1
	v_sub_u32_e32 v0, v0, v2
	s_lshr_b32 s9, s9, 27
	v_and_b32_e32 v1, 32, v1
	v_ashrrev_i16_sdwa v0, v3, sext(v0) dst_sel:DWORD dst_unused:UNUSED_PAD src0_sel:DWORD src1_sel:BYTE_0
	s_add_i32 s9, s8, s9
	v_add_u32_sdwa v1, v1, sext(v0) dst_sel:DWORD dst_unused:UNUSED_PAD src0_sel:DWORD src1_sel:WORD_0
	s_ashr_i32 s10, s9, 5
	v_and_b32_e32 v6, 0x1fffffe, v140
	v_lshrrev_b32_e32 v141, 5, v1
	s_lshl_b32 s11, s10, 3
	v_add_lshl_u32 v1, v141, v6, 6
	v_lshlrev_b32_e32 v6, 5, v140
	s_sub_i32 s10, 64, s11
	v_lshlrev_b32_e32 v2, 1, v140
	v_lshrrev_b32_e32 v3, 2, v140
	v_and_b32_e32 v142, 32, v6
	v_and_b32_sdwa v143, sext(v0), v8 dst_sel:DWORD dst_unused:UNUSED_PAD src0_sel:WORD_0 src1_sel:DWORD
	s_min_i32 s18, s10, 8
	v_and_b32_e32 v2, 24, v2
	v_and_b32_e32 v3, 4, v3
	v_or3_b32 v0, v1, v142, v143
	s_abs_i32 s10, s18
	v_lshlrev_b32_e32 v132, 1, v0
	v_or3_b32 v0, v3, v4, v2
	v_cvt_f32_u32_e32 v2, s10
	v_lshlrev_b32_e32 v1, 5, v5
	v_add_lshl_u32 v0, v0, v141, 6
	v_and_b32_e32 v1, 32, v1
	v_or3_b32 v0, v0, v1, v143
	v_lshlrev_b32_e32 v134, 1, v0
	v_rcp_iflag_f32_e32 v0, v2
	s_sub_i32 s30, 0, s10
	s_andn2_b32 s9, s9, 31
	s_sub_i32 s8, s8, s9
	v_mul_f32_e32 v0, 0x4f7ffffe, v0
	v_cvt_u32_f32_e32 v0, v0
	s_abs_i32 s19, s8
	s_ashr_i32 s7, s36, 6
	s_xor_b32 s9, s8, s18
	v_readfirstlane_b32 s31, v0
	s_mul_i32 s30, s30, s31
	s_mul_hi_u32 s30, s31, s30
	s_add_i32 s31, s31, s30
	s_mul_hi_u32 s30, s19, s31
	s_mul_i32 s31, s30, s10
	s_sub_i32 s19, s19, s31
	s_ashr_i32 s6, s36, 8
	s_lshl_b32 s35, s7, 10
	s_ashr_i32 s9, s9, 31
	s_add_i32 s31, s30, 1
	s_sub_i32 s37, s19, s10
	s_cmp_ge_u32 s19, s10
	s_cselect_b32 s30, s31, s30
	s_cselect_b32 s19, s37, s19
	s_add_i32 s31, s30, 1
	s_cmp_ge_u32 s19, s10
	s_cselect_b32 s10, s31, s30
	s_xor_b32 s10, s10, s9
	s_sub_i32 s10, s10, s9
	s_mul_i32 s9, s10, s18
	s_sub_i32 s8, s8, s9
	s_add_i32 s18, s11, s8
	s_ashr_i32 s19, s18, 31
	s_ashr_i32 s11, s10, 31
	s_lshl_b64 s[8:9], s[18:19], 20
	s_lshl_b64 s[30:31], s[10:11], 19
	s_add_u32 s30, s28, s30
	s_addc_u32 s31, s29, s31
	s_add_i32 s37, s35, 0x100
	s_add_i32 m0, s37, 0x10000
	s_nop 0
	global_load_lds_dwordx4 v130, s[30:31] sc1
	s_add_i32 m0, s37, 0x12000
	s_add_u32 s38, s30, 0x4000
	global_load_lds_dwordx4 v134, s[30:31] sc1
	s_addc_u32 s39, s31, 0
	s_add_i32 m0, s37, 0x14000
	v_readlane_b32 s40, v253, 0
	global_load_lds_dwordx4 v130, s[38:39] sc1
	s_add_i32 m0, s37, 0x16000
	v_readlane_b32 s42, v253, 2
	global_load_lds_dwordx4 v134, s[38:39] sc1
	v_readlane_b32 s43, v253, 3
	s_add_u32 s38, s42, s8
	s_addc_u32 s39, s43, s9
	s_add_i32 s43, s37, 0x2000
	s_mov_b32 m0, s37
	s_add_u32 s8, s38, 0x4000
	global_load_lds_dwordx4 v128, s[38:39] sc1
	s_mov_b32 m0, s43
	s_addc_u32 s9, s39, 0
	s_add_i32 s44, s37, 0x4000
	global_load_lds_dwordx4 v132, s[38:39] sc1
	s_mov_b32 m0, s44
	s_add_i32 s45, s37, 0x6000
	global_load_lds_dwordx4 v128, s[8:9] sc1
	s_mov_b32 m0, s45
	v_mov_b32_e32 v131, 0
	global_load_lds_dwordx4 v132, s[8:9] sc1
	s_mov_b32 s50, 0
	v_mov_b32_e32 v135, v131
	v_mov_b32_e32 v129, v131
	s_cmp_lg_u32 s6, 1
	v_mov_b32_e32 v133, v131
	v_readlane_b32 s41, v253, 1
	s_cbranch_scc1 .LBB0_875
	s_barrier

.LBB0_876:
	s_mov_b32 s10, s40
	s_mov_b32 s18, s56
	s_mov_b64 s[38:39], s[62:63]
	s_mov_b32 s50, s61
	s_andn2_b64 vcc, exec, s[6:7]
	s_cbranch_vccz .LBB0_887

.LBB0_883:
	s_add_u32 s69, s30, 0x10000
	s_addc_u32 s80, s31, 0
	s_ashr_i32 s57, s56, 31
	v_readlane_b32 s64, v253, 0
	s_lshl_b64 s[30:31], s[56:57], 20
	v_readlane_b32 s66, v253, 2
	v_readlane_b32 s67, v253, 3
	s_add_u32 s62, s66, s30
	s_addc_u32 s63, s67, s31
	s_ashr_i32 s41, s40, 31
	s_lshl_b64 s[30:31], s[40:41], 19
	s_add_u32 s30, s28, s30
	v_readlane_b32 s65, v253, 1
	s_addc_u32 s31, s29, s31
	s_lshl_b32 s64, s10, 2
	s_ashr_i32 s19, s18, 31
	s_ashr_i32 s65, s64, 31
	s_lshl_b64 s[66:67], s[18:19], 19
	s_lshl_b64 s[64:65], s[64:65], 15
	s_add_u32 s19, s60, s64
	s_addc_u32 s41, s33, s65
	s_add_u32 s19, s19, s66
	s_addc_u32 s41, s41, s67
	s_add_u32 s66, s19, 0x10000
	s_addc_u32 s57, s41, 0
	s_and_b64 s[64:65], s[8:9], exec
	s_cselect_b32 s57, s63, s57
	s_cselect_b32 s81, s62, s66
	s_cselect_b32 s85, s31, s41
	s_cselect_b32 s86, s30, s19
	v_lshl_add_u64 v[144:145], s[38:39], 0, v[136:137]
	v_lshl_add_u64 v[146:147], s[38:39], 0, v[138:139]
	s_mov_b32 s87, -2
	s_mov_b64 s[64:65], 0
	s_add_u32 s19, s38, s64
	s_addc_u32 s41, s39, s65
	v_add_u32_e32 v168, s49, v151
	v_add_u32_e32 v184, s51, v151
	s_add_u32 s19, s19, 0x10000
	ds_read_b128 v[156:159], v168
	ds_read_b128 v[160:163], v168 offset:1024
	ds_read_b128 v[164:167], v168 offset:2048
	ds_read_b128 v[168:171], v168 offset:3072
	ds_read_b128 v[172:175], v184
	ds_read_b128 v[176:179], v184 offset:1024
	ds_read_b128 v[180:183], v184 offset:2048
	ds_read_b128 v[184:187], v184 offset:3072
	s_addc_u32 s41, s41, 0
	s_add_u32 s66, s69, s64
	s_addc_u32 s67, s80, s65
	s_cmp_eq_u32 s64, 0x70000
	s_cselect_b32 s78, s81, s19
	s_cselect_b32 s79, s57, s41
	s_cselect_b32 s70, s86, s66
	s_cselect_b32 s71, s85, s67
	s_add_u32 s66, s78, 0x8000
	s_addc_u32 s67, s79, 0
	s_add_i32 s19, s37, 0xc000
	v_lshl_add_u64 v[196:197], v[144:145], 0, s[64:65]
	s_mov_b32 m0, s19
	s_add_i32 s41, s37, 0xe000
	ds_read_b128 v[192:195], v154
	ds_read_b128 v[200:203], v154 offset:1024
	ds_read_b128 v[204:207], v154 offset:2048
	ds_read_b128 v[208:211], v154 offset:3072
	ds_read_b128 v[212:215], v154 offset:4096
	ds_read_b128 v[216:219], v154 offset:5120
	ds_read_b128 v[220:223], v154 offset:6144
	ds_read_b128 v[224:227], v154 offset:7168
	global_load_lds_dwordx4 v[196:197], off sc1
	v_lshl_add_u64 v[196:197], v[146:147], 0, s[64:65]
	s_mov_b32 m0, s41
	s_nop 0
	global_load_lds_dwordx4 v[196:197], off sc1
	s_waitcnt vmcnt(8)
	s_waitcnt lgkmcnt(0)
	s_setprio 1
	s_barrier
	v_mfma_f32_16x16x32_bf16 v[112:115], v[156:159], v[192:195], 0
	v_mfma_f32_16x16x32_bf16 v[116:119], v[164:167], v[192:195], 0
	v_mfma_f32_16x16x32_bf16 v[96:99], v[156:159], v[204:207], 0
	v_mfma_f32_16x16x32_bf16 v[100:103], v[164:167], v[204:207], 0
	v_mfma_f32_16x16x32_bf16 v[80:83], v[156:159], v[212:215], 0
	v_mfma_f32_16x16x32_bf16 v[84:87], v[164:167], v[212:215], 0
	v_mfma_f32_16x16x32_bf16 v[64:67], v[156:159], v[220:223], 0
	v_mfma_f32_16x16x32_bf16 v[68:71], v[164:167], v[220:223], 0
	v_mfma_f32_16x16x32_bf16 v[112:115], v[160:163], v[200:203], v[112:115]
	v_mfma_f32_16x16x32_bf16 v[116:119], v[168:171], v[200:203], v[116:119]
	v_mfma_f32_16x16x32_bf16 v[96:99], v[160:163], v[208:211], v[96:99]
	v_mfma_f32_16x16x32_bf16 v[100:103], v[168:171], v[208:211], v[100:103]
	v_mfma_f32_16x16x32_bf16 v[80:83], v[160:163], v[216:219], v[80:83]
	v_mfma_f32_16x16x32_bf16 v[84:87], v[168:171], v[216:219], v[84:87]
	v_mfma_f32_16x16x32_bf16 v[64:67], v[160:163], v[224:227], v[64:67]
	v_mfma_f32_16x16x32_bf16 v[68:71], v[168:171], v[224:227], v[68:71]
	v_mfma_f32_16x16x32_bf16 v[120:123], v[172:175], v[192:195], 0
	v_mfma_f32_16x16x32_bf16 v[124:127], v[180:183], v[192:195], 0
	v_mfma_f32_16x16x32_bf16 v[104:107], v[172:175], v[204:207], 0
	v_mfma_f32_16x16x32_bf16 v[108:111], v[180:183], v[204:207], 0
	v_mfma_f32_16x16x32_bf16 v[88:91], v[172:175], v[212:215], 0
	v_mfma_f32_16x16x32_bf16 v[92:95], v[180:183], v[212:215], 0
	v_mfma_f32_16x16x32_bf16 v[72:75], v[172:175], v[220:223], 0
	v_mfma_f32_16x16x32_bf16 v[76:79], v[180:183], v[220:223], 0
	v_mfma_f32_16x16x32_bf16 v[120:123], v[176:179], v[200:203], v[120:123]
	v_mfma_f32_16x16x32_bf16 v[124:127], v[184:187], v[200:203], v[124:127]
	v_mfma_f32_16x16x32_bf16 v[104:107], v[176:179], v[208:211], v[104:107]
	v_mfma_f32_16x16x32_bf16 v[108:111], v[184:187], v[208:211], v[108:111]
	v_mfma_f32_16x16x32_bf16 v[88:91], v[176:179], v[216:219], v[88:91]
	v_mfma_f32_16x16x32_bf16 v[92:95], v[184:187], v[216:219], v[92:95]
	s_setprio 2
	s_barrier
	v_mfma_f32_16x16x32_bf16 v[72:75], v[176:179], v[224:227], v[72:75]
	v_mfma_f32_16x16x32_bf16 v[76:79], v[184:187], v[224:227], v[76:79]
	s_setprio 0
	s_add_i32 s88, s49, s35
	s_mov_b32 m0, s88
	ds_read_b128 v[192:195], v154 offset:16384
	ds_read_b128 v[200:203], v154 offset:17408
	ds_read_b128 v[204:207], v154 offset:18432
	ds_read_b128 v[208:211], v154 offset:19456
	ds_read_b128 v[212:215], v154 offset:20480
	ds_read_b128 v[216:219], v154 offset:21504
	ds_read_b128 v[220:223], v154 offset:22528
	ds_read_b128 v[224:227], v154 offset:23552
	global_load_lds_dwordx4 v130, s[70:71] sc1
	s_add_i32 m0, s88, 0x2000
	s_add_u32 s88, s70, 0x4000
	s_addc_u32 s89, s71, 0
	s_add_i32 s90, s51, s35
	global_load_lds_dwordx4 v134, s[70:71] sc1
	s_mov_b32 m0, s90
	s_nop 0
	global_load_lds_dwordx4 v130, s[88:89] sc1
	s_add_i32 m0, s90, 0x2000
	s_nop 0
	global_load_lds_dwordx4 v134, s[88:89] sc1
	s_mov_b32 m0, s37
	s_nop 0
	global_load_lds_dwordx4 v128, s[78:79] sc1
	s_mov_b32 m0, s43
	s_nop 0
	global_load_lds_dwordx4 v132, s[78:79] sc1
	s_waitcnt vmcnt(8)
	s_waitcnt lgkmcnt(0)
	s_setprio 1
	s_barrier
	v_mfma_f32_16x16x32_bf16 v[48:51], v[156:159], v[192:195], 0
	v_mfma_f32_16x16x32_bf16 v[52:55], v[164:167], v[192:195], 0
	v_mfma_f32_16x16x32_bf16 v[32:35], v[156:159], v[204:207], 0
	v_mfma_f32_16x16x32_bf16 v[36:39], v[164:167], v[204:207], 0
	v_mfma_f32_16x16x32_bf16 v[16:19], v[156:159], v[212:215], 0
	v_mfma_f32_16x16x32_bf16 v[20:23], v[164:167], v[212:215], 0
	v_mfma_f32_16x16x32_bf16 v[0:3], v[156:159], v[220:223], 0
	v_mfma_f32_16x16x32_bf16 v[4:7], v[164:167], v[220:223], 0
	v_mfma_f32_16x16x32_bf16 v[48:51], v[160:163], v[200:203], v[48:51]
	v_mfma_f32_16x16x32_bf16 v[52:55], v[168:171], v[200:203], v[52:55]
	v_mfma_f32_16x16x32_bf16 v[32:35], v[160:163], v[208:211], v[32:35]
	v_mfma_f32_16x16x32_bf16 v[36:39], v[168:171], v[208:211], v[36:39]
	v_mfma_f32_16x16x32_bf16 v[16:19], v[160:163], v[216:219], v[16:19]
	v_mfma_f32_16x16x32_bf16 v[20:23], v[168:171], v[216:219], v[20:23]
	v_mfma_f32_16x16x32_bf16 v[0:3], v[160:163], v[224:227], v[0:3]
	v_mfma_f32_16x16x32_bf16 v[4:7], v[168:171], v[224:227], v[4:7]
	v_mfma_f32_16x16x32_bf16 v[56:59], v[172:175], v[192:195], 0
	v_mfma_f32_16x16x32_bf16 v[60:63], v[180:183], v[192:195], 0
	v_mfma_f32_16x16x32_bf16 v[40:43], v[172:175], v[204:207], 0
	v_mfma_f32_16x16x32_bf16 v[44:47], v[180:183], v[204:207], 0
	v_mfma_f32_16x16x32_bf16 v[24:27], v[172:175], v[212:215], 0
	v_mfma_f32_16x16x32_bf16 v[28:31], v[180:183], v[212:215], 0
	v_mfma_f32_16x16x32_bf16 v[8:11], v[172:175], v[220:223], 0
	v_mfma_f32_16x16x32_bf16 v[12:15], v[180:183], v[220:223], 0
	v_mfma_f32_16x16x32_bf16 v[56:59], v[176:179], v[200:203], v[56:59]
	v_mfma_f32_16x16x32_bf16 v[60:63], v[184:187], v[200:203], v[60:63]
	v_mfma_f32_16x16x32_bf16 v[40:43], v[176:179], v[208:211], v[40:43]
	v_mfma_f32_16x16x32_bf16 v[44:47], v[184:187], v[208:211], v[44:47]
	v_mfma_f32_16x16x32_bf16 v[24:27], v[176:179], v[216:219], v[24:27]
	v_mfma_f32_16x16x32_bf16 v[28:31], v[184:187], v[216:219], v[28:31]
	s_setprio 2
	s_barrier
	v_mfma_f32_16x16x32_bf16 v[8:11], v[176:179], v[224:227], v[8:11]
	v_mfma_f32_16x16x32_bf16 v[12:15], v[184:187], v[224:227], v[12:15]
	s_setprio 0
	v_add_u32_e32 v168, s54, v151
	v_add_u32_e32 v184, s55, v151
	ds_read_b128 v[156:159], v168
	ds_read_b128 v[160:163], v168 offset:1024
	ds_read_b128 v[164:167], v168 offset:2048
	ds_read_b128 v[168:171], v168 offset:3072
	ds_read_b128 v[172:175], v184
	ds_read_b128 v[176:179], v184 offset:1024
	ds_read_b128 v[180:183], v184 offset:2048
	ds_read_b128 v[184:187], v184 offset:3072
	s_add_u32 s78, s78, 0x4000
	s_addc_u32 s79, s79, 0
	s_mov_b32 m0, s44
	ds_read_b128 v[192:195], v154 offset:32768
	ds_read_b128 v[200:203], v154 offset:33792
	ds_read_b128 v[204:207], v154 offset:34816
	ds_read_b128 v[208:211], v154 offset:35840
	ds_read_b128 v[212:215], v154 offset:36864
	ds_read_b128 v[216:219], v154 offset:37888
	ds_read_b128 v[220:223], v154 offset:38912
	ds_read_b128 v[224:227], v154 offset:39936
	global_load_lds_dwordx4 v128, s[78:79] sc1
	s_mov_b32 m0, s45
	s_nop 0
	global_load_lds_dwordx4 v132, s[78:79] sc1
	s_waitcnt vmcnt(8)
	s_waitcnt lgkmcnt(0)
	s_setprio 1
	s_barrier
	v_mfma_f32_16x16x32_bf16 v[112:115], v[156:159], v[192:195], v[112:115]
	v_mfma_f32_16x16x32_bf16 v[116:119], v[164:167], v[192:195], v[116:119]
	v_mfma_f32_16x16x32_bf16 v[96:99], v[156:159], v[204:207], v[96:99]
	v_mfma_f32_16x16x32_bf16 v[100:103], v[164:167], v[204:207], v[100:103]
	v_mfma_f32_16x16x32_bf16 v[80:83], v[156:159], v[212:215], v[80:83]
	v_mfma_f32_16x16x32_bf16 v[84:87], v[164:167], v[212:215], v[84:87]
	v_mfma_f32_16x16x32_bf16 v[64:67], v[156:159], v[220:223], v[64:67]
	v_mfma_f32_16x16x32_bf16 v[68:71], v[164:167], v[220:223], v[68:71]
	v_mfma_f32_16x16x32_bf16 v[112:115], v[160:163], v[200:203], v[112:115]
	v_mfma_f32_16x16x32_bf16 v[116:119], v[168:171], v[200:203], v[116:119]
	v_mfma_f32_16x16x32_bf16 v[96:99], v[160:163], v[208:211], v[96:99]
	v_mfma_f32_16x16x32_bf16 v[100:103], v[168:171], v[208:211], v[100:103]
	v_mfma_f32_16x16x32_bf16 v[80:83], v[160:163], v[216:219], v[80:83]
	v_mfma_f32_16x16x32_bf16 v[84:87], v[168:171], v[216:219], v[84:87]
	v_mfma_f32_16x16x32_bf16 v[64:67], v[160:163], v[224:227], v[64:67]
	v_mfma_f32_16x16x32_bf16 v[68:71], v[168:171], v[224:227], v[68:71]
	v_mfma_f32_16x16x32_bf16 v[120:123], v[172:175], v[192:195], v[120:123]
	v_mfma_f32_16x16x32_bf16 v[124:127], v[180:183], v[192:195], v[124:127]
	v_mfma_f32_16x16x32_bf16 v[104:107], v[172:175], v[204:207], v[104:107]
	v_mfma_f32_16x16x32_bf16 v[108:111], v[180:183], v[204:207], v[108:111]
	v_mfma_f32_16x16x32_bf16 v[88:91], v[172:175], v[212:215], v[88:91]
	v_mfma_f32_16x16x32_bf16 v[92:95], v[180:183], v[212:215], v[92:95]
	v_mfma_f32_16x16x32_bf16 v[72:75], v[172:175], v[220:223], v[72:75]
	v_mfma_f32_16x16x32_bf16 v[76:79], v[180:183], v[220:223], v[76:79]
	v_mfma_f32_16x16x32_bf16 v[120:123], v[176:179], v[200:203], v[120:123]
	v_mfma_f32_16x16x32_bf16 v[124:127], v[184:187], v[200:203], v[124:127]
	v_mfma_f32_16x16x32_bf16 v[104:107], v[176:179], v[208:211], v[104:107]
	v_mfma_f32_16x16x32_bf16 v[108:111], v[184:187], v[208:211], v[108:111]
	v_mfma_f32_16x16x32_bf16 v[88:91], v[176:179], v[216:219], v[88:91]
	v_mfma_f32_16x16x32_bf16 v[92:95], v[184:187], v[216:219], v[92:95]
	s_setprio 2
	s_barrier
	v_mfma_f32_16x16x32_bf16 v[72:75], v[176:179], v[224:227], v[72:75]
	v_mfma_f32_16x16x32_bf16 v[76:79], v[184:187], v[224:227], v[76:79]
	s_setprio 0
	s_add_u32 s78, s70, 0x8000
	s_addc_u32 s79, s71, 0
	s_add_i32 s88, s54, s35
	s_mov_b32 m0, s88
	ds_read_b128 v[192:195], v154 offset:49152
	ds_read_b128 v[200:203], v154 offset:50176
	ds_read_b128 v[204:207], v154 offset:51200
	ds_read_b128 v[208:211], v154 offset:52224
	ds_read_b128 v[212:215], v154 offset:53248
	ds_read_b128 v[216:219], v154 offset:54272
	ds_read_b128 v[220:223], v154 offset:55296
	ds_read_b128 v[224:227], v154 offset:56320
	global_load_lds_dwordx4 v130, s[78:79] sc1
	s_add_i32 m0, s88, 0x2000
	s_add_u32 s70, s70, 0xc000
	global_load_lds_dwordx4 v134, s[78:79] sc1
	s_addc_u32 s71, s71, 0
	s_add_i32 s78, s55, s35
	s_mov_b32 m0, s78
	s_nop 0
	global_load_lds_dwordx4 v130, s[70:71] sc1
	s_add_i32 m0, s78, 0x2000
	s_nop 0
	global_load_lds_dwordx4 v134, s[70:71] sc1
	s_mov_b32 m0, s47
	s_nop 0
	global_load_lds_dwordx4 v128, s[66:67] sc1
	s_mov_b32 m0, s48
	s_nop 0
	global_load_lds_dwordx4 v132, s[66:67] sc1
	s_waitcnt vmcnt(8)
	s_waitcnt lgkmcnt(0)
	s_setprio 1
	s_barrier
	v_mfma_f32_16x16x32_bf16 v[48:51], v[156:159], v[192:195], v[48:51]
	v_mfma_f32_16x16x32_bf16 v[52:55], v[164:167], v[192:195], v[52:55]
	v_mfma_f32_16x16x32_bf16 v[32:35], v[156:159], v[204:207], v[32:35]
	v_mfma_f32_16x16x32_bf16 v[36:39], v[164:167], v[204:207], v[36:39]
	v_mfma_f32_16x16x32_bf16 v[16:19], v[156:159], v[212:215], v[16:19]
	v_mfma_f32_16x16x32_bf16 v[20:23], v[164:167], v[212:215], v[20:23]
	v_mfma_f32_16x16x32_bf16 v[0:3], v[156:159], v[220:223], v[0:3]
	v_mfma_f32_16x16x32_bf16 v[4:7], v[164:167], v[220:223], v[4:7]
	v_mfma_f32_16x16x32_bf16 v[48:51], v[160:163], v[200:203], v[48:51]
	v_mfma_f32_16x16x32_bf16 v[52:55], v[168:171], v[200:203], v[52:55]
	v_mfma_f32_16x16x32_bf16 v[32:35], v[160:163], v[208:211], v[32:35]
	v_mfma_f32_16x16x32_bf16 v[36:39], v[168:171], v[208:211], v[36:39]
	v_mfma_f32_16x16x32_bf16 v[16:19], v[160:163], v[216:219], v[16:19]
	v_mfma_f32_16x16x32_bf16 v[20:23], v[168:171], v[216:219], v[20:23]
	v_mfma_f32_16x16x32_bf16 v[0:3], v[160:163], v[224:227], v[0:3]
	v_mfma_f32_16x16x32_bf16 v[4:7], v[168:171], v[224:227], v[4:7]
	v_mfma_f32_16x16x32_bf16 v[56:59], v[172:175], v[192:195], v[56:59]
	v_mfma_f32_16x16x32_bf16 v[60:63], v[180:183], v[192:195], v[60:63]
	v_mfma_f32_16x16x32_bf16 v[40:43], v[172:175], v[204:207], v[40:43]
	v_mfma_f32_16x16x32_bf16 v[44:47], v[180:183], v[204:207], v[44:47]
	v_mfma_f32_16x16x32_bf16 v[24:27], v[172:175], v[212:215], v[24:27]
	v_mfma_f32_16x16x32_bf16 v[28:31], v[180:183], v[212:215], v[28:31]
	v_mfma_f32_16x16x32_bf16 v[8:11], v[172:175], v[220:223], v[8:11]
	v_mfma_f32_16x16x32_bf16 v[12:15], v[180:183], v[220:223], v[12:15]
	v_mfma_f32_16x16x32_bf16 v[56:59], v[176:179], v[200:203], v[56:59]
	v_mfma_f32_16x16x32_bf16 v[60:63], v[184:187], v[200:203], v[60:63]
	v_mfma_f32_16x16x32_bf16 v[40:43], v[176:179], v[208:211], v[40:43]
	v_mfma_f32_16x16x32_bf16 v[44:47], v[184:187], v[208:211], v[44:47]
	v_mfma_f32_16x16x32_bf16 v[24:27], v[176:179], v[216:219], v[24:27]
	v_mfma_f32_16x16x32_bf16 v[28:31], v[184:187], v[216:219], v[28:31]
	s_setprio 2
	s_barrier
	v_mfma_f32_16x16x32_bf16 v[8:11], v[176:179], v[224:227], v[8:11]
	v_mfma_f32_16x16x32_bf16 v[12:15], v[184:187], v[224:227], v[12:15]
	s_setprio 0
	s_add_i32 s87, s87, 2
	s_add_u32 s64, s64, 0x10000
	s_addc_u32 s65, s65, 0
	s_cmp_gt_u32 s87, 13

.LBB0_964:
	v_bfe_i32 v2, v191, 27, 1
	v_lshlrev_b32_e32 v0, 4, v191
	v_lshrrev_b32_e32 v2, 22, v2
	v_add_u32_e32 v2, v0, v2
	v_and_b32_e32 v2, 0xfffffc00, v2
	v_sub_u32_e32 v2, v0, v2
	v_ashrrev_i32_e32 v1, 31, v191
	v_lshrrev_b32_e32 v3, 4, v2
	v_lshrrev_b32_e32 v1, 26, v1
	v_bitop3_b32 v2, v3, v2, 32 bitop3:0x6c
	v_add_u32_e32 v1, v191, v1
	v_ashrrev_i32_e32 v4, 31, v2
	v_ashrrev_i32_e32 v1, 6, v1
	v_lshrrev_b32_e32 v4, 26, v4
	v_lshlrev_b32_e32 v3, 3, v1
	v_add_u32_e32 v4, v2, v4
	v_and_b32_e32 v3, -16, v3
	v_ashrrev_i32_e32 v132, 6, v4
	v_add_u32_e32 v136, v132, v3
	v_and_b32_e32 v3, 0xc0, v4
	v_lshlrev_b32_e32 v1, 5, v1
	v_sub_u32_e32 v2, v2, v3
	v_mov_b32_e32 v3, 1
	v_and_b32_e32 v1, 32, v1
	v_ashrrev_i16_sdwa v2, v3, sext(v2) dst_sel:DWORD dst_unused:UNUSED_PAD src0_sel:DWORD src1_sel:BYTE_0
	v_add_u32_sdwa v1, v1, sext(v2) dst_sel:DWORD dst_unused:UNUSED_PAD src0_sel:DWORD src1_sel:WORD_0
	v_and_b32_e32 v4, 0x1fffffe, v136
	v_lshrrev_b32_e32 v137, 5, v1
	v_add_lshl_u32 v1, v137, v4, 6
	v_lshlrev_b32_e32 v4, 5, v136
	v_and_b32_e32 v138, 32, v4
	v_mov_b32_e32 v4, 31
	v_and_b32_sdwa v139, sext(v2), v4 dst_sel:DWORD dst_unused:UNUSED_PAD src0_sel:WORD_0 src1_sel:DWORD
	v_or3_b32 v1, v1, v138, v139
	v_add_u32_e32 v0, 0x2000, v0
	v_lshlrev_b32_e32 v128, 1, v1
	v_ashrrev_i32_e32 v1, 31, v0
	v_lshrrev_b32_e32 v1, 22, v1
	v_add_u32_e32 v1, v0, v1
	v_ashrrev_i32_e32 v1, 10, v1
	v_mul_i32_i24_e32 v2, 0x400, v1
	v_sub_u32_e32 v0, v0, v2
	v_readlane_b32 s6, v252, 7
	v_lshrrev_b32_e32 v2, 4, v0
	s_add_i32 s6, s8, s6
	v_bitop3_b32 v0, v2, v0, 32 bitop3:0x6c
	s_ashr_i32 s7, s6, 31
	v_ashrrev_i32_e32 v5, 31, v0
	s_lshr_b32 s7, s7, 27
	v_lshrrev_b32_e32 v5, 26, v5
	s_add_i32 s7, s6, s7
	v_lshlrev_b32_e32 v2, 3, v1
	v_add_u32_e32 v5, v0, v5
	s_ashr_i32 s8, s7, 5
	v_and_b32_e32 v2, -16, v2
	v_ashrrev_i32_e32 v133, 6, v5
	s_lshl_b32 s8, s8, 3
	v_add_u32_e32 v140, v133, v2
	v_and_b32_e32 v2, 0xc0, v5
	s_sub_i32 s9, 64, s8
	v_lshlrev_b32_e32 v1, 5, v1
	v_sub_u32_e32 v0, v0, v2
	s_min_i32 s9, s9, 8
	v_and_b32_e32 v1, 32, v1
	v_ashrrev_i16_sdwa v0, v3, sext(v0) dst_sel:DWORD dst_unused:UNUSED_PAD src0_sel:DWORD src1_sel:BYTE_0
	s_abs_i32 s10, s9
	v_add_u32_sdwa v1, v1, sext(v0) dst_sel:DWORD dst_unused:UNUSED_PAD src0_sel:DWORD src1_sel:WORD_0
	v_and_b32_sdwa v143, sext(v0), v4 dst_sel:DWORD dst_unused:UNUSED_PAD src0_sel:WORD_0 src1_sel:DWORD
	v_cvt_f32_u32_e32 v0, s10
	s_sub_i32 s16, 0, s10
	s_andn2_b32 s7, s7, 31
	s_sub_i32 s6, s6, s7
	v_rcp_iflag_f32_e32 v0, v0
	s_abs_i32 s11, s6
	s_ashr_i32 s61, s36, 6
	s_xor_b32 s7, s6, s9
	v_mul_f32_e32 v0, 0x4f7ffffe, v0
	v_cvt_u32_f32_e32 v0, v0
	s_ashr_i32 s35, s36, 8
	s_lshl_b32 s37, s61, 10
	s_ashr_i32 s7, s7, 31
	v_readfirstlane_b32 s17, v0
	s_mul_i32 s16, s16, s17
	s_mul_hi_u32 s16, s17, s16
	s_add_i32 s17, s17, s16
	s_mul_hi_u32 s16, s11, s17
	s_mul_i32 s17, s16, s10
	s_sub_i32 s11, s11, s17
	s_add_i32 s17, s16, 1
	s_sub_i32 s18, s11, s10
	s_cmp_ge_u32 s11, s10
	s_cselect_b32 s16, s17, s16
	s_cselect_b32 s11, s18, s11
	s_add_i32 s17, s16, 1
	s_cmp_ge_u32 s11, s10
	s_cselect_b32 s10, s17, s16
	s_xor_b32 s10, s10, s7
	s_sub_i32 s16, s10, s7
	s_mul_i32 s7, s16, s9
	s_sub_i32 s6, s6, s7
	s_add_i32 s10, s8, s6
	s_ashr_i32 s11, s10, 31
	s_lshl_b64 s[6:7], s[10:11], 19
	v_and_b32_e32 v2, 0x1fffffe, v140
	v_lshrrev_b32_e32 v141, 5, v1
	s_add_u32 s18, s60, s6
	v_add_lshl_u32 v1, v141, v2, 6
	v_lshlrev_b32_e32 v2, 5, v140
	s_addc_u32 s19, s33, s7
	s_add_i32 s11, s37, 0x100
	v_and_b32_e32 v142, 32, v2
	s_add_i32 s42, s11, 0x2000
	v_or3_b32 v1, v1, v142, v143
	s_mov_b32 m0, s11
	s_add_u32 s6, s18, 0x4000
	v_lshlrev_b32_e32 v130, 1, v1
	global_load_lds_dwordx4 v128, s[18:19] sc1
	s_mov_b32 m0, s42
	s_addc_u32 s7, s19, 0
	s_add_i32 s43, s11, 0x4000
	global_load_lds_dwordx4 v130, s[18:19] sc1
	s_mov_b32 m0, s43
	s_add_i32 s44, s11, 0x6000
	global_load_lds_dwordx4 v128, s[6:7] sc1
	s_mov_b32 m0, s44
	v_mov_b32_e32 v129, 0
	global_load_lds_dwordx4 v130, s[6:7] sc1
	s_mov_b32 s47, 0
	s_cmp_lg_u32 s35, 1
	v_mov_b32_e32 v131, v129
	s_cbranch_scc1 .LBB0_966
	s_barrier

.LBB0_975:
	s_add_u32 s55, s64, 0x10000
	s_addc_u32 s69, s65, 0
	s_ashr_i32 s41, s40, 31
	s_lshl_b64 s[56:57], s[40:41], 19
	s_add_u32 s62, s60, s56
	s_addc_u32 s63, s33, s57
	s_and_b64 s[56:57], s[8:9], exec
	s_cselect_b32 s41, s63, s19
	s_cselect_b32 s80, s62, s18
	s_ashr_i32 s39, s38, 31
	s_lshl_b64 s[56:57], s[38:39], 19
	s_add_u32 s56, s30, s56
	s_addc_u32 s57, s31, s57
	s_and_b64 s[66:67], s[8:9], exec
	s_cselect_b32 s39, s57, s65
	s_cselect_b32 s81, s56, s64
	v_lshl_add_u64 v[144:145], s[18:19], 0, v[136:137]
	v_lshl_add_u64 v[146:147], s[18:19], 0, v[138:139]
	s_mov_b32 s85, -2
	s_mov_b64 s[64:65], 0
	s_add_u32 s66, s18, s64
	v_add_u32_e32 v151, s48, v149
	s_addc_u32 s67, s19, s65
	ds_read_b128 v[152:155], v151
	ds_read_b128 v[156:159], v151 offset:1024
	ds_read_b128 v[160:163], v151 offset:2048
	ds_read_b128 v[164:167], v151 offset:3072
	v_add_u32_e32 v151, s49, v149
	s_add_u32 s66, s66, 0x10000
	ds_read_b128 v[168:171], v151
	ds_read_b128 v[172:175], v151 offset:1024
	ds_read_b128 v[176:179], v151 offset:2048
	ds_read_b128 v[180:183], v151 offset:3072
	s_addc_u32 s67, s67, 0
	s_add_u32 s70, s55, s64
	s_addc_u32 s71, s69, s65
	s_cmp_eq_u32 s64, 0x70000
	s_cselect_b32 s78, s80, s66
	s_cselect_b32 s79, s41, s67
	s_cselect_b32 s70, s81, s70
	s_cselect_b32 s71, s39, s71
	s_add_u32 s66, s78, 0x8000
	s_addc_u32 s67, s79, 0
	v_lshl_add_u64 v[196:197], v[144:145], 0, s[64:65]
	s_add_i32 m0, s11, 0xc000
	ds_read_b128 v[184:187], v150
	ds_read_b128 v[192:195], v150 offset:1024
	ds_read_b128 v[200:203], v150 offset:2048
	ds_read_b128 v[204:207], v150 offset:3072
	ds_read_b128 v[208:211], v150 offset:4096
	ds_read_b128 v[212:215], v150 offset:5120
	ds_read_b128 v[216:219], v150 offset:6144
	ds_read_b128 v[220:223], v150 offset:7168
	global_load_lds_dwordx4 v[196:197], off sc1
	v_lshl_add_u64 v[196:197], v[146:147], 0, s[64:65]
	s_add_i32 m0, s11, 0xe000
	s_nop 0
	global_load_lds_dwordx4 v[196:197], off sc1
	s_waitcnt vmcnt(8)
	s_waitcnt lgkmcnt(0)
	s_setprio 1
	s_barrier
	v_mfma_f32_16x16x32_bf16 v[104:107], v[152:155], v[184:187], 0
	v_mfma_f32_16x16x32_bf16 v[108:111], v[160:163], v[184:187], 0
	v_mfma_f32_16x16x32_bf16 v[84:87], v[152:155], v[200:203], 0
	v_mfma_f32_16x16x32_bf16 v[92:95], v[160:163], v[200:203], 0
	v_mfma_f32_16x16x32_bf16 v[72:75], v[152:155], v[208:211], 0
	v_mfma_f32_16x16x32_bf16 v[76:79], v[160:163], v[208:211], 0
	v_mfma_f32_16x16x32_bf16 v[64:67], v[152:155], v[216:219], 0
	v_mfma_f32_16x16x32_bf16 v[68:71], v[160:163], v[216:219], 0
	v_mfma_f32_16x16x32_bf16 v[104:107], v[156:159], v[192:195], v[104:107]
	v_mfma_f32_16x16x32_bf16 v[108:111], v[164:167], v[192:195], v[108:111]
	v_mfma_f32_16x16x32_bf16 v[84:87], v[156:159], v[204:207], v[84:87]
	v_mfma_f32_16x16x32_bf16 v[92:95], v[164:167], v[204:207], v[92:95]
	v_mfma_f32_16x16x32_bf16 v[72:75], v[156:159], v[212:215], v[72:75]
	v_mfma_f32_16x16x32_bf16 v[76:79], v[164:167], v[212:215], v[76:79]
	v_mfma_f32_16x16x32_bf16 v[64:67], v[156:159], v[220:223], v[64:67]
	v_mfma_f32_16x16x32_bf16 v[68:71], v[164:167], v[220:223], v[68:71]
	v_mfma_f32_16x16x32_bf16 v[120:123], v[168:171], v[184:187], 0
	v_mfma_f32_16x16x32_bf16 v[124:127], v[176:179], v[184:187], 0
	v_mfma_f32_16x16x32_bf16 v[112:115], v[168:171], v[200:203], 0
	v_mfma_f32_16x16x32_bf16 v[116:119], v[176:179], v[200:203], 0
	v_mfma_f32_16x16x32_bf16 v[96:99], v[168:171], v[208:211], 0
	v_mfma_f32_16x16x32_bf16 v[100:103], v[176:179], v[208:211], 0
	v_mfma_f32_16x16x32_bf16 v[80:83], v[168:171], v[216:219], 0
	v_mfma_f32_16x16x32_bf16 v[88:91], v[176:179], v[216:219], 0
	v_mfma_f32_16x16x32_bf16 v[120:123], v[172:175], v[192:195], v[120:123]
	v_mfma_f32_16x16x32_bf16 v[124:127], v[180:183], v[192:195], v[124:127]
	v_mfma_f32_16x16x32_bf16 v[112:115], v[172:175], v[204:207], v[112:115]
	v_mfma_f32_16x16x32_bf16 v[116:119], v[180:183], v[204:207], v[116:119]
	v_mfma_f32_16x16x32_bf16 v[96:99], v[172:175], v[212:215], v[96:99]
	v_mfma_f32_16x16x32_bf16 v[100:103], v[180:183], v[212:215], v[100:103]
	s_setprio 2
	s_barrier
	v_mfma_f32_16x16x32_bf16 v[80:83], v[172:175], v[220:223], v[80:83]
	v_mfma_f32_16x16x32_bf16 v[88:91], v[180:183], v[220:223], v[88:91]
	s_setprio 0
	s_add_i32 s86, s48, s37
	s_mov_b32 m0, s86
	ds_read_b128 v[184:187], v150 offset:16384
	ds_read_b128 v[192:195], v150 offset:17408
	ds_read_b128 v[200:203], v150 offset:18432
	ds_read_b128 v[204:207], v150 offset:19456
	ds_read_b128 v[208:211], v150 offset:20480
	ds_read_b128 v[212:215], v150 offset:21504
	ds_read_b128 v[216:219], v150 offset:22528
	ds_read_b128 v[220:223], v150 offset:23552
	global_load_lds_dwordx4 v132, s[70:71] sc1
	s_add_i32 m0, s86, 0x2000
	s_add_u32 s86, s70, 0x4000
	s_addc_u32 s87, s71, 0
	s_add_i32 s88, s49, s37
	global_load_lds_dwordx4 v134, s[70:71] sc1
	s_mov_b32 m0, s88
	s_nop 0
	global_load_lds_dwordx4 v132, s[86:87] sc1
	s_add_i32 m0, s88, 0x2000
	s_nop 0
	global_load_lds_dwordx4 v134, s[86:87] sc1
	s_mov_b32 m0, s11
	s_nop 0
	global_load_lds_dwordx4 v128, s[78:79] sc1
	s_mov_b32 m0, s42
	s_nop 0
	global_load_lds_dwordx4 v130, s[78:79] sc1
	s_waitcnt vmcnt(8)
	s_waitcnt lgkmcnt(0)
	s_setprio 1
	s_barrier
	v_mfma_f32_16x16x32_bf16 v[36:39], v[152:155], v[184:187], 0
	v_mfma_f32_16x16x32_bf16 v[44:47], v[160:163], v[184:187], 0
	v_mfma_f32_16x16x32_bf16 v[20:23], v[152:155], v[200:203], 0
	v_mfma_f32_16x16x32_bf16 v[28:31], v[160:163], v[200:203], 0
	v_mfma_f32_16x16x32_bf16 v[8:11], v[152:155], v[208:211], 0
	v_mfma_f32_16x16x32_bf16 v[12:15], v[160:163], v[208:211], 0
	v_mfma_f32_16x16x32_bf16 v[0:3], v[152:155], v[216:219], 0
	v_mfma_f32_16x16x32_bf16 v[4:7], v[160:163], v[216:219], 0
	v_mfma_f32_16x16x32_bf16 v[36:39], v[156:159], v[192:195], v[36:39]
	v_mfma_f32_16x16x32_bf16 v[44:47], v[164:167], v[192:195], v[44:47]
	v_mfma_f32_16x16x32_bf16 v[20:23], v[156:159], v[204:207], v[20:23]
	v_mfma_f32_16x16x32_bf16 v[28:31], v[164:167], v[204:207], v[28:31]
	v_mfma_f32_16x16x32_bf16 v[8:11], v[156:159], v[212:215], v[8:11]
	v_mfma_f32_16x16x32_bf16 v[12:15], v[164:167], v[212:215], v[12:15]
	v_mfma_f32_16x16x32_bf16 v[0:3], v[156:159], v[220:223], v[0:3]
	v_mfma_f32_16x16x32_bf16 v[4:7], v[164:167], v[220:223], v[4:7]
	v_mfma_f32_16x16x32_bf16 v[56:59], v[168:171], v[184:187], 0
	v_mfma_f32_16x16x32_bf16 v[60:63], v[176:179], v[184:187], 0
	v_mfma_f32_16x16x32_bf16 v[48:51], v[168:171], v[200:203], 0
	v_mfma_f32_16x16x32_bf16 v[52:55], v[176:179], v[200:203], 0
	v_mfma_f32_16x16x32_bf16 v[32:35], v[168:171], v[208:211], 0
	v_mfma_f32_16x16x32_bf16 v[40:43], v[176:179], v[208:211], 0
	v_mfma_f32_16x16x32_bf16 v[16:19], v[168:171], v[216:219], 0
	v_mfma_f32_16x16x32_bf16 v[24:27], v[176:179], v[216:219], 0
	v_mfma_f32_16x16x32_bf16 v[56:59], v[172:175], v[192:195], v[56:59]
	v_mfma_f32_16x16x32_bf16 v[60:63], v[180:183], v[192:195], v[60:63]
	v_mfma_f32_16x16x32_bf16 v[48:51], v[172:175], v[204:207], v[48:51]
	v_mfma_f32_16x16x32_bf16 v[52:55], v[180:183], v[204:207], v[52:55]
	v_mfma_f32_16x16x32_bf16 v[32:35], v[172:175], v[212:215], v[32:35]
	v_mfma_f32_16x16x32_bf16 v[40:43], v[180:183], v[212:215], v[40:43]
	s_setprio 2
	s_barrier
	v_mfma_f32_16x16x32_bf16 v[16:19], v[172:175], v[220:223], v[16:19]
	v_mfma_f32_16x16x32_bf16 v[24:27], v[180:183], v[220:223], v[24:27]
	s_setprio 0
	v_add_u32_e32 v151, s50, v149
	ds_read_b128 v[152:155], v151
	ds_read_b128 v[156:159], v151 offset:1024
	ds_read_b128 v[160:163], v151 offset:2048
	ds_read_b128 v[164:167], v151 offset:3072
	v_add_u32_e32 v151, s51, v149
	ds_read_b128 v[168:171], v151
	ds_read_b128 v[172:175], v151 offset:1024
	ds_read_b128 v[176:179], v151 offset:2048
	ds_read_b128 v[180:183], v151 offset:3072
	s_add_u32 s78, s78, 0x4000
	s_addc_u32 s79, s79, 0
	s_mov_b32 m0, s43
	ds_read_b128 v[184:187], v150 offset:32768
	ds_read_b128 v[192:195], v150 offset:33792
	ds_read_b128 v[200:203], v150 offset:34816
	ds_read_b128 v[204:207], v150 offset:35840
	ds_read_b128 v[208:211], v150 offset:36864
	ds_read_b128 v[212:215], v150 offset:37888
	ds_read_b128 v[216:219], v150 offset:38912
	ds_read_b128 v[220:223], v150 offset:39936
	global_load_lds_dwordx4 v128, s[78:79] sc1
	s_mov_b32 m0, s44
	s_nop 0
	global_load_lds_dwordx4 v130, s[78:79] sc1
	s_waitcnt vmcnt(8)
	s_waitcnt lgkmcnt(0)
	s_setprio 1
	s_barrier
	v_mfma_f32_16x16x32_bf16 v[104:107], v[152:155], v[184:187], v[104:107]
	v_mfma_f32_16x16x32_bf16 v[108:111], v[160:163], v[184:187], v[108:111]
	v_mfma_f32_16x16x32_bf16 v[84:87], v[152:155], v[200:203], v[84:87]
	v_mfma_f32_16x16x32_bf16 v[92:95], v[160:163], v[200:203], v[92:95]
	v_mfma_f32_16x16x32_bf16 v[72:75], v[152:155], v[208:211], v[72:75]
	v_mfma_f32_16x16x32_bf16 v[76:79], v[160:163], v[208:211], v[76:79]
	v_mfma_f32_16x16x32_bf16 v[64:67], v[152:155], v[216:219], v[64:67]
	v_mfma_f32_16x16x32_bf16 v[68:71], v[160:163], v[216:219], v[68:71]
	v_mfma_f32_16x16x32_bf16 v[104:107], v[156:159], v[192:195], v[104:107]
	v_mfma_f32_16x16x32_bf16 v[108:111], v[164:167], v[192:195], v[108:111]
	v_mfma_f32_16x16x32_bf16 v[84:87], v[156:159], v[204:207], v[84:87]
	v_mfma_f32_16x16x32_bf16 v[92:95], v[164:167], v[204:207], v[92:95]
	v_mfma_f32_16x16x32_bf16 v[72:75], v[156:159], v[212:215], v[72:75]
	v_mfma_f32_16x16x32_bf16 v[76:79], v[164:167], v[212:215], v[76:79]
	v_mfma_f32_16x16x32_bf16 v[64:67], v[156:159], v[220:223], v[64:67]
	v_mfma_f32_16x16x32_bf16 v[68:71], v[164:167], v[220:223], v[68:71]
	v_mfma_f32_16x16x32_bf16 v[120:123], v[168:171], v[184:187], v[120:123]
	v_mfma_f32_16x16x32_bf16 v[124:127], v[176:179], v[184:187], v[124:127]
	v_mfma_f32_16x16x32_bf16 v[112:115], v[168:171], v[200:203], v[112:115]
	v_mfma_f32_16x16x32_bf16 v[116:119], v[176:179], v[200:203], v[116:119]
	v_mfma_f32_16x16x32_bf16 v[96:99], v[168:171], v[208:211], v[96:99]
	v_mfma_f32_16x16x32_bf16 v[100:103], v[176:179], v[208:211], v[100:103]
	v_mfma_f32_16x16x32_bf16 v[80:83], v[168:171], v[216:219], v[80:83]
	v_mfma_f32_16x16x32_bf16 v[88:91], v[176:179], v[216:219], v[88:91]
	v_mfma_f32_16x16x32_bf16 v[120:123], v[172:175], v[192:195], v[120:123]
	v_mfma_f32_16x16x32_bf16 v[124:127], v[180:183], v[192:195], v[124:127]
	v_mfma_f32_16x16x32_bf16 v[112:115], v[172:175], v[204:207], v[112:115]
	v_mfma_f32_16x16x32_bf16 v[116:119], v[180:183], v[204:207], v[116:119]
	v_mfma_f32_16x16x32_bf16 v[96:99], v[172:175], v[212:215], v[96:99]
	v_mfma_f32_16x16x32_bf16 v[100:103], v[180:183], v[212:215], v[100:103]
	s_setprio 2
	s_barrier
	v_mfma_f32_16x16x32_bf16 v[80:83], v[172:175], v[220:223], v[80:83]
	v_mfma_f32_16x16x32_bf16 v[88:91], v[180:183], v[220:223], v[88:91]
	s_setprio 0
	s_add_u32 s78, s70, 0x8000
	s_addc_u32 s79, s71, 0
	s_add_i32 s86, s50, s37
	s_mov_b32 m0, s86
	ds_read_b128 v[184:187], v150 offset:49152
	ds_read_b128 v[192:195], v150 offset:50176
	ds_read_b128 v[200:203], v150 offset:51200
	ds_read_b128 v[204:207], v150 offset:52224
	ds_read_b128 v[208:211], v150 offset:53248
	ds_read_b128 v[212:215], v150 offset:54272
	ds_read_b128 v[216:219], v150 offset:55296
	ds_read_b128 v[220:223], v150 offset:56320
	global_load_lds_dwordx4 v132, s[78:79] sc1
	s_add_i32 m0, s86, 0x2000
	s_add_u32 s70, s70, 0xc000
	global_load_lds_dwordx4 v134, s[78:79] sc1
	s_addc_u32 s71, s71, 0
	s_add_i32 s78, s51, s37
	s_mov_b32 m0, s78
	s_nop 0
	global_load_lds_dwordx4 v132, s[70:71] sc1
	s_add_i32 m0, s78, 0x2000
	s_nop 0
	global_load_lds_dwordx4 v134, s[70:71] sc1
	s_mov_b32 m0, s17
	s_nop 0
	global_load_lds_dwordx4 v128, s[66:67] sc1
	s_mov_b32 m0, s46
	s_nop 0
	global_load_lds_dwordx4 v130, s[66:67] sc1
	s_waitcnt vmcnt(8)
	s_waitcnt lgkmcnt(0)
	s_setprio 1
	s_barrier
	v_mfma_f32_16x16x32_bf16 v[36:39], v[152:155], v[184:187], v[36:39]
	v_mfma_f32_16x16x32_bf16 v[44:47], v[160:163], v[184:187], v[44:47]
	v_mfma_f32_16x16x32_bf16 v[20:23], v[152:155], v[200:203], v[20:23]
	v_mfma_f32_16x16x32_bf16 v[28:31], v[160:163], v[200:203], v[28:31]
	v_mfma_f32_16x16x32_bf16 v[8:11], v[152:155], v[208:211], v[8:11]
	v_mfma_f32_16x16x32_bf16 v[12:15], v[160:163], v[208:211], v[12:15]
	v_mfma_f32_16x16x32_bf16 v[0:3], v[152:155], v[216:219], v[0:3]
	v_mfma_f32_16x16x32_bf16 v[4:7], v[160:163], v[216:219], v[4:7]
	v_mfma_f32_16x16x32_bf16 v[36:39], v[156:159], v[192:195], v[36:39]
	v_mfma_f32_16x16x32_bf16 v[44:47], v[164:167], v[192:195], v[44:47]
	v_mfma_f32_16x16x32_bf16 v[20:23], v[156:159], v[204:207], v[20:23]
	v_mfma_f32_16x16x32_bf16 v[28:31], v[164:167], v[204:207], v[28:31]
	v_mfma_f32_16x16x32_bf16 v[8:11], v[156:159], v[212:215], v[8:11]
	v_mfma_f32_16x16x32_bf16 v[12:15], v[164:167], v[212:215], v[12:15]
	v_mfma_f32_16x16x32_bf16 v[0:3], v[156:159], v[220:223], v[0:3]
	v_mfma_f32_16x16x32_bf16 v[4:7], v[164:167], v[220:223], v[4:7]
	v_mfma_f32_16x16x32_bf16 v[56:59], v[168:171], v[184:187], v[56:59]
	v_mfma_f32_16x16x32_bf16 v[60:63], v[176:179], v[184:187], v[60:63]
	v_mfma_f32_16x16x32_bf16 v[48:51], v[168:171], v[200:203], v[48:51]
	v_mfma_f32_16x16x32_bf16 v[52:55], v[176:179], v[200:203], v[52:55]
	v_mfma_f32_16x16x32_bf16 v[32:35], v[168:171], v[208:211], v[32:35]
	v_mfma_f32_16x16x32_bf16 v[40:43], v[176:179], v[208:211], v[40:43]
	v_mfma_f32_16x16x32_bf16 v[16:19], v[168:171], v[216:219], v[16:19]
	v_mfma_f32_16x16x32_bf16 v[24:27], v[176:179], v[216:219], v[24:27]
	v_mfma_f32_16x16x32_bf16 v[56:59], v[172:175], v[192:195], v[56:59]
	v_mfma_f32_16x16x32_bf16 v[60:63], v[180:183], v[192:195], v[60:63]
	v_mfma_f32_16x16x32_bf16 v[48:51], v[172:175], v[204:207], v[48:51]
	v_mfma_f32_16x16x32_bf16 v[52:55], v[180:183], v[204:207], v[52:55]
	v_mfma_f32_16x16x32_bf16 v[32:35], v[172:175], v[212:215], v[32:35]
	v_mfma_f32_16x16x32_bf16 v[40:43], v[180:183], v[212:215], v[40:43]
	s_setprio 2
	s_barrier
	v_mfma_f32_16x16x32_bf16 v[16:19], v[172:175], v[220:223], v[16:19]
	v_mfma_f32_16x16x32_bf16 v[24:27], v[180:183], v[220:223], v[24:27]
	s_setprio 0
	s_add_i32 s85, s85, 2
	s_add_u32 s64, s64, 0x10000
	s_addc_u32 s65, s65, 0
	s_cmp_gt_u32 s85, 13
.LBB0_976:
	s_add_u32 s66, s18, s64
	v_add_u32_e32 v151, s48, v149
	s_addc_u32 s67, s19, s65
	ds_read_b128 v[152:155], v151
	ds_read_b128 v[156:159], v151 offset:1024
	ds_read_b128 v[160:163], v151 offset:2048
	ds_read_b128 v[164:167], v151 offset:3072
	v_add_u32_e32 v151, s49, v149
	s_add_u32 s66, s66, 0x10000
	ds_read_b128 v[168:171], v151
	ds_read_b128 v[172:175], v151 offset:1024
	ds_read_b128 v[176:179], v151 offset:2048
	ds_read_b128 v[180:183], v151 offset:3072
	s_addc_u32 s67, s67, 0
	s_add_u32 s70, s55, s64
	s_addc_u32 s71, s69, s65
	s_cmp_eq_u32 s64, 0x70000
	s_cselect_b32 s78, s80, s66
	s_cselect_b32 s79, s41, s67
	s_cselect_b32 s70, s81, s70
	s_cselect_b32 s71, s39, s71
	s_add_u32 s66, s78, 0x8000
	s_addc_u32 s67, s79, 0
	v_lshl_add_u64 v[196:197], v[144:145], 0, s[64:65]
	s_add_i32 m0, s11, 0xc000
	ds_read_b128 v[184:187], v150
	ds_read_b128 v[192:195], v150 offset:1024
	ds_read_b128 v[200:203], v150 offset:2048
	ds_read_b128 v[204:207], v150 offset:3072
	ds_read_b128 v[208:211], v150 offset:4096
	ds_read_b128 v[212:215], v150 offset:5120
	ds_read_b128 v[216:219], v150 offset:6144
	ds_read_b128 v[220:223], v150 offset:7168
	global_load_lds_dwordx4 v[196:197], off sc1
	v_lshl_add_u64 v[196:197], v[146:147], 0, s[64:65]
	s_add_i32 m0, s11, 0xe000
	s_nop 0
	global_load_lds_dwordx4 v[196:197], off sc1
	s_waitcnt vmcnt(8)
	s_waitcnt lgkmcnt(0)
	s_setprio 1
	s_barrier
	v_mfma_f32_16x16x32_bf16 v[104:107], v[152:155], v[184:187], v[104:107]
	v_mfma_f32_16x16x32_bf16 v[108:111], v[160:163], v[184:187], v[108:111]
	v_mfma_f32_16x16x32_bf16 v[84:87], v[152:155], v[200:203], v[84:87]
	v_mfma_f32_16x16x32_bf16 v[92:95], v[160:163], v[200:203], v[92:95]
	v_mfma_f32_16x16x32_bf16 v[72:75], v[152:155], v[208:211], v[72:75]
	v_mfma_f32_16x16x32_bf16 v[76:79], v[160:163], v[208:211], v[76:79]
	v_mfma_f32_16x16x32_bf16 v[64:67], v[152:155], v[216:219], v[64:67]
	v_mfma_f32_16x16x32_bf16 v[68:71], v[160:163], v[216:219], v[68:71]
	v_mfma_f32_16x16x32_bf16 v[104:107], v[156:159], v[192:195], v[104:107]
	v_mfma_f32_16x16x32_bf16 v[108:111], v[164:167], v[192:195], v[108:111]
	v_mfma_f32_16x16x32_bf16 v[84:87], v[156:159], v[204:207], v[84:87]
	v_mfma_f32_16x16x32_bf16 v[92:95], v[164:167], v[204:207], v[92:95]
	v_mfma_f32_16x16x32_bf16 v[72:75], v[156:159], v[212:215], v[72:75]
	v_mfma_f32_16x16x32_bf16 v[76:79], v[164:167], v[212:215], v[76:79]
	v_mfma_f32_16x16x32_bf16 v[64:67], v[156:159], v[220:223], v[64:67]
	v_mfma_f32_16x16x32_bf16 v[68:71], v[164:167], v[220:223], v[68:71]
	v_mfma_f32_16x16x32_bf16 v[120:123], v[168:171], v[184:187], v[120:123]
	v_mfma_f32_16x16x32_bf16 v[124:127], v[176:179], v[184:187], v[124:127]
	v_mfma_f32_16x16x32_bf16 v[112:115], v[168:171], v[200:203], v[112:115]
	v_mfma_f32_16x16x32_bf16 v[116:119], v[176:179], v[200:203], v[116:119]
	v_mfma_f32_16x16x32_bf16 v[96:99], v[168:171], v[208:211], v[96:99]
	v_mfma_f32_16x16x32_bf16 v[100:103], v[176:179], v[208:211], v[100:103]
	v_mfma_f32_16x16x32_bf16 v[80:83], v[168:171], v[216:219], v[80:83]
	v_mfma_f32_16x16x32_bf16 v[88:91], v[176:179], v[216:219], v[88:91]
	v_mfma_f32_16x16x32_bf16 v[120:123], v[172:175], v[192:195], v[120:123]
	v_mfma_f32_16x16x32_bf16 v[124:127], v[180:183], v[192:195], v[124:127]
	v_mfma_f32_16x16x32_bf16 v[112:115], v[172:175], v[204:207], v[112:115]
	v_mfma_f32_16x16x32_bf16 v[116:119], v[180:183], v[204:207], v[116:119]
	v_mfma_f32_16x16x32_bf16 v[96:99], v[172:175], v[212:215], v[96:99]
	v_mfma_f32_16x16x32_bf16 v[100:103], v[180:183], v[212:215], v[100:103]
	s_setprio 2
	s_barrier
	v_mfma_f32_16x16x32_bf16 v[80:83], v[172:175], v[220:223], v[80:83]
	v_mfma_f32_16x16x32_bf16 v[88:91], v[180:183], v[220:223], v[88:91]
	s_setprio 0
	s_add_i32 s86, s48, s37
	s_mov_b32 m0, s86
	ds_read_b128 v[184:187], v150 offset:16384
	ds_read_b128 v[192:195], v150 offset:17408
	ds_read_b128 v[200:203], v150 offset:18432
	ds_read_b128 v[204:207], v150 offset:19456
	ds_read_b128 v[208:211], v150 offset:20480
	ds_read_b128 v[212:215], v150 offset:21504
	ds_read_b128 v[216:219], v150 offset:22528
	ds_read_b128 v[220:223], v150 offset:23552
	global_load_lds_dwordx4 v132, s[70:71] sc1
	s_add_i32 m0, s86, 0x2000
	s_add_u32 s86, s70, 0x4000
	s_addc_u32 s87, s71, 0
	s_add_i32 s88, s49, s37
	global_load_lds_dwordx4 v134, s[70:71] sc1
	s_mov_b32 m0, s88
	s_nop 0
	global_load_lds_dwordx4 v132, s[86:87] sc1
	s_add_i32 m0, s88, 0x2000
	s_nop 0
	global_load_lds_dwordx4 v134, s[86:87] sc1
	s_mov_b32 m0, s11
	s_nop 0
	global_load_lds_dwordx4 v128, s[78:79] sc1
	s_mov_b32 m0, s42
	s_nop 0
	global_load_lds_dwordx4 v130, s[78:79] sc1
	s_waitcnt vmcnt(8)
	s_waitcnt lgkmcnt(0)
	s_setprio 1
	s_barrier
	v_mfma_f32_16x16x32_bf16 v[36:39], v[152:155], v[184:187], v[36:39]
	v_mfma_f32_16x16x32_bf16 v[44:47], v[160:163], v[184:187], v[44:47]
	v_mfma_f32_16x16x32_bf16 v[20:23], v[152:155], v[200:203], v[20:23]
	v_mfma_f32_16x16x32_bf16 v[28:31], v[160:163], v[200:203], v[28:31]
	v_mfma_f32_16x16x32_bf16 v[8:11], v[152:155], v[208:211], v[8:11]
	v_mfma_f32_16x16x32_bf16 v[12:15], v[160:163], v[208:211], v[12:15]
	v_mfma_f32_16x16x32_bf16 v[0:3], v[152:155], v[216:219], v[0:3]
	v_mfma_f32_16x16x32_bf16 v[4:7], v[160:163], v[216:219], v[4:7]
	v_mfma_f32_16x16x32_bf16 v[36:39], v[156:159], v[192:195], v[36:39]
	v_mfma_f32_16x16x32_bf16 v[44:47], v[164:167], v[192:195], v[44:47]
	v_mfma_f32_16x16x32_bf16 v[20:23], v[156:159], v[204:207], v[20:23]
	v_mfma_f32_16x16x32_bf16 v[28:31], v[164:167], v[204:207], v[28:31]
	v_mfma_f32_16x16x32_bf16 v[8:11], v[156:159], v[212:215], v[8:11]
	v_mfma_f32_16x16x32_bf16 v[12:15], v[164:167], v[212:215], v[12:15]
	v_mfma_f32_16x16x32_bf16 v[0:3], v[156:159], v[220:223], v[0:3]
	v_mfma_f32_16x16x32_bf16 v[4:7], v[164:167], v[220:223], v[4:7]
	v_mfma_f32_16x16x32_bf16 v[56:59], v[168:171], v[184:187], v[56:59]
	v_mfma_f32_16x16x32_bf16 v[60:63], v[176:179], v[184:187], v[60:63]
	v_mfma_f32_16x16x32_bf16 v[48:51], v[168:171], v[200:203], v[48:51]
	v_mfma_f32_16x16x32_bf16 v[52:55], v[176:179], v[200:203], v[52:55]
	v_mfma_f32_16x16x32_bf16 v[32:35], v[168:171], v[208:211], v[32:35]
	v_mfma_f32_16x16x32_bf16 v[40:43], v[176:179], v[208:211], v[40:43]
	v_mfma_f32_16x16x32_bf16 v[16:19], v[168:171], v[216:219], v[16:19]
	v_mfma_f32_16x16x32_bf16 v[24:27], v[176:179], v[216:219], v[24:27]
	v_mfma_f32_16x16x32_bf16 v[56:59], v[172:175], v[192:195], v[56:59]
	v_mfma_f32_16x16x32_bf16 v[60:63], v[180:183], v[192:195], v[60:63]
	v_mfma_f32_16x16x32_bf16 v[48:51], v[172:175], v[204:207], v[48:51]
	v_mfma_f32_16x16x32_bf16 v[52:55], v[180:183], v[204:207], v[52:55]
	v_mfma_f32_16x16x32_bf16 v[32:35], v[172:175], v[212:215], v[32:35]
	v_mfma_f32_16x16x32_bf16 v[40:43], v[180:183], v[212:215], v[40:43]
	s_setprio 2
	s_barrier
	v_mfma_f32_16x16x32_bf16 v[16:19], v[172:175], v[220:223], v[16:19]
	v_mfma_f32_16x16x32_bf16 v[24:27], v[180:183], v[220:223], v[24:27]
	s_setprio 0
	v_add_u32_e32 v151, s50, v149
	ds_read_b128 v[152:155], v151
	ds_read_b128 v[156:159], v151 offset:1024
	ds_read_b128 v[160:163], v151 offset:2048
	ds_read_b128 v[164:167], v151 offset:3072
	v_add_u32_e32 v151, s51, v149
	ds_read_b128 v[168:171], v151
	ds_read_b128 v[172:175], v151 offset:1024
	ds_read_b128 v[176:179], v151 offset:2048
	ds_read_b128 v[180:183], v151 offset:3072
	s_add_u32 s78, s78, 0x4000
	s_addc_u32 s79, s79, 0
	s_mov_b32 m0, s43
	ds_read_b128 v[184:187], v150 offset:32768
	ds_read_b128 v[192:195], v150 offset:33792
	ds_read_b128 v[200:203], v150 offset:34816
	ds_read_b128 v[204:207], v150 offset:35840
	ds_read_b128 v[208:211], v150 offset:36864
	ds_read_b128 v[212:215], v150 offset:37888
	ds_read_b128 v[216:219], v150 offset:38912
	ds_read_b128 v[220:223], v150 offset:39936
	global_load_lds_dwordx4 v128, s[78:79] sc1
	s_mov_b32 m0, s44
	s_nop 0
	global_load_lds_dwordx4 v130, s[78:79] sc1
	s_waitcnt vmcnt(8)
	s_waitcnt lgkmcnt(0)
	s_setprio 1
	s_barrier
	v_mfma_f32_16x16x32_bf16 v[104:107], v[152:155], v[184:187], v[104:107]
	v_mfma_f32_16x16x32_bf16 v[108:111], v[160:163], v[184:187], v[108:111]
	v_mfma_f32_16x16x32_bf16 v[84:87], v[152:155], v[200:203], v[84:87]
	v_mfma_f32_16x16x32_bf16 v[92:95], v[160:163], v[200:203], v[92:95]
	v_mfma_f32_16x16x32_bf16 v[72:75], v[152:155], v[208:211], v[72:75]
	v_mfma_f32_16x16x32_bf16 v[76:79], v[160:163], v[208:211], v[76:79]
	v_mfma_f32_16x16x32_bf16 v[64:67], v[152:155], v[216:219], v[64:67]
	v_mfma_f32_16x16x32_bf16 v[68:71], v[160:163], v[216:219], v[68:71]
	v_mfma_f32_16x16x32_bf16 v[104:107], v[156:159], v[192:195], v[104:107]
	v_mfma_f32_16x16x32_bf16 v[108:111], v[164:167], v[192:195], v[108:111]
	v_mfma_f32_16x16x32_bf16 v[84:87], v[156:159], v[204:207], v[84:87]
	v_mfma_f32_16x16x32_bf16 v[92:95], v[164:167], v[204:207], v[92:95]
	v_mfma_f32_16x16x32_bf16 v[72:75], v[156:159], v[212:215], v[72:75]
	v_mfma_f32_16x16x32_bf16 v[76:79], v[164:167], v[212:215], v[76:79]
	v_mfma_f32_16x16x32_bf16 v[64:67], v[156:159], v[220:223], v[64:67]
	v_mfma_f32_16x16x32_bf16 v[68:71], v[164:167], v[220:223], v[68:71]
	v_mfma_f32_16x16x32_bf16 v[120:123], v[168:171], v[184:187], v[120:123]
	v_mfma_f32_16x16x32_bf16 v[124:127], v[176:179], v[184:187], v[124:127]
	v_mfma_f32_16x16x32_bf16 v[112:115], v[168:171], v[200:203], v[112:115]
	v_mfma_f32_16x16x32_bf16 v[116:119], v[176:179], v[200:203], v[116:119]
	v_mfma_f32_16x16x32_bf16 v[96:99], v[168:171], v[208:211], v[96:99]
	v_mfma_f32_16x16x32_bf16 v[100:103], v[176:179], v[208:211], v[100:103]
	v_mfma_f32_16x16x32_bf16 v[80:83], v[168:171], v[216:219], v[80:83]
	v_mfma_f32_16x16x32_bf16 v[88:91], v[176:179], v[216:219], v[88:91]
	v_mfma_f32_16x16x32_bf16 v[120:123], v[172:175], v[192:195], v[120:123]
	v_mfma_f32_16x16x32_bf16 v[124:127], v[180:183], v[192:195], v[124:127]
	v_mfma_f32_16x16x32_bf16 v[112:115], v[172:175], v[204:207], v[112:115]
	v_mfma_f32_16x16x32_bf16 v[116:119], v[180:183], v[204:207], v[116:119]
	v_mfma_f32_16x16x32_bf16 v[96:99], v[172:175], v[212:215], v[96:99]
	v_mfma_f32_16x16x32_bf16 v[100:103], v[180:183], v[212:215], v[100:103]
	s_setprio 2
	s_barrier
	v_mfma_f32_16x16x32_bf16 v[80:83], v[172:175], v[220:223], v[80:83]
	v_mfma_f32_16x16x32_bf16 v[88:91], v[180:183], v[220:223], v[88:91]
	s_setprio 0
	s_add_u32 s78, s70, 0x8000
	s_addc_u32 s79, s71, 0
	s_add_i32 s86, s50, s37
	s_mov_b32 m0, s86
	ds_read_b128 v[184:187], v150 offset:49152
	ds_read_b128 v[192:195], v150 offset:50176
	ds_read_b128 v[200:203], v150 offset:51200
	ds_read_b128 v[204:207], v150 offset:52224
	ds_read_b128 v[208:211], v150 offset:53248
	ds_read_b128 v[212:215], v150 offset:54272
	ds_read_b128 v[216:219], v150 offset:55296
	ds_read_b128 v[220:223], v150 offset:56320
	global_load_lds_dwordx4 v132, s[78:79] sc1
	s_add_i32 m0, s86, 0x2000
	s_add_u32 s70, s70, 0xc000
	global_load_lds_dwordx4 v134, s[78:79] sc1
	s_addc_u32 s71, s71, 0
	s_add_i32 s78, s51, s37
	s_mov_b32 m0, s78
	s_nop 0
	global_load_lds_dwordx4 v132, s[70:71] sc1
	s_add_i32 m0, s78, 0x2000
	s_nop 0
	global_load_lds_dwordx4 v134, s[70:71] sc1
	s_mov_b32 m0, s17
	s_nop 0
	global_load_lds_dwordx4 v128, s[66:67] sc1
	s_mov_b32 m0, s46
	s_nop 0
	global_load_lds_dwordx4 v130, s[66:67] sc1
	s_waitcnt vmcnt(8)
	s_waitcnt lgkmcnt(0)
	s_setprio 1
	s_barrier
	v_mfma_f32_16x16x32_bf16 v[36:39], v[152:155], v[184:187], v[36:39]
	v_mfma_f32_16x16x32_bf16 v[44:47], v[160:163], v[184:187], v[44:47]
	v_mfma_f32_16x16x32_bf16 v[20:23], v[152:155], v[200:203], v[20:23]
	v_mfma_f32_16x16x32_bf16 v[28:31], v[160:163], v[200:203], v[28:31]
	v_mfma_f32_16x16x32_bf16 v[8:11], v[152:155], v[208:211], v[8:11]
	v_mfma_f32_16x16x32_bf16 v[12:15], v[160:163], v[208:211], v[12:15]
	v_mfma_f32_16x16x32_bf16 v[0:3], v[152:155], v[216:219], v[0:3]
	v_mfma_f32_16x16x32_bf16 v[4:7], v[160:163], v[216:219], v[4:7]
	v_mfma_f32_16x16x32_bf16 v[36:39], v[156:159], v[192:195], v[36:39]
	v_mfma_f32_16x16x32_bf16 v[44:47], v[164:167], v[192:195], v[44:47]
	v_mfma_f32_16x16x32_bf16 v[20:23], v[156:159], v[204:207], v[20:23]
	v_mfma_f32_16x16x32_bf16 v[28:31], v[164:167], v[204:207], v[28:31]
	v_mfma_f32_16x16x32_bf16 v[8:11], v[156:159], v[212:215], v[8:11]
	v_mfma_f32_16x16x32_bf16 v[12:15], v[164:167], v[212:215], v[12:15]
	v_mfma_f32_16x16x32_bf16 v[0:3], v[156:159], v[220:223], v[0:3]
	v_mfma_f32_16x16x32_bf16 v[4:7], v[164:167], v[220:223], v[4:7]
	v_mfma_f32_16x16x32_bf16 v[56:59], v[168:171], v[184:187], v[56:59]
	v_mfma_f32_16x16x32_bf16 v[60:63], v[176:179], v[184:187], v[60:63]
	v_mfma_f32_16x16x32_bf16 v[48:51], v[168:171], v[200:203], v[48:51]
	v_mfma_f32_16x16x32_bf16 v[52:55], v[176:179], v[200:203], v[52:55]
	v_mfma_f32_16x16x32_bf16 v[32:35], v[168:171], v[208:211], v[32:35]
	v_mfma_f32_16x16x32_bf16 v[40:43], v[176:179], v[208:211], v[40:43]
	v_mfma_f32_16x16x32_bf16 v[16:19], v[168:171], v[216:219], v[16:19]
	v_mfma_f32_16x16x32_bf16 v[24:27], v[176:179], v[216:219], v[24:27]
	v_mfma_f32_16x16x32_bf16 v[56:59], v[172:175], v[192:195], v[56:59]
	v_mfma_f32_16x16x32_bf16 v[60:63], v[180:183], v[192:195], v[60:63]
	v_mfma_f32_16x16x32_bf16 v[48:51], v[172:175], v[204:207], v[48:51]
	v_mfma_f32_16x16x32_bf16 v[52:55], v[180:183], v[204:207], v[52:55]
	v_mfma_f32_16x16x32_bf16 v[32:35], v[172:175], v[212:215], v[32:35]
	v_mfma_f32_16x16x32_bf16 v[40:43], v[180:183], v[212:215], v[40:43]
	s_setprio 2
	s_barrier
	v_mfma_f32_16x16x32_bf16 v[16:19], v[172:175], v[220:223], v[16:19]
	v_mfma_f32_16x16x32_bf16 v[24:27], v[180:183], v[220:223], v[24:27]
	s_setprio 0
	s_add_i32 s85, s85, 2
	s_add_u32 s64, s64, 0x10000
	s_addc_u32 s65, s65, 0
	s_cmp_gt_u32 s85, 13
	s_cbranch_scc0 .LBB0_976
	s_add_u32 s64, s55, 0xffff0000
	s_addc_u32 s65, s69, -1
	s_andn2_b64 vcc, exec, s[8:9]
	s_cbranch_vccnz .LBB0_967
	s_mov_b32 s16, s38
	s_mov_b32 s10, s40
	s_mov_b64 s[18:19], s[62:63]
	s_mov_b32 s47, s54
	s_andn2_b64 vcc, exec, s[6:7]
	s_cbranch_vccnz .LBB0_968

.LBB0_1016:
	v_bfe_i32 v2, v148, 27, 1
	v_lshlrev_b32_e32 v0, 4, v148
	v_lshrrev_b32_e32 v2, 22, v2
	v_add_u32_e32 v2, v0, v2
	v_and_b32_e32 v2, 0xfffffc00, v2
	v_sub_u32_e32 v2, v0, v2
	v_ashrrev_i32_e32 v1, 31, v148
	v_lshrrev_b32_e32 v3, 4, v2
	v_lshrrev_b32_e32 v1, 26, v1
	v_bitop3_b32 v2, v3, v2, 32 bitop3:0x6c
	v_add_u32_e32 v1, v148, v1
	v_ashrrev_i32_e32 v4, 31, v2
	v_ashrrev_i32_e32 v1, 6, v1
	v_lshrrev_b32_e32 v4, 26, v4
	v_lshlrev_b32_e32 v3, 3, v1
	v_add_u32_e32 v4, v2, v4
	v_and_b32_e32 v3, -16, v3
	v_ashrrev_i32_e32 v132, 6, v4
	v_add_u32_e32 v136, v132, v3
	v_and_b32_e32 v3, 0xc0, v4
	v_lshlrev_b32_e32 v1, 5, v1
	v_sub_u32_e32 v2, v2, v3
	v_mov_b32_e32 v3, 1
	v_and_b32_e32 v1, 32, v1
	v_ashrrev_i16_sdwa v2, v3, sext(v2) dst_sel:DWORD dst_unused:UNUSED_PAD src0_sel:DWORD src1_sel:BYTE_0
	v_add_u32_sdwa v1, v1, sext(v2) dst_sel:DWORD dst_unused:UNUSED_PAD src0_sel:DWORD src1_sel:WORD_0
	v_and_b32_e32 v4, 0x1fffffe, v136
	v_lshrrev_b32_e32 v137, 5, v1
	v_add_lshl_u32 v1, v137, v4, 6
	v_lshlrev_b32_e32 v4, 5, v136
	v_and_b32_e32 v138, 32, v4
	v_mov_b32_e32 v4, 31
	v_and_b32_sdwa v139, sext(v2), v4 dst_sel:DWORD dst_unused:UNUSED_PAD src0_sel:WORD_0 src1_sel:DWORD
	v_or3_b32 v1, v1, v138, v139
	v_add_u32_e32 v0, 0x2000, v0
	v_lshlrev_b32_e32 v128, 1, v1
	v_ashrrev_i32_e32 v1, 31, v0
	v_lshrrev_b32_e32 v1, 22, v1
	v_add_u32_e32 v1, v0, v1
	v_ashrrev_i32_e32 v1, 10, v1
	v_mul_i32_i24_e32 v2, 0x400, v1
	v_sub_u32_e32 v0, v0, v2
	v_lshrrev_b32_e32 v2, 4, v0
	v_bitop3_b32 v0, v2, v0, 32 bitop3:0x6c
	v_ashrrev_i32_e32 v5, 31, v0
	v_lshrrev_b32_e32 v5, 26, v5
	v_readlane_b32 s7, v252, 7
	v_lshlrev_b32_e32 v2, 3, v1
	v_add_u32_e32 v5, v0, v5
	s_add_i32 s8, s8, s7
	v_and_b32_e32 v2, -16, v2
	v_ashrrev_i32_e32 v133, 6, v5
	s_ashr_i32 s7, s8, 31
	v_add_u32_e32 v140, v133, v2
	v_and_b32_e32 v2, 0xc0, v5
	s_lshr_b32 s7, s7, 27
	v_lshlrev_b32_e32 v1, 5, v1
	v_sub_u32_e32 v0, v0, v2
	s_add_i32 s9, s8, s7
	v_and_b32_e32 v1, 32, v1
	v_ashrrev_i16_sdwa v0, v3, sext(v0) dst_sel:DWORD dst_unused:UNUSED_PAD src0_sel:DWORD src1_sel:BYTE_0
	s_ashr_i32 s7, s9, 5
	v_add_u32_sdwa v1, v1, sext(v0) dst_sel:DWORD dst_unused:UNUSED_PAD src0_sel:DWORD src1_sel:WORD_0
	s_lshl_b32 s10, s7, 3
	v_and_b32_e32 v2, 0x1fffffe, v140
	v_lshrrev_b32_e32 v141, 5, v1
	s_sub_i32 s7, 64, s10
	v_add_lshl_u32 v1, v141, v2, 6
	v_lshlrev_b32_e32 v2, 5, v140
	s_min_i32 s11, s7, 8
	v_and_b32_e32 v142, 32, v2
	v_and_b32_sdwa v143, sext(v0), v4 dst_sel:DWORD dst_unused:UNUSED_PAD src0_sel:WORD_0 src1_sel:DWORD
	s_abs_i32 s18, s11
	v_or3_b32 v0, v1, v142, v143
	v_cvt_f32_u32_e32 v1, s18
	v_lshlrev_b32_e32 v130, 1, v0
	s_sub_i32 s37, 0, s18
	s_andn2_b32 s9, s9, 31
	v_rcp_iflag_f32_e32 v0, v1
	s_sub_i32 s8, s8, s9
	s_abs_i32 s19, s8
	s_ashr_i32 s6, s36, 6
	v_mul_f32_e32 v0, 0x4f7ffffe, v0
	v_cvt_u32_f32_e32 v0, v0
	s_xor_b32 s9, s8, s11
	s_ashr_i32 s7, s36, 8
	s_lshl_b32 s35, s6, 10
	v_readfirstlane_b32 s40, v0
	s_mul_i32 s37, s37, s40
	s_mul_hi_u32 s37, s40, s37
	s_add_i32 s40, s40, s37
	s_mul_hi_u32 s37, s19, s40
	s_mul_i32 s40, s37, s18
	s_sub_i32 s19, s19, s40
	s_ashr_i32 s9, s9, 31
	s_add_i32 s40, s37, 1
	s_sub_i32 s41, s19, s18
	s_cmp_ge_u32 s19, s18
	s_cselect_b32 s37, s40, s37
	s_cselect_b32 s19, s41, s19
	s_add_i32 s40, s37, 1
	s_cmp_ge_u32 s19, s18
	s_cselect_b32 s18, s40, s37
	s_xor_b32 s18, s18, s9
	s_sub_i32 s18, s18, s9
	s_mul_i32 s9, s18, s11
	s_sub_i32 s8, s8, s9
	s_add_i32 s40, s10, s8
	s_mul_i32 s9, s40, 0x180000
	s_mul_hi_i32 s8, s40, 0x180000
	s_add_u32 s56, s76, s9
	v_readlane_b32 s9, v253, 53
	s_addc_u32 s57, s9, s8
	s_add_i32 s42, s35, 0x100
	s_add_i32 s43, s42, 0x2000
	s_mov_b32 m0, s42
	s_add_u32 s8, s56, 0x4000
	global_load_lds_dwordx4 v128, s[56:57] sc1
	s_mov_b32 m0, s43
	s_addc_u32 s9, s57, 0
	s_add_i32 s44, s42, 0x4000
	global_load_lds_dwordx4 v130, s[56:57] sc1
	s_mov_b32 m0, s44
	s_add_i32 s45, s42, 0x6000
	global_load_lds_dwordx4 v128, s[8:9] sc1
	s_mov_b32 m0, s45
	v_mov_b32_e32 v129, 0
	global_load_lds_dwordx4 v130, s[8:9] sc1
	s_mov_b32 s49, 0
	s_cmp_lg_u32 s7, 1
	v_mov_b32_e32 v131, v129
	s_cbranch_scc1 .LBB0_1018
	s_barrier

.LBB0_1019:
	s_mov_b32 s18, s64
	s_mov_b32 s40, s61
	s_mov_b64 s[56:57], s[66:67]
	s_mov_b32 s49, s69
	s_andn2_b64 vcc, exec, s[6:7]
	s_cbranch_vccz .LBB0_1032

.LBB0_1028:
	s_add_u32 s77, s62, 0x10000
	s_addc_u32 s82, s63, 0
	s_ashr_i32 s65, s64, 31
	s_lshl_b64 s[62:63], s[64:65], 19
	s_add_u32 s62, s38, s62
	s_addc_u32 s63, s39, s63
	s_lshl_b32 s70, s18, 2
	s_ashr_i32 s41, s40, 31
	s_ashr_i32 s71, s70, 31
	s_lshl_b64 s[78:79], s[40:41], 19
	s_lshl_b64 s[70:71], s[70:71], 15
	s_add_u32 s41, s60, s70
	s_addc_u32 s65, s33, s71
	s_add_u32 s41, s41, s78
	s_addc_u32 s65, s65, s79
	s_add_u32 s70, s41, 0x10000
	s_addc_u32 s71, s65, 0
	s_and_b64 s[10:11], s[10:11], exec
	s_cselect_b32 s83, s67, s71
	s_cselect_b32 s84, s66, s70
	s_cselect_b32 s85, s63, s65
	s_cselect_b32 s86, s62, s41
	v_lshl_add_u64 v[144:145], s[56:57], 0, v[136:137]
	v_lshl_add_u64 v[146:147], s[56:57], 0, v[138:139]
	s_mov_b32 s87, -2
	s_mov_b64 s[10:11], 0
	s_add_u32 s41, s56, s10
	s_addc_u32 s65, s57, s11
	v_add_u32_e32 v168, s50, v151
	v_add_u32_e32 v184, s51, v151
	s_add_u32 s41, s41, 0x10000
	ds_read_b128 v[156:159], v168
	ds_read_b128 v[160:163], v168 offset:1024
	ds_read_b128 v[164:167], v168 offset:2048
	ds_read_b128 v[168:171], v168 offset:3072
	ds_read_b128 v[172:175], v184
	ds_read_b128 v[176:179], v184 offset:1024
	ds_read_b128 v[180:183], v184 offset:2048
	ds_read_b128 v[184:187], v184 offset:3072
	s_addc_u32 s65, s65, 0
	s_add_u32 s70, s77, s10
	s_addc_u32 s71, s82, s11
	s_cmp_eq_u32 s10, 0x70000
	s_cselect_b32 s80, s84, s41
	s_cselect_b32 s81, s83, s65
	s_cselect_b32 s78, s86, s70
	s_cselect_b32 s79, s85, s71
	s_add_u32 s70, s80, 0x8000
	s_addc_u32 s71, s81, 0
	s_add_i32 s41, s42, 0xc000
	v_lshl_add_u64 v[196:197], v[144:145], 0, s[10:11]
	s_mov_b32 m0, s41
	s_add_i32 s65, s42, 0xe000
	ds_read_b128 v[192:195], v154
	ds_read_b128 v[200:203], v154 offset:1024
	ds_read_b128 v[204:207], v154 offset:2048
	ds_read_b128 v[208:211], v154 offset:3072
	ds_read_b128 v[212:215], v154 offset:4096
	ds_read_b128 v[216:219], v154 offset:5120
	ds_read_b128 v[220:223], v154 offset:6144
	ds_read_b128 v[224:227], v154 offset:7168
	global_load_lds_dwordx4 v[196:197], off sc1
	v_lshl_add_u64 v[196:197], v[146:147], 0, s[10:11]
	s_mov_b32 m0, s65
	s_nop 0
	global_load_lds_dwordx4 v[196:197], off sc1
	s_waitcnt vmcnt(8)
	s_waitcnt lgkmcnt(0)
	s_setprio 1
	s_barrier
	v_mfma_f32_16x16x32_bf16 v[112:115], v[156:159], v[192:195], 0
	v_mfma_f32_16x16x32_bf16 v[116:119], v[164:167], v[192:195], 0
	v_mfma_f32_16x16x32_bf16 v[96:99], v[156:159], v[204:207], 0
	v_mfma_f32_16x16x32_bf16 v[100:103], v[164:167], v[204:207], 0
	v_mfma_f32_16x16x32_bf16 v[80:83], v[156:159], v[212:215], 0
	v_mfma_f32_16x16x32_bf16 v[84:87], v[164:167], v[212:215], 0
	v_mfma_f32_16x16x32_bf16 v[64:67], v[156:159], v[220:223], 0
	v_mfma_f32_16x16x32_bf16 v[68:71], v[164:167], v[220:223], 0
	v_mfma_f32_16x16x32_bf16 v[112:115], v[160:163], v[200:203], v[112:115]
	v_mfma_f32_16x16x32_bf16 v[116:119], v[168:171], v[200:203], v[116:119]
	v_mfma_f32_16x16x32_bf16 v[96:99], v[160:163], v[208:211], v[96:99]
	v_mfma_f32_16x16x32_bf16 v[100:103], v[168:171], v[208:211], v[100:103]
	v_mfma_f32_16x16x32_bf16 v[80:83], v[160:163], v[216:219], v[80:83]
	v_mfma_f32_16x16x32_bf16 v[84:87], v[168:171], v[216:219], v[84:87]
	v_mfma_f32_16x16x32_bf16 v[64:67], v[160:163], v[224:227], v[64:67]
	v_mfma_f32_16x16x32_bf16 v[68:71], v[168:171], v[224:227], v[68:71]
	v_mfma_f32_16x16x32_bf16 v[120:123], v[172:175], v[192:195], 0
	v_mfma_f32_16x16x32_bf16 v[124:127], v[180:183], v[192:195], 0
	v_mfma_f32_16x16x32_bf16 v[104:107], v[172:175], v[204:207], 0
	v_mfma_f32_16x16x32_bf16 v[108:111], v[180:183], v[204:207], 0
	v_mfma_f32_16x16x32_bf16 v[88:91], v[172:175], v[212:215], 0
	v_mfma_f32_16x16x32_bf16 v[92:95], v[180:183], v[212:215], 0
	v_mfma_f32_16x16x32_bf16 v[72:75], v[172:175], v[220:223], 0
	v_mfma_f32_16x16x32_bf16 v[76:79], v[180:183], v[220:223], 0
	v_mfma_f32_16x16x32_bf16 v[120:123], v[176:179], v[200:203], v[120:123]
	v_mfma_f32_16x16x32_bf16 v[124:127], v[184:187], v[200:203], v[124:127]
	v_mfma_f32_16x16x32_bf16 v[104:107], v[176:179], v[208:211], v[104:107]
	v_mfma_f32_16x16x32_bf16 v[108:111], v[184:187], v[208:211], v[108:111]
	v_mfma_f32_16x16x32_bf16 v[88:91], v[176:179], v[216:219], v[88:91]
	v_mfma_f32_16x16x32_bf16 v[92:95], v[184:187], v[216:219], v[92:95]
	s_setprio 2
	s_barrier
	v_mfma_f32_16x16x32_bf16 v[72:75], v[176:179], v[224:227], v[72:75]
	v_mfma_f32_16x16x32_bf16 v[76:79], v[184:187], v[224:227], v[76:79]
	s_setprio 0
	s_add_i32 s88, s50, s35
	s_mov_b32 m0, s88
	ds_read_b128 v[192:195], v154 offset:16384
	ds_read_b128 v[200:203], v154 offset:17408
	ds_read_b128 v[204:207], v154 offset:18432
	ds_read_b128 v[208:211], v154 offset:19456
	ds_read_b128 v[212:215], v154 offset:20480
	ds_read_b128 v[216:219], v154 offset:21504
	ds_read_b128 v[220:223], v154 offset:22528
	ds_read_b128 v[224:227], v154 offset:23552
	global_load_lds_dwordx4 v132, s[78:79] sc1
	s_add_i32 m0, s88, 0x2000
	s_add_u32 s88, s78, 0x4000
	s_addc_u32 s89, s79, 0
	s_add_i32 s90, s51, s35
	global_load_lds_dwordx4 v134, s[78:79] sc1
	s_mov_b32 m0, s90
	s_nop 0
	global_load_lds_dwordx4 v132, s[88:89] sc1
	s_add_i32 m0, s90, 0x2000
	s_nop 0
	global_load_lds_dwordx4 v134, s[88:89] sc1
	s_mov_b32 m0, s42
	s_nop 0
	global_load_lds_dwordx4 v128, s[80:81] sc1
	s_mov_b32 m0, s43
	s_nop 0
	global_load_lds_dwordx4 v130, s[80:81] sc1
	s_waitcnt vmcnt(8)
	s_waitcnt lgkmcnt(0)
	s_setprio 1
	s_barrier
	v_mfma_f32_16x16x32_bf16 v[48:51], v[156:159], v[192:195], 0
	v_mfma_f32_16x16x32_bf16 v[52:55], v[164:167], v[192:195], 0
	v_mfma_f32_16x16x32_bf16 v[32:35], v[156:159], v[204:207], 0
	v_mfma_f32_16x16x32_bf16 v[36:39], v[164:167], v[204:207], 0
	v_mfma_f32_16x16x32_bf16 v[16:19], v[156:159], v[212:215], 0
	v_mfma_f32_16x16x32_bf16 v[20:23], v[164:167], v[212:215], 0
	v_mfma_f32_16x16x32_bf16 v[0:3], v[156:159], v[220:223], 0
	v_mfma_f32_16x16x32_bf16 v[4:7], v[164:167], v[220:223], 0
	v_mfma_f32_16x16x32_bf16 v[48:51], v[160:163], v[200:203], v[48:51]
	v_mfma_f32_16x16x32_bf16 v[52:55], v[168:171], v[200:203], v[52:55]
	v_mfma_f32_16x16x32_bf16 v[32:35], v[160:163], v[208:211], v[32:35]
	v_mfma_f32_16x16x32_bf16 v[36:39], v[168:171], v[208:211], v[36:39]
	v_mfma_f32_16x16x32_bf16 v[16:19], v[160:163], v[216:219], v[16:19]
	v_mfma_f32_16x16x32_bf16 v[20:23], v[168:171], v[216:219], v[20:23]
	v_mfma_f32_16x16x32_bf16 v[0:3], v[160:163], v[224:227], v[0:3]
	v_mfma_f32_16x16x32_bf16 v[4:7], v[168:171], v[224:227], v[4:7]
	v_mfma_f32_16x16x32_bf16 v[56:59], v[172:175], v[192:195], 0
	v_mfma_f32_16x16x32_bf16 v[60:63], v[180:183], v[192:195], 0
	v_mfma_f32_16x16x32_bf16 v[40:43], v[172:175], v[204:207], 0
	v_mfma_f32_16x16x32_bf16 v[44:47], v[180:183], v[204:207], 0
	v_mfma_f32_16x16x32_bf16 v[24:27], v[172:175], v[212:215], 0
	v_mfma_f32_16x16x32_bf16 v[28:31], v[180:183], v[212:215], 0
	v_mfma_f32_16x16x32_bf16 v[8:11], v[172:175], v[220:223], 0
	v_mfma_f32_16x16x32_bf16 v[12:15], v[180:183], v[220:223], 0
	v_mfma_f32_16x16x32_bf16 v[56:59], v[176:179], v[200:203], v[56:59]
	v_mfma_f32_16x16x32_bf16 v[60:63], v[184:187], v[200:203], v[60:63]
	v_mfma_f32_16x16x32_bf16 v[40:43], v[176:179], v[208:211], v[40:43]
	v_mfma_f32_16x16x32_bf16 v[44:47], v[184:187], v[208:211], v[44:47]
	v_mfma_f32_16x16x32_bf16 v[24:27], v[176:179], v[216:219], v[24:27]
	v_mfma_f32_16x16x32_bf16 v[28:31], v[184:187], v[216:219], v[28:31]
	s_setprio 2
	s_barrier
	v_mfma_f32_16x16x32_bf16 v[8:11], v[176:179], v[224:227], v[8:11]
	v_mfma_f32_16x16x32_bf16 v[12:15], v[184:187], v[224:227], v[12:15]
	s_setprio 0
	v_add_u32_e32 v168, s54, v151
	v_add_u32_e32 v184, s55, v151
	ds_read_b128 v[156:159], v168
	ds_read_b128 v[160:163], v168 offset:1024
	ds_read_b128 v[164:167], v168 offset:2048
	ds_read_b128 v[168:171], v168 offset:3072
	ds_read_b128 v[172:175], v184
	ds_read_b128 v[176:179], v184 offset:1024
	ds_read_b128 v[180:183], v184 offset:2048
	ds_read_b128 v[184:187], v184 offset:3072
	s_add_u32 s80, s80, 0x4000
	s_addc_u32 s81, s81, 0
	s_mov_b32 m0, s44
	ds_read_b128 v[192:195], v154 offset:32768
	ds_read_b128 v[200:203], v154 offset:33792
	ds_read_b128 v[204:207], v154 offset:34816
	ds_read_b128 v[208:211], v154 offset:35840
	ds_read_b128 v[212:215], v154 offset:36864
	ds_read_b128 v[216:219], v154 offset:37888
	ds_read_b128 v[220:223], v154 offset:38912
	ds_read_b128 v[224:227], v154 offset:39936
	global_load_lds_dwordx4 v128, s[80:81] sc1
	s_mov_b32 m0, s45
	s_nop 0
	global_load_lds_dwordx4 v130, s[80:81] sc1
	s_waitcnt vmcnt(8)
	s_waitcnt lgkmcnt(0)
	s_setprio 1
	s_barrier
	v_mfma_f32_16x16x32_bf16 v[112:115], v[156:159], v[192:195], v[112:115]
	v_mfma_f32_16x16x32_bf16 v[116:119], v[164:167], v[192:195], v[116:119]
	v_mfma_f32_16x16x32_bf16 v[96:99], v[156:159], v[204:207], v[96:99]
	v_mfma_f32_16x16x32_bf16 v[100:103], v[164:167], v[204:207], v[100:103]
	v_mfma_f32_16x16x32_bf16 v[80:83], v[156:159], v[212:215], v[80:83]
	v_mfma_f32_16x16x32_bf16 v[84:87], v[164:167], v[212:215], v[84:87]
	v_mfma_f32_16x16x32_bf16 v[64:67], v[156:159], v[220:223], v[64:67]
	v_mfma_f32_16x16x32_bf16 v[68:71], v[164:167], v[220:223], v[68:71]
	v_mfma_f32_16x16x32_bf16 v[112:115], v[160:163], v[200:203], v[112:115]
	v_mfma_f32_16x16x32_bf16 v[116:119], v[168:171], v[200:203], v[116:119]
	v_mfma_f32_16x16x32_bf16 v[96:99], v[160:163], v[208:211], v[96:99]
	v_mfma_f32_16x16x32_bf16 v[100:103], v[168:171], v[208:211], v[100:103]
	v_mfma_f32_16x16x32_bf16 v[80:83], v[160:163], v[216:219], v[80:83]
	v_mfma_f32_16x16x32_bf16 v[84:87], v[168:171], v[216:219], v[84:87]
	v_mfma_f32_16x16x32_bf16 v[64:67], v[160:163], v[224:227], v[64:67]
	v_mfma_f32_16x16x32_bf16 v[68:71], v[168:171], v[224:227], v[68:71]
	v_mfma_f32_16x16x32_bf16 v[120:123], v[172:175], v[192:195], v[120:123]
	v_mfma_f32_16x16x32_bf16 v[124:127], v[180:183], v[192:195], v[124:127]
	v_mfma_f32_16x16x32_bf16 v[104:107], v[172:175], v[204:207], v[104:107]
	v_mfma_f32_16x16x32_bf16 v[108:111], v[180:183], v[204:207], v[108:111]
	v_mfma_f32_16x16x32_bf16 v[88:91], v[172:175], v[212:215], v[88:91]
	v_mfma_f32_16x16x32_bf16 v[92:95], v[180:183], v[212:215], v[92:95]
	v_mfma_f32_16x16x32_bf16 v[72:75], v[172:175], v[220:223], v[72:75]
	v_mfma_f32_16x16x32_bf16 v[76:79], v[180:183], v[220:223], v[76:79]
	v_mfma_f32_16x16x32_bf16 v[120:123], v[176:179], v[200:203], v[120:123]
	v_mfma_f32_16x16x32_bf16 v[124:127], v[184:187], v[200:203], v[124:127]
	v_mfma_f32_16x16x32_bf16 v[104:107], v[176:179], v[208:211], v[104:107]
	v_mfma_f32_16x16x32_bf16 v[108:111], v[184:187], v[208:211], v[108:111]
	v_mfma_f32_16x16x32_bf16 v[88:91], v[176:179], v[216:219], v[88:91]
	v_mfma_f32_16x16x32_bf16 v[92:95], v[184:187], v[216:219], v[92:95]
	s_setprio 2
	s_barrier
	v_mfma_f32_16x16x32_bf16 v[72:75], v[176:179], v[224:227], v[72:75]
	v_mfma_f32_16x16x32_bf16 v[76:79], v[184:187], v[224:227], v[76:79]
	s_setprio 0
	s_add_u32 s80, s78, 0x8000
	s_addc_u32 s81, s79, 0
	s_add_i32 s88, s54, s35
	s_mov_b32 m0, s88
	ds_read_b128 v[192:195], v154 offset:49152
	ds_read_b128 v[200:203], v154 offset:50176
	ds_read_b128 v[204:207], v154 offset:51200
	ds_read_b128 v[208:211], v154 offset:52224
	ds_read_b128 v[212:215], v154 offset:53248
	ds_read_b128 v[216:219], v154 offset:54272
	ds_read_b128 v[220:223], v154 offset:55296
	ds_read_b128 v[224:227], v154 offset:56320
	global_load_lds_dwordx4 v132, s[80:81] sc1
	s_add_i32 m0, s88, 0x2000
	s_add_u32 s78, s78, 0xc000
	global_load_lds_dwordx4 v134, s[80:81] sc1
	s_addc_u32 s79, s79, 0
	s_add_i32 s80, s55, s35
	s_mov_b32 m0, s80
	s_nop 0
	global_load_lds_dwordx4 v132, s[78:79] sc1
	s_add_i32 m0, s80, 0x2000
	s_nop 0
	global_load_lds_dwordx4 v134, s[78:79] sc1
	s_mov_b32 m0, s47
	s_nop 0
	global_load_lds_dwordx4 v128, s[70:71] sc1
	s_mov_b32 m0, s48
	s_nop 0
	global_load_lds_dwordx4 v130, s[70:71] sc1
	s_waitcnt vmcnt(8)
	s_waitcnt lgkmcnt(0)
	s_setprio 1
	s_barrier
	v_mfma_f32_16x16x32_bf16 v[48:51], v[156:159], v[192:195], v[48:51]
	v_mfma_f32_16x16x32_bf16 v[52:55], v[164:167], v[192:195], v[52:55]
	v_mfma_f32_16x16x32_bf16 v[32:35], v[156:159], v[204:207], v[32:35]
	v_mfma_f32_16x16x32_bf16 v[36:39], v[164:167], v[204:207], v[36:39]
	v_mfma_f32_16x16x32_bf16 v[16:19], v[156:159], v[212:215], v[16:19]
	v_mfma_f32_16x16x32_bf16 v[20:23], v[164:167], v[212:215], v[20:23]
	v_mfma_f32_16x16x32_bf16 v[0:3], v[156:159], v[220:223], v[0:3]
	v_mfma_f32_16x16x32_bf16 v[4:7], v[164:167], v[220:223], v[4:7]
	v_mfma_f32_16x16x32_bf16 v[48:51], v[160:163], v[200:203], v[48:51]
	v_mfma_f32_16x16x32_bf16 v[52:55], v[168:171], v[200:203], v[52:55]
	v_mfma_f32_16x16x32_bf16 v[32:35], v[160:163], v[208:211], v[32:35]
	v_mfma_f32_16x16x32_bf16 v[36:39], v[168:171], v[208:211], v[36:39]
	v_mfma_f32_16x16x32_bf16 v[16:19], v[160:163], v[216:219], v[16:19]
	v_mfma_f32_16x16x32_bf16 v[20:23], v[168:171], v[216:219], v[20:23]
	v_mfma_f32_16x16x32_bf16 v[0:3], v[160:163], v[224:227], v[0:3]
	v_mfma_f32_16x16x32_bf16 v[4:7], v[168:171], v[224:227], v[4:7]
	v_mfma_f32_16x16x32_bf16 v[56:59], v[172:175], v[192:195], v[56:59]
	v_mfma_f32_16x16x32_bf16 v[60:63], v[180:183], v[192:195], v[60:63]
	v_mfma_f32_16x16x32_bf16 v[40:43], v[172:175], v[204:207], v[40:43]
	v_mfma_f32_16x16x32_bf16 v[44:47], v[180:183], v[204:207], v[44:47]
	v_mfma_f32_16x16x32_bf16 v[24:27], v[172:175], v[212:215], v[24:27]
	v_mfma_f32_16x16x32_bf16 v[28:31], v[180:183], v[212:215], v[28:31]
	v_mfma_f32_16x16x32_bf16 v[8:11], v[172:175], v[220:223], v[8:11]
	v_mfma_f32_16x16x32_bf16 v[12:15], v[180:183], v[220:223], v[12:15]
	v_mfma_f32_16x16x32_bf16 v[56:59], v[176:179], v[200:203], v[56:59]
	v_mfma_f32_16x16x32_bf16 v[60:63], v[184:187], v[200:203], v[60:63]
	v_mfma_f32_16x16x32_bf16 v[40:43], v[176:179], v[208:211], v[40:43]
	v_mfma_f32_16x16x32_bf16 v[44:47], v[184:187], v[208:211], v[44:47]
	v_mfma_f32_16x16x32_bf16 v[24:27], v[176:179], v[216:219], v[24:27]
	v_mfma_f32_16x16x32_bf16 v[28:31], v[184:187], v[216:219], v[28:31]
	s_setprio 2
	s_barrier
	v_mfma_f32_16x16x32_bf16 v[8:11], v[176:179], v[224:227], v[8:11]
	v_mfma_f32_16x16x32_bf16 v[12:15], v[184:187], v[224:227], v[12:15]
	s_setprio 0
	s_add_i32 s87, s87, 2
	s_add_u32 s10, s10, 0x10000
	s_addc_u32 s11, s11, 0
	s_cmp_gt_u32 s87, 13

.LBB0_1087:
	s_or_b64 exec, exec, s[8:9]
	v_mov_b32_e32 v133, v188
	s_waitcnt lgkmcnt(0)
	s_barrier
	s_nop 0
	v_bfe_i32 v2, v133, 27, 1
	v_lshlrev_b32_e32 v0, 4, v133
	v_lshrrev_b32_e32 v2, 22, v2
	v_add_u32_e32 v2, v0, v2
	v_and_b32_e32 v2, 0xfffffc00, v2
	v_sub_u32_e32 v2, v0, v2
	v_ashrrev_i32_e32 v1, 31, v133
	v_lshrrev_b32_e32 v3, 4, v2
	v_lshrrev_b32_e32 v1, 26, v1
	v_bitop3_b32 v2, v3, v2, 32 bitop3:0x6c
	v_add_u32_e32 v1, v133, v1
	v_ashrrev_i32_e32 v4, 31, v2
	v_ashrrev_i32_e32 v1, 6, v1
	v_lshrrev_b32_e32 v4, 26, v4
	v_lshlrev_b32_e32 v3, 3, v1
	v_add_u32_e32 v4, v2, v4
	v_and_b32_e32 v3, -16, v3
	v_ashrrev_i32_e32 v132, 6, v4
	v_add_u32_e32 v144, v132, v3
	v_and_b32_e32 v3, 0xc0, v4
	v_lshlrev_b32_e32 v1, 5, v1
	v_sub_u32_e32 v2, v2, v3
	v_mov_b32_e32 v3, 1
	v_and_b32_e32 v1, 32, v1
	v_ashrrev_i16_sdwa v2, v3, sext(v2) dst_sel:DWORD dst_unused:UNUSED_PAD src0_sel:DWORD src1_sel:BYTE_0
	v_add_u32_sdwa v1, v1, sext(v2) dst_sel:DWORD dst_unused:UNUSED_PAD src0_sel:DWORD src1_sel:WORD_0
	v_lshrrev_b32_e32 v145, 5, v1
	v_mov_b32_e32 v1, 31
	v_add_u32_e32 v0, 0x2000, v0
	v_and_b32_sdwa v146, sext(v2), v1 dst_sel:DWORD dst_unused:UNUSED_PAD src0_sel:WORD_0 src1_sel:DWORD
	v_ashrrev_i32_e32 v2, 31, v0
	v_lshrrev_b32_e32 v2, 22, v2
	v_add_u32_e32 v2, v0, v2
	v_ashrrev_i32_e32 v2, 10, v2
	v_mul_i32_i24_e32 v4, 0x400, v2
	v_sub_u32_e32 v0, v0, v4
	v_lshrrev_b32_e32 v4, 4, v0
	v_bitop3_b32 v0, v4, v0, 32 bitop3:0x6c
	v_ashrrev_i32_e32 v5, 31, v0
	v_lshrrev_b32_e32 v5, 26, v5
	v_lshlrev_b32_e32 v4, 3, v2
	v_add_u32_e32 v5, v0, v5
	v_and_b32_e32 v4, -16, v4
	v_ashrrev_i32_e32 v134, 6, v5
	v_add_u32_e32 v147, v134, v4
	v_and_b32_e32 v4, 0xc0, v5
	v_lshlrev_b32_e32 v2, 5, v2
	v_sub_u32_e32 v0, v0, v4
	v_and_b32_e32 v2, 32, v2
	v_ashrrev_i16_sdwa v0, v3, sext(v0) dst_sel:DWORD dst_unused:UNUSED_PAD src0_sel:DWORD src1_sel:BYTE_0
	v_add_u32_sdwa v2, v2, sext(v0) dst_sel:DWORD dst_unused:UNUSED_PAD src0_sel:DWORD src1_sel:WORD_0
	v_lshrrev_b32_e32 v155, 5, v2
	v_and_b32_sdwa v154, sext(v0), v1 dst_sel:DWORD dst_unused:UNUSED_PAD src0_sel:WORD_0 src1_sel:DWORD
	v_and_b32_e32 v0, 0x1fffffe, v147
	v_lshlrev_b32_e32 v1, 5, v147
	v_add_lshl_u32 v0, v155, v0, 6
	v_and_b32_e32 v156, 32, v1
	v_readfirstlane_b32 s18, v133
	v_or3_b32 v0, v0, v156, v154
	s_ashr_i32 s7, s18, 6
	v_lshlrev_b32_e32 v128, 1, v0
	v_and_b32_e32 v0, 0x1fffffe, v144
	v_lshlrev_b32_e32 v1, 5, v144
	s_lshl_b32 s36, s7, 10
	v_add_lshl_u32 v0, v145, v0, 6
	v_and_b32_e32 v157, 32, v1
	v_or3_b32 v0, v0, v157, v146
	s_add_i32 s37, s36, 0x100
	v_lshlrev_b32_e32 v130, 1, v0
	s_mov_b32 m0, s37
	s_add_i32 s42, s37, 0x2000
	global_load_lds_dwordx4 v130, s[0:1] sc1
	s_mov_b32 m0, s42
	s_add_i32 s43, s37, 0x4000
	v_readlane_b32 s8, v252, 17
	global_load_lds_dwordx4 v128, s[0:1] sc1
	s_mov_b32 m0, s43
	v_readlane_b32 s9, v252, 18
	s_add_i32 s44, s37, 0x6000
	s_ashr_i32 s10, s18, 8
	v_mov_b32_e32 v131, 0
	s_cmp_eq_u32 s10, 1
	v_mov_b32_e32 v129, v131
	global_load_lds_dwordx4 v130, s[8:9] sc1
	s_mov_b32 m0, s44
	s_nop 0
	global_load_lds_dwordx4 v128, s[8:9] sc1
	s_cselect_b64 s[8:9], -1, 0
	s_cmp_lg_u32 s10, 1
	s_cbranch_scc1 .LBB0_1089
	s_barrier

.LBB0_1092:
	s_mov_b32 s54, s35
	s_add_i32 s35, s35, 1
	s_cmp_lt_u32 s35, s12
	s_mov_b64 s[40:41], s[16:17]
	s_mov_b32 s16, s61
	s_cselect_b64 s[56:57], -1, 0
	s_add_i32 s61, s35, s6
	s_mov_b64 s[18:19], s[0:1]
	s_and_b64 s[0:1], s[56:57], exec
	s_cselect_b32 s0, s58, s58
	s_cselect_b32 s16, s61, s16
	s_ashr_i32 s1, s0, 31
	s_lshl_b64 s[0:1], s[0:1], 19
	s_add_u32 s0, s60, s0
	s_addc_u32 s1, s33, s1
	s_and_b64 s[62:63], s[56:57], exec
	s_cselect_b32 s55, s1, s19
	s_cselect_b32 s69, s0, s18
	s_ashr_i32 s17, s16, 31
	s_lshl_b64 s[16:17], s[16:17], 19
	s_add_u32 s16, s66, s16
	s_addc_u32 s17, s67, s17
	s_and_b64 s[56:57], s[56:57], exec
	s_cselect_b32 s70, s17, s41
	s_cselect_b32 s71, s16, s40
	s_add_u32 s76, s40, 0x10000
	s_addc_u32 s77, s41, 0
	s_mov_b32 s78, -2
	v_add_u32_e32 v155, s47, v148
	ds_read_b128 v[156:159], v155
	ds_read_b128 v[160:163], v155 offset:1024
	ds_read_b128 v[164:167], v155 offset:2048
	ds_read_b128 v[168:171], v155 offset:3072
	v_add_u32_e32 v155, s48, v148
	ds_read_b128 v[172:175], v155
	ds_read_b128 v[176:179], v155 offset:1024
	ds_read_b128 v[180:183], v155 offset:2048
	ds_read_b128 v[184:187], v155 offset:3072
	s_add_u32 s40, s18, 0x10000
	s_addc_u32 s41, s19, 0
	s_cmp_eq_u32 s78, 12
	s_cselect_b32 s64, s69, s40
	s_cselect_b32 s65, s55, s41
	s_cselect_b32 s62, s71, s76
	s_cselect_b32 s63, s70, s77
	s_add_u32 s56, s64, 0x8000
	s_addc_u32 s57, s65, 0
	s_add_i32 m0, s37, 0xc000
	ds_read_b128 v[192:195], v154
	ds_read_b128 v[200:203], v154 offset:1024
	ds_read_b128 v[204:207], v154 offset:2048
	ds_read_b128 v[208:211], v154 offset:3072
	ds_read_b128 v[212:215], v154 offset:4096
	ds_read_b128 v[216:219], v154 offset:5120
	ds_read_b128 v[220:223], v154 offset:6144
	ds_read_b128 v[224:227], v154 offset:7168
	global_load_lds_dwordx4 v144, s[18:19] sc1
	s_add_i32 m0, s37, 0xe000
	s_nop 0
	global_load_lds_dwordx4 v146, s[18:19] sc1
	s_waitcnt vmcnt(8)
	s_waitcnt lgkmcnt(0)
	s_setprio 1
	s_barrier
	v_mfma_f32_16x16x32_bf16 v[116:119], v[156:159], v[192:195], 0
	v_mfma_f32_16x16x32_bf16 v[108:111], v[164:167], v[192:195], 0
	v_mfma_f32_16x16x32_bf16 v[100:103], v[156:159], v[204:207], 0
	v_mfma_f32_16x16x32_bf16 v[92:95], v[164:167], v[204:207], 0
	v_mfma_f32_16x16x32_bf16 v[84:87], v[156:159], v[212:215], 0
	v_mfma_f32_16x16x32_bf16 v[76:79], v[164:167], v[212:215], 0
	v_mfma_f32_16x16x32_bf16 v[60:63], v[156:159], v[220:223], 0
	v_mfma_f32_16x16x32_bf16 v[52:55], v[164:167], v[220:223], 0
	v_mfma_f32_16x16x32_bf16 v[116:119], v[160:163], v[200:203], v[116:119]
	v_mfma_f32_16x16x32_bf16 v[108:111], v[168:171], v[200:203], v[108:111]
	v_mfma_f32_16x16x32_bf16 v[100:103], v[160:163], v[208:211], v[100:103]
	v_mfma_f32_16x16x32_bf16 v[92:95], v[168:171], v[208:211], v[92:95]
	v_mfma_f32_16x16x32_bf16 v[84:87], v[160:163], v[216:219], v[84:87]
	v_mfma_f32_16x16x32_bf16 v[76:79], v[168:171], v[216:219], v[76:79]
	v_mfma_f32_16x16x32_bf16 v[60:63], v[160:163], v[224:227], v[60:63]
	v_mfma_f32_16x16x32_bf16 v[52:55], v[168:171], v[224:227], v[52:55]
	v_mfma_f32_16x16x32_bf16 v[124:127], v[172:175], v[192:195], 0
	v_mfma_f32_16x16x32_bf16 v[120:123], v[180:183], v[192:195], 0
	v_mfma_f32_16x16x32_bf16 v[112:115], v[172:175], v[204:207], 0
	v_mfma_f32_16x16x32_bf16 v[104:107], v[180:183], v[204:207], 0
	v_mfma_f32_16x16x32_bf16 v[96:99], v[172:175], v[212:215], 0
	v_mfma_f32_16x16x32_bf16 v[88:91], v[180:183], v[212:215], 0
	v_mfma_f32_16x16x32_bf16 v[80:83], v[172:175], v[220:223], 0
	v_mfma_f32_16x16x32_bf16 v[68:71], v[180:183], v[220:223], 0
	v_mfma_f32_16x16x32_bf16 v[124:127], v[176:179], v[200:203], v[124:127]
	v_mfma_f32_16x16x32_bf16 v[120:123], v[184:187], v[200:203], v[120:123]
	v_mfma_f32_16x16x32_bf16 v[112:115], v[176:179], v[208:211], v[112:115]
	v_mfma_f32_16x16x32_bf16 v[104:107], v[184:187], v[208:211], v[104:107]
	v_mfma_f32_16x16x32_bf16 v[96:99], v[176:179], v[216:219], v[96:99]
	v_mfma_f32_16x16x32_bf16 v[88:91], v[184:187], v[216:219], v[88:91]
	s_setprio 2
	s_barrier
	v_mfma_f32_16x16x32_bf16 v[80:83], v[176:179], v[224:227], v[80:83]
	v_mfma_f32_16x16x32_bf16 v[68:71], v[184:187], v[224:227], v[68:71]
	s_setprio 0
	s_add_i32 s18, s47, s36
	s_mov_b32 m0, s18
	ds_read_b128 v[192:195], v154 offset:16384
	ds_read_b128 v[200:203], v154 offset:17408
	ds_read_b128 v[204:207], v154 offset:18432
	ds_read_b128 v[208:211], v154 offset:19456
	ds_read_b128 v[212:215], v154 offset:20480
	ds_read_b128 v[216:219], v154 offset:21504
	ds_read_b128 v[220:223], v154 offset:22528
	ds_read_b128 v[224:227], v154 offset:23552
	global_load_lds_dwordx4 v132, s[62:63] sc1
	s_add_i32 m0, s18, 0x2000
	s_add_u32 s18, s62, 0x4000
	s_addc_u32 s19, s63, 0
	s_add_i32 s79, s48, s36
	global_load_lds_dwordx4 v134, s[62:63] sc1
	s_mov_b32 m0, s79
	s_nop 0
	global_load_lds_dwordx4 v132, s[18:19] sc1
	s_add_i32 m0, s79, 0x2000
	s_nop 0
	global_load_lds_dwordx4 v134, s[18:19] sc1
	s_mov_b32 m0, s37
	s_nop 0
	global_load_lds_dwordx4 v130, s[64:65] sc1
	s_mov_b32 m0, s42
	s_nop 0
	global_load_lds_dwordx4 v128, s[64:65] sc1
	s_waitcnt vmcnt(8)
	s_waitcnt lgkmcnt(0)
	s_setprio 1
	s_barrier
	v_mfma_f32_16x16x32_bf16 v[56:59], v[156:159], v[192:195], 0
	v_mfma_f32_16x16x32_bf16 v[44:47], v[164:167], v[192:195], 0
	v_mfma_f32_16x16x32_bf16 v[36:39], v[156:159], v[204:207], 0
	v_mfma_f32_16x16x32_bf16 v[28:31], v[164:167], v[204:207], 0
	v_mfma_f32_16x16x32_bf16 v[20:23], v[156:159], v[212:215], 0
	v_mfma_f32_16x16x32_bf16 v[12:15], v[164:167], v[212:215], 0
	v_mfma_f32_16x16x32_bf16 v[4:7], v[156:159], v[220:223], 0
	v_mfma_f32_16x16x32_bf16 v[0:3], v[164:167], v[220:223], 0
	v_mfma_f32_16x16x32_bf16 v[56:59], v[160:163], v[200:203], v[56:59]
	v_mfma_f32_16x16x32_bf16 v[44:47], v[168:171], v[200:203], v[44:47]
	v_mfma_f32_16x16x32_bf16 v[36:39], v[160:163], v[208:211], v[36:39]
	v_mfma_f32_16x16x32_bf16 v[28:31], v[168:171], v[208:211], v[28:31]
	v_mfma_f32_16x16x32_bf16 v[20:23], v[160:163], v[216:219], v[20:23]
	v_mfma_f32_16x16x32_bf16 v[12:15], v[168:171], v[216:219], v[12:15]
	v_mfma_f32_16x16x32_bf16 v[4:7], v[160:163], v[224:227], v[4:7]
	v_mfma_f32_16x16x32_bf16 v[0:3], v[168:171], v[224:227], v[0:3]
	v_mfma_f32_16x16x32_bf16 v[72:75], v[172:175], v[192:195], 0
	v_mfma_f32_16x16x32_bf16 v[64:67], v[180:183], v[192:195], 0
	v_mfma_f32_16x16x32_bf16 v[48:51], v[172:175], v[204:207], 0
	v_mfma_f32_16x16x32_bf16 v[40:43], v[180:183], v[204:207], 0
	v_mfma_f32_16x16x32_bf16 v[32:35], v[172:175], v[212:215], 0
	v_mfma_f32_16x16x32_bf16 v[24:27], v[180:183], v[212:215], 0
	v_mfma_f32_16x16x32_bf16 v[16:19], v[172:175], v[220:223], 0
	v_mfma_f32_16x16x32_bf16 v[8:11], v[180:183], v[220:223], 0
	v_mfma_f32_16x16x32_bf16 v[72:75], v[176:179], v[200:203], v[72:75]
	v_mfma_f32_16x16x32_bf16 v[64:67], v[184:187], v[200:203], v[64:67]
	v_mfma_f32_16x16x32_bf16 v[48:51], v[176:179], v[208:211], v[48:51]
	v_mfma_f32_16x16x32_bf16 v[40:43], v[184:187], v[208:211], v[40:43]
	v_mfma_f32_16x16x32_bf16 v[32:35], v[176:179], v[216:219], v[32:35]
	v_mfma_f32_16x16x32_bf16 v[24:27], v[184:187], v[216:219], v[24:27]
	s_setprio 2
	s_barrier
	v_mfma_f32_16x16x32_bf16 v[16:19], v[176:179], v[224:227], v[16:19]
	v_mfma_f32_16x16x32_bf16 v[8:11], v[184:187], v[224:227], v[8:11]
	s_setprio 0
	v_add_u32_e32 v155, s49, v148
	ds_read_b128 v[156:159], v155
	ds_read_b128 v[160:163], v155 offset:1024
	ds_read_b128 v[164:167], v155 offset:2048
	ds_read_b128 v[168:171], v155 offset:3072
	v_add_u32_e32 v155, s50, v148
	ds_read_b128 v[172:175], v155
	ds_read_b128 v[176:179], v155 offset:1024
	ds_read_b128 v[180:183], v155 offset:2048
	ds_read_b128 v[184:187], v155 offset:3072
	s_add_u32 s18, s64, 0x4000
	s_addc_u32 s19, s65, 0
	s_mov_b32 m0, s43
	ds_read_b128 v[192:195], v154 offset:32768
	ds_read_b128 v[200:203], v154 offset:33792
	ds_read_b128 v[204:207], v154 offset:34816
	ds_read_b128 v[208:211], v154 offset:35840
	ds_read_b128 v[212:215], v154 offset:36864
	ds_read_b128 v[216:219], v154 offset:37888
	ds_read_b128 v[220:223], v154 offset:38912
	ds_read_b128 v[224:227], v154 offset:39936
	global_load_lds_dwordx4 v130, s[18:19] sc1
	s_mov_b32 m0, s44
	s_nop 0
	global_load_lds_dwordx4 v128, s[18:19] sc1
	s_waitcnt vmcnt(8)
	s_waitcnt lgkmcnt(0)
	s_setprio 1
	s_barrier
	v_mfma_f32_16x16x32_bf16 v[116:119], v[156:159], v[192:195], v[116:119]
	v_mfma_f32_16x16x32_bf16 v[108:111], v[164:167], v[192:195], v[108:111]
	v_mfma_f32_16x16x32_bf16 v[100:103], v[156:159], v[204:207], v[100:103]
	v_mfma_f32_16x16x32_bf16 v[92:95], v[164:167], v[204:207], v[92:95]
	v_mfma_f32_16x16x32_bf16 v[84:87], v[156:159], v[212:215], v[84:87]
	v_mfma_f32_16x16x32_bf16 v[76:79], v[164:167], v[212:215], v[76:79]
	v_mfma_f32_16x16x32_bf16 v[60:63], v[156:159], v[220:223], v[60:63]
	v_mfma_f32_16x16x32_bf16 v[52:55], v[164:167], v[220:223], v[52:55]
	v_mfma_f32_16x16x32_bf16 v[116:119], v[160:163], v[200:203], v[116:119]
	v_mfma_f32_16x16x32_bf16 v[108:111], v[168:171], v[200:203], v[108:111]
	v_mfma_f32_16x16x32_bf16 v[100:103], v[160:163], v[208:211], v[100:103]
	v_mfma_f32_16x16x32_bf16 v[92:95], v[168:171], v[208:211], v[92:95]
	v_mfma_f32_16x16x32_bf16 v[84:87], v[160:163], v[216:219], v[84:87]
	v_mfma_f32_16x16x32_bf16 v[76:79], v[168:171], v[216:219], v[76:79]
	v_mfma_f32_16x16x32_bf16 v[60:63], v[160:163], v[224:227], v[60:63]
	v_mfma_f32_16x16x32_bf16 v[52:55], v[168:171], v[224:227], v[52:55]
	v_mfma_f32_16x16x32_bf16 v[124:127], v[172:175], v[192:195], v[124:127]
	v_mfma_f32_16x16x32_bf16 v[120:123], v[180:183], v[192:195], v[120:123]
	v_mfma_f32_16x16x32_bf16 v[112:115], v[172:175], v[204:207], v[112:115]
	v_mfma_f32_16x16x32_bf16 v[104:107], v[180:183], v[204:207], v[104:107]
	v_mfma_f32_16x16x32_bf16 v[96:99], v[172:175], v[212:215], v[96:99]
	v_mfma_f32_16x16x32_bf16 v[88:91], v[180:183], v[212:215], v[88:91]
	v_mfma_f32_16x16x32_bf16 v[80:83], v[172:175], v[220:223], v[80:83]
	v_mfma_f32_16x16x32_bf16 v[68:71], v[180:183], v[220:223], v[68:71]
	v_mfma_f32_16x16x32_bf16 v[124:127], v[176:179], v[200:203], v[124:127]
	v_mfma_f32_16x16x32_bf16 v[120:123], v[184:187], v[200:203], v[120:123]
	v_mfma_f32_16x16x32_bf16 v[112:115], v[176:179], v[208:211], v[112:115]
	v_mfma_f32_16x16x32_bf16 v[104:107], v[184:187], v[208:211], v[104:107]
	v_mfma_f32_16x16x32_bf16 v[96:99], v[176:179], v[216:219], v[96:99]
	v_mfma_f32_16x16x32_bf16 v[88:91], v[184:187], v[216:219], v[88:91]
	s_setprio 2
	s_barrier
	v_mfma_f32_16x16x32_bf16 v[80:83], v[176:179], v[224:227], v[80:83]
	v_mfma_f32_16x16x32_bf16 v[68:71], v[184:187], v[224:227], v[68:71]
	s_setprio 0
	s_add_u32 s18, s62, 0x8000
	s_addc_u32 s19, s63, 0
	s_add_i32 s64, s49, s36
	s_mov_b32 m0, s64
	ds_read_b128 v[192:195], v154 offset:49152
	ds_read_b128 v[200:203], v154 offset:50176
	ds_read_b128 v[204:207], v154 offset:51200
	ds_read_b128 v[208:211], v154 offset:52224
	ds_read_b128 v[212:215], v154 offset:53248
	ds_read_b128 v[216:219], v154 offset:54272
	ds_read_b128 v[220:223], v154 offset:55296
	ds_read_b128 v[224:227], v154 offset:56320
	global_load_lds_dwordx4 v132, s[18:19] sc1
	s_add_i32 m0, s64, 0x2000
	s_nop 0
	global_load_lds_dwordx4 v134, s[18:19] sc1
	s_add_u32 s18, s62, 0xc000
	s_addc_u32 s19, s63, 0
	s_add_i32 s62, s50, s36
	s_mov_b32 m0, s62
	s_nop 0
	global_load_lds_dwordx4 v132, s[18:19] sc1
	s_add_i32 m0, s62, 0x2000
	s_nop 0
	global_load_lds_dwordx4 v134, s[18:19] sc1
	s_mov_b32 m0, s7
	s_nop 0
	global_load_lds_dwordx4 v130, s[56:57] sc1
	s_mov_b32 m0, s45
	s_nop 0
	global_load_lds_dwordx4 v128, s[56:57] sc1
	s_waitcnt vmcnt(8)
	s_waitcnt lgkmcnt(0)
	s_setprio 1
	s_barrier
	v_mfma_f32_16x16x32_bf16 v[56:59], v[156:159], v[192:195], v[56:59]
	v_mfma_f32_16x16x32_bf16 v[44:47], v[164:167], v[192:195], v[44:47]
	v_mfma_f32_16x16x32_bf16 v[36:39], v[156:159], v[204:207], v[36:39]
	v_mfma_f32_16x16x32_bf16 v[28:31], v[164:167], v[204:207], v[28:31]
	v_mfma_f32_16x16x32_bf16 v[20:23], v[156:159], v[212:215], v[20:23]
	v_mfma_f32_16x16x32_bf16 v[12:15], v[164:167], v[212:215], v[12:15]
	v_mfma_f32_16x16x32_bf16 v[4:7], v[156:159], v[220:223], v[4:7]
	v_mfma_f32_16x16x32_bf16 v[0:3], v[164:167], v[220:223], v[0:3]
	v_mfma_f32_16x16x32_bf16 v[56:59], v[160:163], v[200:203], v[56:59]
	v_mfma_f32_16x16x32_bf16 v[44:47], v[168:171], v[200:203], v[44:47]
	v_mfma_f32_16x16x32_bf16 v[36:39], v[160:163], v[208:211], v[36:39]
	v_mfma_f32_16x16x32_bf16 v[28:31], v[168:171], v[208:211], v[28:31]
	v_mfma_f32_16x16x32_bf16 v[20:23], v[160:163], v[216:219], v[20:23]
	v_mfma_f32_16x16x32_bf16 v[12:15], v[168:171], v[216:219], v[12:15]
	v_mfma_f32_16x16x32_bf16 v[4:7], v[160:163], v[224:227], v[4:7]
	v_mfma_f32_16x16x32_bf16 v[0:3], v[168:171], v[224:227], v[0:3]
	v_mfma_f32_16x16x32_bf16 v[72:75], v[172:175], v[192:195], v[72:75]
	v_mfma_f32_16x16x32_bf16 v[64:67], v[180:183], v[192:195], v[64:67]
	v_mfma_f32_16x16x32_bf16 v[48:51], v[172:175], v[204:207], v[48:51]
	v_mfma_f32_16x16x32_bf16 v[40:43], v[180:183], v[204:207], v[40:43]
	v_mfma_f32_16x16x32_bf16 v[32:35], v[172:175], v[212:215], v[32:35]
	v_mfma_f32_16x16x32_bf16 v[24:27], v[180:183], v[212:215], v[24:27]
	v_mfma_f32_16x16x32_bf16 v[16:19], v[172:175], v[220:223], v[16:19]
	v_mfma_f32_16x16x32_bf16 v[8:11], v[180:183], v[220:223], v[8:11]
	v_mfma_f32_16x16x32_bf16 v[72:75], v[176:179], v[200:203], v[72:75]
	v_mfma_f32_16x16x32_bf16 v[64:67], v[184:187], v[200:203], v[64:67]
	v_mfma_f32_16x16x32_bf16 v[48:51], v[176:179], v[208:211], v[48:51]
	v_mfma_f32_16x16x32_bf16 v[40:43], v[184:187], v[208:211], v[40:43]
	v_mfma_f32_16x16x32_bf16 v[32:35], v[176:179], v[216:219], v[32:35]
	v_mfma_f32_16x16x32_bf16 v[24:27], v[184:187], v[216:219], v[24:27]
	s_setprio 2
	s_barrier
	v_mfma_f32_16x16x32_bf16 v[16:19], v[176:179], v[224:227], v[16:19]
	v_mfma_f32_16x16x32_bf16 v[8:11], v[184:187], v[224:227], v[8:11]
	s_setprio 0
	s_add_i32 s78, s78, 2
	s_add_u32 s76, s76, 0x10000
	s_addc_u32 s77, s77, 0
	s_cmp_gt_u32 s78, 13
	s_mov_b64 s[18:19], s[40:41]

.LBB0_1096:
	v_lshl_add_u32 v155, s54, 10, v153
	ds_read_b32 v157, v155
	s_add_i32 s18, s54, s6
	s_lshl_b32 s18, s18, 15
	s_or_b32 s18, s18, s51
	s_and_b32 s18, s18, 0xffffc000
	s_waitcnt lgkmcnt(0)
	v_mul_f32_e32 v156, 0xbfb8aa3b, v157
	v_mul_f32_e32 v157, v157, v157
	v_rcp_f32_e32 v157, v157
	s_add_i32 s19, s18, s46
	s_cmp_eq_u32 s54, s59
	v_pk_mul_f32 v[158:159], v[118:119], v[156:157] op_sel_hi:[1,0]
	v_pk_mul_f32 v[160:161], v[116:117], v[156:157] op_sel_hi:[1,0]
	v_exp_f32_e32 v159, v159
	v_exp_f32_e32 v160, v160
	v_exp_f32_e32 v161, v161
	v_exp_f32_e32 v162, v158
	v_fma_f32 v159, v159, v157, v157
	v_fma_f32 v158, v160, v157, v157
	v_fma_f32 v163, v161, v157, v157
	v_pk_mul_f32 v[118:119], v[118:119], v[126:127]
	v_pk_mul_f32 v[116:117], v[116:117], v[124:125]
	v_pk_mul_f32 v[124:125], v[110:111], v[156:157] op_sel_hi:[1,0]
	v_pk_mul_f32 v[126:127], v[108:109], v[156:157] op_sel_hi:[1,0]
	v_rcp_f32_e32 v158, v158
	v_rcp_f32_e32 v161, v159
	v_rcp_f32_e32 v159, v163
	v_exp_f32_e32 v126, v126
	v_exp_f32_e32 v127, v127
	v_exp_f32_e32 v156, v124
	v_exp_f32_e32 v125, v125
	v_fma_f32 v160, v162, v157, v157
	v_pk_mul_f32 v[116:117], v[116:117], v[158:159]
	v_fma_f32 v124, v126, v157, v157
	v_fma_f32 v158, v127, v157, v157
	v_fma_f32 v126, v156, v157, v157
	v_fmac_f32_e32 v157, v125, v157
	v_rcp_f32_e32 v160, v160
	v_rcp_f32_e32 v124, v124
	v_rcp_f32_e32 v126, v126
	v_rcp_f32_e32 v127, v157
	v_rcp_f32_e32 v125, v158
	v_pk_mul_f32 v[110:111], v[110:111], v[122:123]
	v_pk_mul_f32 v[108:109], v[108:109], v[120:121]
	v_pk_mul_f32 v[118:119], v[118:119], v[160:161]
	v_pk_mul_f32 v[120:121], v[110:111], v[126:127]
	v_pk_mul_f32 v[122:123], v[108:109], v[124:125]
	s_nop 0
	s_nop 0
	v_cvt_pk_bf16_f32 v108, v116, v117
	v_cvt_pk_bf16_f32 v109, v118, v119
	v_cvt_pk_bf16_f32 v110, v122, v123
	v_cvt_pk_bf16_f32 v111, v120, v121
	ds_read_b32 v116, v155 offset:64
	v_or_b32_e32 v117, s19, v137
	v_lshlrev_b32_e32 v117, 1, v117
	buffer_store_dwordx4 v[108:111], v117, s[72:75], 0 offen sc1
	s_waitcnt lgkmcnt(0)
	s_nop 0
	v_mul_f32_e32 v108, 0xbfb8aa3b, v116
	v_mul_f32_e32 v109, v116, v116
	v_pk_mul_f32 v[116:117], v[100:101], v[108:109] op_sel_hi:[1,0]
	v_rcp_f32_e32 v118, v109
	v_pk_mul_f32 v[110:111], v[102:103], v[108:109] op_sel_hi:[1,0]
	v_exp_f32_e32 v109, v116
	v_exp_f32_e32 v116, v117
	v_exp_f32_e32 v111, v111
	v_exp_f32_e32 v117, v110
	v_fma_f32 v109, v109, v118, v118
	v_rcp_f32_e32 v110, v109
	v_fma_f32 v109, v116, v118, v118
	v_fma_f32 v111, v111, v118, v118
	v_fma_f32 v116, v117, v118, v118
	v_rcp_f32_e32 v117, v111
	v_rcp_f32_e32 v111, v109
	v_pk_mul_f32 v[100:101], v[100:101], v[112:113]
	v_rcp_f32_e32 v116, v116
	v_pk_mul_f32 v[102:103], v[102:103], v[114:115]
	v_pk_mul_f32 v[100:101], v[100:101], v[110:111]
	v_pk_mul_f32 v[110:111], v[94:95], v[108:109] op_sel_hi:[1,0]
	v_pk_mul_f32 v[108:109], v[92:93], v[108:109] op_sel_hi:[1,0]
	v_exp_f32_e32 v110, v110
	v_exp_f32_e32 v108, v108
	v_exp_f32_e32 v109, v109
	v_exp_f32_e32 v111, v111
	v_fma_f32 v110, v110, v118, v118
	v_fma_f32 v108, v108, v118, v118
	v_fma_f32 v109, v109, v118, v118
	v_fmac_f32_e32 v118, v111, v118
	v_rcp_f32_e32 v108, v108
	v_rcp_f32_e32 v110, v110
	v_rcp_f32_e32 v111, v118
	v_rcp_f32_e32 v109, v109
	v_pk_mul_f32 v[94:95], v[94:95], v[106:107]
	v_pk_mul_f32 v[92:93], v[92:93], v[104:105]
	v_pk_mul_f32 v[102:103], v[102:103], v[116:117]
	v_pk_mul_f32 v[104:105], v[94:95], v[110:111]
	v_pk_mul_f32 v[106:107], v[92:93], v[108:109]
	s_nop 0
	s_nop 0
	v_cvt_pk_bf16_f32 v92, v100, v101
	v_cvt_pk_bf16_f32 v93, v102, v103
	v_cvt_pk_bf16_f32 v94, v106, v107
	v_cvt_pk_bf16_f32 v95, v104, v105
	ds_read_b32 v100, v155 offset:128
	v_or_b32_e32 v101, s19, v139
	v_lshlrev_b32_e32 v101, 1, v101
	buffer_store_dwordx4 v[92:95], v101, s[72:75], 0 offen sc1
	s_waitcnt lgkmcnt(0)
	s_nop 0
	v_mul_f32_e32 v92, 0xbfb8aa3b, v100
	v_mul_f32_e32 v93, v100, v100
	v_pk_mul_f32 v[100:101], v[84:85], v[92:93] op_sel_hi:[1,0]
	v_rcp_f32_e32 v102, v93
	v_pk_mul_f32 v[94:95], v[86:87], v[92:93] op_sel_hi:[1,0]
	v_exp_f32_e32 v93, v100
	v_exp_f32_e32 v100, v101
	v_exp_f32_e32 v95, v95
	v_exp_f32_e32 v101, v94
	v_fma_f32 v93, v93, v102, v102
	v_rcp_f32_e32 v94, v93
	v_fma_f32 v93, v100, v102, v102
	v_fma_f32 v95, v95, v102, v102
	v_fma_f32 v100, v101, v102, v102
	v_rcp_f32_e32 v101, v95
	v_rcp_f32_e32 v95, v93
	v_pk_mul_f32 v[84:85], v[84:85], v[96:97]
	v_rcp_f32_e32 v100, v100
	v_pk_mul_f32 v[86:87], v[86:87], v[98:99]
	v_pk_mul_f32 v[84:85], v[84:85], v[94:95]
	v_pk_mul_f32 v[94:95], v[78:79], v[92:93] op_sel_hi:[1,0]
	v_pk_mul_f32 v[92:93], v[76:77], v[92:93] op_sel_hi:[1,0]
	v_exp_f32_e32 v94, v94
	v_exp_f32_e32 v92, v92
	v_exp_f32_e32 v93, v93
	v_exp_f32_e32 v95, v95
	v_fma_f32 v94, v94, v102, v102
	v_fma_f32 v92, v92, v102, v102
	v_fma_f32 v93, v93, v102, v102
	v_fmac_f32_e32 v102, v95, v102
	v_rcp_f32_e32 v92, v92
	v_rcp_f32_e32 v94, v94
	v_rcp_f32_e32 v95, v102
	v_rcp_f32_e32 v93, v93
	v_pk_mul_f32 v[78:79], v[78:79], v[90:91]
	v_pk_mul_f32 v[76:77], v[76:77], v[88:89]
	v_pk_mul_f32 v[86:87], v[86:87], v[100:101]
	v_pk_mul_f32 v[88:89], v[78:79], v[94:95]
	v_pk_mul_f32 v[90:91], v[76:77], v[92:93]
	s_nop 0
	s_nop 0
	v_cvt_pk_bf16_f32 v76, v84, v85
	v_cvt_pk_bf16_f32 v77, v86, v87
	v_cvt_pk_bf16_f32 v78, v90, v91
	v_cvt_pk_bf16_f32 v79, v88, v89
	ds_read_b32 v84, v155 offset:192
	v_or_b32_e32 v85, s19, v141
	v_lshlrev_b32_e32 v85, 1, v85
	buffer_store_dwordx4 v[76:79], v85, s[72:75], 0 offen sc1
	s_waitcnt lgkmcnt(0)
	s_nop 0
	v_mul_f32_e32 v76, 0xbfb8aa3b, v84
	v_mul_f32_e32 v77, v84, v84
	v_pk_mul_f32 v[84:85], v[60:61], v[76:77] op_sel_hi:[1,0]
	v_rcp_f32_e32 v86, v77
	v_pk_mul_f32 v[78:79], v[62:63], v[76:77] op_sel_hi:[1,0]
	v_exp_f32_e32 v77, v84
	v_exp_f32_e32 v84, v85
	v_exp_f32_e32 v79, v79
	v_exp_f32_e32 v85, v78
	v_fma_f32 v77, v77, v86, v86
	v_rcp_f32_e32 v78, v77
	v_fma_f32 v77, v84, v86, v86
	v_fma_f32 v79, v79, v86, v86
	v_fma_f32 v84, v85, v86, v86
	v_rcp_f32_e32 v85, v79
	v_rcp_f32_e32 v79, v77
	v_pk_mul_f32 v[60:61], v[60:61], v[80:81]
	v_rcp_f32_e32 v84, v84
	v_pk_mul_f32 v[62:63], v[62:63], v[82:83]
	v_pk_mul_f32 v[60:61], v[60:61], v[78:79]
	v_pk_mul_f32 v[78:79], v[54:55], v[76:77] op_sel_hi:[1,0]
	v_pk_mul_f32 v[76:77], v[52:53], v[76:77] op_sel_hi:[1,0]
	v_exp_f32_e32 v78, v78
	v_exp_f32_e32 v76, v76
	v_exp_f32_e32 v77, v77
	v_exp_f32_e32 v79, v79
	v_fma_f32 v78, v78, v86, v86
	v_fma_f32 v76, v76, v86, v86
	v_fma_f32 v77, v77, v86, v86
	v_fmac_f32_e32 v86, v79, v86
	v_rcp_f32_e32 v76, v76
	v_rcp_f32_e32 v78, v78
	v_rcp_f32_e32 v79, v86
	v_rcp_f32_e32 v77, v77
	v_pk_mul_f32 v[54:55], v[54:55], v[70:71]
	v_pk_mul_f32 v[52:53], v[52:53], v[68:69]
	v_pk_mul_f32 v[62:63], v[62:63], v[84:85]
	v_pk_mul_f32 v[68:69], v[54:55], v[78:79]
	v_pk_mul_f32 v[70:71], v[52:53], v[76:77]
	s_nop 0
	s_nop 0
	v_cvt_pk_bf16_f32 v52, v60, v61
	v_cvt_pk_bf16_f32 v53, v62, v63
	v_cvt_pk_bf16_f32 v54, v70, v71
	v_cvt_pk_bf16_f32 v55, v68, v69
	ds_read_b32 v60, v155 offset:512
	v_or_b32_e32 v61, s19, v143
	v_lshlrev_b32_e32 v61, 1, v61
	buffer_store_dwordx4 v[52:55], v61, s[72:75], 0 offen sc1
	s_waitcnt lgkmcnt(0)
	s_nop 0
	v_mul_f32_e32 v52, 0xbfb8aa3b, v60
	v_mul_f32_e32 v53, v60, v60
	v_pk_mul_f32 v[60:61], v[56:57], v[52:53] op_sel_hi:[1,0]
	v_rcp_f32_e32 v62, v53
	v_pk_mul_f32 v[54:55], v[58:59], v[52:53] op_sel_hi:[1,0]
	v_exp_f32_e32 v53, v60
	v_exp_f32_e32 v60, v61
	v_exp_f32_e32 v55, v55
	v_exp_f32_e32 v61, v54
	v_fma_f32 v53, v53, v62, v62
	v_rcp_f32_e32 v54, v53
	v_fma_f32 v53, v60, v62, v62
	v_fma_f32 v55, v55, v62, v62
	v_fma_f32 v60, v61, v62, v62
	v_rcp_f32_e32 v61, v55
	v_rcp_f32_e32 v55, v53
	v_pk_mul_f32 v[56:57], v[56:57], v[72:73]
	v_rcp_f32_e32 v60, v60
	v_pk_mul_f32 v[58:59], v[58:59], v[74:75]
	v_pk_mul_f32 v[54:55], v[56:57], v[54:55]
	v_pk_mul_f32 v[56:57], v[46:47], v[52:53] op_sel_hi:[1,0]
	v_pk_mul_f32 v[52:53], v[44:45], v[52:53] op_sel_hi:[1,0]
	v_exp_f32_e32 v56, v56
	v_exp_f32_e32 v52, v52
	v_exp_f32_e32 v53, v53
	v_exp_f32_e32 v57, v57
	v_fma_f32 v56, v56, v62, v62
	v_fma_f32 v52, v52, v62, v62
	v_fma_f32 v53, v53, v62, v62
	v_rcp_f32_e32 v52, v52
	v_fmac_f32_e32 v62, v57, v62
	v_rcp_f32_e32 v53, v53
	v_rcp_f32_e32 v56, v56
	v_rcp_f32_e32 v57, v62
	v_pk_mul_f32 v[44:45], v[44:45], v[64:65]
	v_pk_mul_f32 v[46:47], v[46:47], v[66:67]
	v_pk_mul_f32 v[52:53], v[44:45], v[52:53]
	v_pk_mul_f32 v[58:59], v[58:59], v[60:61]
	v_pk_mul_f32 v[56:57], v[46:47], v[56:57]
	s_nop 0
	s_nop 0
	v_cvt_pk_bf16_f32 v44, v54, v55
	v_cvt_pk_bf16_f32 v45, v58, v59
	v_cvt_pk_bf16_f32 v46, v52, v53
	v_cvt_pk_bf16_f32 v47, v56, v57
	ds_read_b32 v52, v155 offset:576
	v_add_u32_e32 v53, s18, v136
	v_or_b32_e32 v53, v53, v149
	v_lshlrev_b32_e32 v53, 1, v53
	buffer_store_dwordx4 v[44:47], v53, s[72:75], 0 offen sc1
	s_waitcnt lgkmcnt(0)
	s_nop 0
	v_mul_f32_e32 v44, 0xbfb8aa3b, v52
	v_mul_f32_e32 v45, v52, v52
	v_pk_mul_f32 v[52:53], v[36:37], v[44:45] op_sel_hi:[1,0]
	v_rcp_f32_e32 v54, v45
	v_pk_mul_f32 v[46:47], v[38:39], v[44:45] op_sel_hi:[1,0]
	v_exp_f32_e32 v45, v52
	v_exp_f32_e32 v52, v53
	v_exp_f32_e32 v47, v47
	v_exp_f32_e32 v53, v46
	v_fma_f32 v45, v45, v54, v54
	v_rcp_f32_e32 v46, v45
	v_fma_f32 v45, v52, v54, v54
	v_fma_f32 v47, v47, v54, v54
	v_fma_f32 v52, v53, v54, v54
	v_rcp_f32_e32 v53, v47
	v_rcp_f32_e32 v47, v45
	v_pk_mul_f32 v[36:37], v[36:37], v[48:49]
	v_rcp_f32_e32 v52, v52
	v_pk_mul_f32 v[38:39], v[38:39], v[50:51]
	v_pk_mul_f32 v[36:37], v[36:37], v[46:47]
	v_pk_mul_f32 v[46:47], v[30:31], v[44:45] op_sel_hi:[1,0]
	v_pk_mul_f32 v[44:45], v[28:29], v[44:45] op_sel_hi:[1,0]
	v_exp_f32_e32 v46, v46
	v_exp_f32_e32 v44, v44
	v_exp_f32_e32 v45, v45
	v_exp_f32_e32 v47, v47
	v_fma_f32 v46, v46, v54, v54
	v_fma_f32 v44, v44, v54, v54
	v_fma_f32 v45, v45, v54, v54
	v_fmac_f32_e32 v54, v47, v54
	v_rcp_f32_e32 v44, v44
	v_rcp_f32_e32 v46, v46
	v_rcp_f32_e32 v47, v54
	v_rcp_f32_e32 v45, v45
	v_pk_mul_f32 v[30:31], v[30:31], v[42:43]
	v_pk_mul_f32 v[28:29], v[28:29], v[40:41]
	v_pk_mul_f32 v[38:39], v[38:39], v[52:53]
	v_pk_mul_f32 v[40:41], v[30:31], v[46:47]
	v_pk_mul_f32 v[42:43], v[28:29], v[44:45]
	s_nop 0
	s_nop 0
	v_cvt_pk_bf16_f32 v28, v36, v37
	v_cvt_pk_bf16_f32 v29, v38, v39
	v_cvt_pk_bf16_f32 v30, v42, v43
	v_cvt_pk_bf16_f32 v31, v40, v41
	ds_read_b32 v36, v155 offset:640
	v_add_u32_e32 v37, s18, v138
	v_or_b32_e32 v37, v37, v150
	v_lshlrev_b32_e32 v37, 1, v37
	buffer_store_dwordx4 v[28:31], v37, s[72:75], 0 offen sc1
	s_waitcnt lgkmcnt(0)
	s_nop 0
	v_mul_f32_e32 v28, 0xbfb8aa3b, v36
	v_mul_f32_e32 v29, v36, v36
	v_pk_mul_f32 v[36:37], v[20:21], v[28:29] op_sel_hi:[1,0]
	v_rcp_f32_e32 v38, v29
	v_pk_mul_f32 v[30:31], v[22:23], v[28:29] op_sel_hi:[1,0]
	v_exp_f32_e32 v29, v36
	v_exp_f32_e32 v36, v37
	v_exp_f32_e32 v31, v31
	v_exp_f32_e32 v37, v30
	v_fma_f32 v29, v29, v38, v38
	v_rcp_f32_e32 v30, v29
	v_fma_f32 v29, v36, v38, v38
	v_fma_f32 v31, v31, v38, v38
	v_fma_f32 v36, v37, v38, v38
	v_rcp_f32_e32 v37, v31
	v_rcp_f32_e32 v31, v29
	v_pk_mul_f32 v[20:21], v[20:21], v[32:33]
	v_rcp_f32_e32 v36, v36
	v_pk_mul_f32 v[22:23], v[22:23], v[34:35]
	v_pk_mul_f32 v[20:21], v[20:21], v[30:31]
	v_pk_mul_f32 v[30:31], v[14:15], v[28:29] op_sel_hi:[1,0]
	v_pk_mul_f32 v[28:29], v[12:13], v[28:29] op_sel_hi:[1,0]
	v_exp_f32_e32 v30, v30
	v_exp_f32_e32 v28, v28
	v_exp_f32_e32 v29, v29
	v_exp_f32_e32 v31, v31
	v_fma_f32 v30, v30, v38, v38
	v_fma_f32 v28, v28, v38, v38
	v_fma_f32 v29, v29, v38, v38
	v_fmac_f32_e32 v38, v31, v38
	v_rcp_f32_e32 v28, v28
	v_rcp_f32_e32 v30, v30
	v_rcp_f32_e32 v31, v38
	v_rcp_f32_e32 v29, v29
	v_pk_mul_f32 v[14:15], v[14:15], v[26:27]
	v_pk_mul_f32 v[12:13], v[12:13], v[24:25]
	v_pk_mul_f32 v[22:23], v[22:23], v[36:37]
	v_pk_mul_f32 v[24:25], v[14:15], v[30:31]
	v_pk_mul_f32 v[26:27], v[12:13], v[28:29]
	s_nop 0
	s_nop 0
	v_cvt_pk_bf16_f32 v12, v20, v21
	v_cvt_pk_bf16_f32 v13, v22, v23
	v_cvt_pk_bf16_f32 v14, v26, v27
	v_cvt_pk_bf16_f32 v15, v24, v25
	ds_read_b32 v20, v155 offset:704
	v_add_u32_e32 v21, s18, v140
	v_or_b32_e32 v21, v21, v151
	v_lshlrev_b32_e32 v21, 1, v21
	buffer_store_dwordx4 v[12:15], v21, s[72:75], 0 offen sc1
	s_waitcnt lgkmcnt(0)
	s_nop 0
	v_mul_f32_e32 v12, 0xbfb8aa3b, v20
	v_mul_f32_e32 v13, v20, v20
	v_pk_mul_f32 v[20:21], v[4:5], v[12:13] op_sel_hi:[1,0]
	v_rcp_f32_e32 v22, v13
	v_pk_mul_f32 v[14:15], v[6:7], v[12:13] op_sel_hi:[1,0]
	v_exp_f32_e32 v13, v20
	v_exp_f32_e32 v20, v21
	v_exp_f32_e32 v15, v15
	v_exp_f32_e32 v21, v14
	v_fma_f32 v13, v13, v22, v22
	v_rcp_f32_e32 v14, v13
	v_fma_f32 v13, v20, v22, v22
	v_fma_f32 v15, v15, v22, v22
	v_fma_f32 v20, v21, v22, v22
	v_rcp_f32_e32 v21, v15
	v_rcp_f32_e32 v15, v13
	v_pk_mul_f32 v[4:5], v[4:5], v[16:17]
	v_rcp_f32_e32 v20, v20
	v_pk_mul_f32 v[6:7], v[6:7], v[18:19]
	v_pk_mul_f32 v[4:5], v[4:5], v[14:15]
	v_pk_mul_f32 v[14:15], v[2:3], v[12:13] op_sel_hi:[1,0]
	v_pk_mul_f32 v[12:13], v[0:1], v[12:13] op_sel_hi:[1,0]
	v_exp_f32_e32 v14, v14
	v_exp_f32_e32 v12, v12
	v_exp_f32_e32 v13, v13
	v_exp_f32_e32 v15, v15
	v_fma_f32 v14, v14, v22, v22
	v_fma_f32 v12, v12, v22, v22
	v_fma_f32 v13, v13, v22, v22
	v_rcp_f32_e32 v12, v12
	v_fmac_f32_e32 v22, v15, v22
	v_rcp_f32_e32 v13, v13
	v_rcp_f32_e32 v14, v14
	v_rcp_f32_e32 v15, v22
	v_pk_mul_f32 v[0:1], v[0:1], v[8:9]
	v_pk_mul_f32 v[2:3], v[2:3], v[10:11]
	v_pk_mul_f32 v[10:11], v[0:1], v[12:13]
	v_add_u32_e32 v12, s18, v142
	v_pk_mul_f32 v[6:7], v[6:7], v[20:21]
	v_pk_mul_f32 v[8:9], v[2:3], v[14:15]
	s_mov_b64 s[18:19], -1
	s_nop 0
	v_cvt_pk_bf16_f32 v0, v4, v5
	v_cvt_pk_bf16_f32 v1, v6, v7
	v_cvt_pk_bf16_f32 v2, v10, v11
	v_cvt_pk_bf16_f32 v3, v8, v9
	v_or_b32_e32 v4, v12, v152
	v_lshlrev_b32_e32 v4, 1, v4
	buffer_store_dwordx4 v[0:3], v4, s[72:75], 0 offen sc1
	s_cbranch_scc1 .LBB0_1091
	s_andn2_b64 vcc, exec, s[8:9]
	s_cbranch_vccnz .LBB0_1090
	s_barrier
	s_branch .LBB0_1090

.LBB0_1233:
	v_bfe_i32 v2, v188, 27, 1
	v_lshlrev_b32_e32 v1, 4, v188
	v_lshrrev_b32_e32 v2, 22, v2
	v_add_u32_e32 v2, v1, v2
	v_and_b32_e32 v2, 0xfffffc00, v2
	v_sub_u32_e32 v2, v1, v2
	v_ashrrev_i32_e32 v0, 31, v188
	v_lshrrev_b32_e32 v3, 4, v2
	v_lshrrev_b32_e32 v0, 26, v0
	v_bitop3_b32 v2, v3, v2, 32 bitop3:0x6c
	v_add_u32_e32 v0, v188, v0
	v_ashrrev_i32_e32 v4, 31, v2
	v_ashrrev_i32_e32 v0, 6, v0
	v_lshrrev_b32_e32 v4, 26, v4
	v_lshlrev_b32_e32 v3, 3, v0
	v_add_u32_e32 v4, v2, v4
	v_and_b32_e32 v3, -16, v3
	v_ashrrev_i32_e32 v5, 6, v4
	v_add_u32_e32 v8, v5, v3
	v_and_b32_e32 v3, 0xc0, v4
	v_lshlrev_b32_e32 v0, 5, v0
	v_sub_u32_e32 v2, v2, v3
	v_mov_b32_e32 v3, 1
	v_and_b32_e32 v0, 32, v0
	v_ashrrev_i16_sdwa v2, v3, sext(v2) dst_sel:DWORD dst_unused:UNUSED_PAD src0_sel:DWORD src1_sel:BYTE_0
	v_lshlrev_b32_e32 v4, 1, v8
	v_lshrrev_b32_e32 v6, 2, v8
	v_and_b32_e32 v7, 2, v5
	s_mov_b32 s1, 0x1ffffe0
	v_add_u32_sdwa v0, v0, sext(v2) dst_sel:DWORD dst_unused:UNUSED_PAD src0_sel:DWORD src1_sel:WORD_0
	v_and_b32_e32 v4, 24, v4
	v_and_b32_e32 v6, 4, v6
	v_and_or_b32 v7, v8, s1, v7
	v_mov_b32_e32 v15, 31
	v_lshrrev_b32_e32 v9, 5, v0
	v_and_b32_sdwa v11, sext(v2), v15 dst_sel:DWORD dst_unused:UNUSED_PAD src0_sel:WORD_0 src1_sel:DWORD
	v_or3_b32 v2, v6, v7, v4
	v_lshlrev_b32_e32 v4, 5, v5
	v_add_lshl_u32 v2, v2, v9, 6
	v_and_b32_e32 v4, 32, v4
	v_add_u32_e32 v1, 0x2000, v1
	v_or3_b32 v2, v2, v4, v11
	v_ashrrev_i32_e32 v4, 31, v1
	v_lshrrev_b32_e32 v4, 22, v4
	v_add_u32_e32 v4, v1, v4
	v_ashrrev_i32_e32 v4, 10, v4
	v_mul_i32_i24_e32 v5, 0x400, v4
	v_sub_u32_e32 v1, v1, v5
	v_lshrrev_b32_e32 v5, 4, v1
	v_bitop3_b32 v1, v5, v1, 32 bitop3:0x6c
	v_ashrrev_i32_e32 v6, 31, v1
	v_lshrrev_b32_e32 v6, 26, v6
	v_lshlrev_b32_e32 v5, 3, v4
	v_add_u32_e32 v6, v1, v6
	v_and_b32_e32 v5, -16, v5
	v_ashrrev_i32_e32 v7, 6, v6
	v_add_u32_e32 v12, v7, v5
	v_and_b32_e32 v5, 0xc0, v6
	v_lshlrev_b32_e32 v4, 5, v4
	v_sub_u32_e32 v1, v1, v5
	v_and_b32_e32 v4, 32, v4
	v_ashrrev_i16_sdwa v1, v3, sext(v1) dst_sel:DWORD dst_unused:UNUSED_PAD src0_sel:DWORD src1_sel:BYTE_0
	v_add_u32_sdwa v3, v4, sext(v1) dst_sel:DWORD dst_unused:UNUSED_PAD src0_sel:DWORD src1_sel:WORD_0
	v_lshlrev_b32_e32 v4, 1, v12
	v_and_b32_e32 v5, 24, v4
	v_lshrrev_b32_e32 v4, 2, v12
	v_and_b32_e32 v6, 4, v4
	v_and_b32_e32 v4, 2, v7
	s_add_u32 s25, s96, 0x3b80000
	v_and_or_b32 v16, v12, s1, v4
	v_readlane_b32 s1, v252, 7
	s_addc_u32 s26, s97, 0
	s_add_i32 s1, s4, s1
	s_ashr_i32 s4, s1, 31
	s_lshr_b32 s4, s4, 27
	v_and_b32_e32 v4, 0x1fffffe, v12
	v_lshrrev_b32_e32 v13, 5, v3
	s_add_i32 s4, s1, s4
	v_add_lshl_u32 v3, v13, v4, 6
	v_lshlrev_b32_e32 v4, 5, v12
	s_ashr_i32 s5, s4, 5
	v_and_b32_e32 v14, 32, v4
	v_and_b32_sdwa v15, sext(v1), v15 dst_sel:DWORD dst_unused:UNUSED_PAD src0_sel:WORD_0 src1_sel:DWORD
	s_lshl_b32 s5, s5, 3
	v_or3_b32 v1, v3, v14, v15
	s_sub_i32 s6, 64, s5
	v_lshlrev_b32_e32 v4, 1, v1
	v_or3_b32 v1, v6, v16, v5
	v_lshlrev_b32_e32 v3, 5, v7
	s_min_i32 s6, s6, 8
	v_add_lshl_u32 v1, v1, v13, 6
	v_and_b32_e32 v3, 32, v3
	s_abs_i32 s7, s6
	v_or3_b32 v1, v1, v3, v15
	v_cvt_f32_u32_e32 v3, s7
	v_lshlrev_b32_e32 v6, 1, v1
	s_sub_i32 s10, 0, s7
	s_andn2_b32 s4, s4, 31
	v_rcp_iflag_f32_e32 v1, v3
	s_sub_i32 s1, s1, s4
	s_abs_i32 s8, s1
	s_ashr_i32 s0, s9, 6
	v_mul_f32_e32 v1, 0x4f7ffffe, v1
	v_cvt_u32_f32_e32 v1, v1
	s_xor_b32 s4, s1, s6
	s_ashr_i32 s24, s9, 8
	s_lshl_b32 s27, s0, 10
	v_readfirstlane_b32 s11, v1
	s_mul_i32 s10, s10, s11
	s_mul_hi_u32 s10, s11, s10
	s_add_i32 s11, s11, s10
	s_mul_hi_u32 s10, s8, s11
	s_mul_i32 s11, s10, s7
	s_sub_i32 s8, s8, s11
	s_ashr_i32 s4, s4, 31
	s_add_i32 s11, s10, 1
	s_sub_i32 s12, s8, s7
	s_cmp_ge_u32 s8, s7
	s_cselect_b32 s10, s11, s10
	s_cselect_b32 s8, s12, s8
	s_add_i32 s11, s10, 1
	s_cmp_ge_u32 s8, s7
	s_cselect_b32 s7, s11, s10
	s_xor_b32 s7, s7, s4
	s_sub_i32 s8, s7, s4
	s_mul_i32 s4, s8, s6
	s_sub_i32 s1, s1, s4
	s_add_i32 s10, s5, s1
	s_mul_i32 s5, s8, 0x160000
	s_mul_hi_i32 s4, s8, 0x160000
	s_add_u32 s18, s25, s5
	s_addc_u32 s19, s26, s4
	s_add_i32 s29, s27, 0x100
	v_lshlrev_b32_e32 v2, 1, v2
	s_add_i32 m0, s29, 0x10000
	s_nop 0
	global_load_lds_dwordx4 v2, s[18:19] sc1
	s_add_i32 m0, s29, 0x12000
	s_add_u32 s4, s18, 0x4000
	v_and_b32_e32 v10, 0x1fffffe, v8
	global_load_lds_dwordx4 v6, s[18:19] sc1
	s_addc_u32 s5, s19, 0
	s_add_i32 m0, s29, 0x14000
	v_add_lshl_u32 v0, v9, v10, 6
	v_lshlrev_b32_e32 v10, 5, v8
	s_mul_i32 s6, s10, 0x180000
	global_load_lds_dwordx4 v2, s[4:5] sc1
	s_add_i32 m0, s29, 0x16000
	v_and_b32_e32 v10, 32, v10
	s_mul_hi_i32 s1, s10, 0x180000
	s_add_u32 s12, s92, s6
	v_or3_b32 v0, v0, v10, v11
	s_addc_u32 s13, s93, s1
	s_add_i32 s30, s29, 0x2000
	v_lshlrev_b32_e32 v0, 1, v0
	global_load_lds_dwordx4 v6, s[4:5] sc1
	s_mov_b32 m0, s29
	s_add_u32 s4, s12, 0x4000
	global_load_lds_dwordx4 v0, s[12:13] sc1
	s_mov_b32 m0, s30
	s_addc_u32 s5, s13, 0
	s_add_i32 s31, s29, 0x4000
	global_load_lds_dwordx4 v4, s[12:13] sc1
	s_mov_b32 m0, s31
	s_add_i32 s35, s29, 0x6000
	global_load_lds_dwordx4 v0, s[4:5] sc1
	s_mov_b32 m0, s35
	v_mov_b32_e32 v3, 0
	global_load_lds_dwordx4 v4, s[4:5] sc1
	s_mov_b32 s42, 0
	s_mov_b32 s1, 0x10000
	v_mov_b32_e32 v7, v3
	s_mov_b32 s4, 0x14000
	v_mov_b32_e32 v1, v3
	s_cmp_lg_u32 s24, 1
	v_mov_b32_e32 v5, v3
	s_cbranch_scc1 .LBB0_1235
	s_barrier

.LBB0_1248:
	s_add_u32 s49, s18, 0x10000
	s_addc_u32 s50, s19, 0
	s_lshl_b32 s18, s8, 2
	s_ashr_i32 s11, s10, 31
	s_ashr_i32 s19, s18, 31
	s_lshl_b64 s[20:21], s[10:11], 19
	s_lshl_b64 s[18:19], s[18:19], 15
	s_add_u32 s11, s60, s18
	s_addc_u32 s18, s33, s19
	s_add_u32 s11, s11, s20
	s_addc_u32 s18, s18, s21
	s_add_u32 s19, s11, 0x10000
	s_addc_u32 s20, s18, 0
	s_and_b64 s[6:7], s[6:7], exec
	s_cselect_b32 s51, s17, s20
	s_cselect_b32 s52, s16, s19
	s_cselect_b32 s53, s15, s18
	s_cselect_b32 s54, s14, s11
	v_lshl_add_u64 v[144:145], s[12:13], 0, v[8:9]
	v_lshl_add_u64 v[146:147], s[12:13], 0, v[10:11]
	s_mov_b32 s55, -2
	s_mov_b64 s[6:7], 0
	s_add_u32 s11, s12, s6
	v_add_u32_e32 v160, s40, v150
	s_addc_u32 s18, s13, s7
	ds_read_b128 v[152:155], v160
	ds_read_b128 v[156:159], v160 offset:1024
	ds_read_b128 v[164:167], v160 offset:2048
	ds_read_b128 v[168:171], v160 offset:3072
	v_add_u32_e32 v160, s41, v150
	s_add_u32 s11, s11, 0x10000
	ds_read_b128 v[172:175], v160
	ds_read_b128 v[182:185], v160 offset:1024
	ds_read_b128 v[190:193], v160 offset:2048
	ds_read_b128 v[194:197], v160 offset:3072
	s_addc_u32 s18, s18, 0
	s_add_u32 s19, s49, s6
	s_addc_u32 s21, s50, s7
	s_cmp_eq_u32 s6, 0x150000
	s_cselect_b32 s22, s52, s11
	s_cselect_b32 s23, s51, s18
	s_cselect_b32 s20, s54, s19
	s_cselect_b32 s21, s53, s21
	s_add_u32 s18, s22, 0x8000
	s_addc_u32 s19, s23, 0
	s_add_i32 s11, s29, 0xc000
	v_lshl_add_u64 v[160:161], v[144:145], 0, s[6:7]
	s_mov_b32 m0, s11
	s_add_i32 s48, s29, 0xe000
	ds_read_b128 v[198:201], v151
	ds_read_b128 v[202:205], v151 offset:1024
	ds_read_b128 v[206:209], v151 offset:2048
	ds_read_b128 v[210:213], v151 offset:3072
	ds_read_b128 v[214:217], v151 offset:4096
	ds_read_b128 v[218:221], v151 offset:5120
	ds_read_b128 v[222:225], v151 offset:6144
	ds_read_b128 v[226:229], v151 offset:7168
	global_load_lds_dwordx4 v[160:161], off sc1
	v_lshl_add_u64 v[160:161], v[146:147], 0, s[6:7]
	s_mov_b32 m0, s48
	s_nop 0
	global_load_lds_dwordx4 v[160:161], off sc1
	s_waitcnt vmcnt(8)
	s_waitcnt lgkmcnt(0)
	s_setprio 1
	s_barrier
	v_mfma_f32_16x16x32_bf16 v[128:131], v[152:155], v[198:201], 0
	v_mfma_f32_16x16x32_bf16 v[132:135], v[164:167], v[198:201], 0
	v_mfma_f32_16x16x32_bf16 v[112:115], v[152:155], v[206:209], 0
	v_mfma_f32_16x16x32_bf16 v[116:119], v[164:167], v[206:209], 0
	v_mfma_f32_16x16x32_bf16 v[96:99], v[152:155], v[214:217], 0
	v_mfma_f32_16x16x32_bf16 v[100:103], v[164:167], v[214:217], 0
	v_mfma_f32_16x16x32_bf16 v[72:75], v[152:155], v[222:225], 0
	v_mfma_f32_16x16x32_bf16 v[76:79], v[164:167], v[222:225], 0
	v_mfma_f32_16x16x32_bf16 v[128:131], v[156:159], v[202:205], v[128:131]
	v_mfma_f32_16x16x32_bf16 v[132:135], v[168:171], v[202:205], v[132:135]
	v_mfma_f32_16x16x32_bf16 v[112:115], v[156:159], v[210:213], v[112:115]
	v_mfma_f32_16x16x32_bf16 v[116:119], v[168:171], v[210:213], v[116:119]
	v_mfma_f32_16x16x32_bf16 v[96:99], v[156:159], v[218:221], v[96:99]
	v_mfma_f32_16x16x32_bf16 v[100:103], v[168:171], v[218:221], v[100:103]
	v_mfma_f32_16x16x32_bf16 v[72:75], v[156:159], v[226:229], v[72:75]
	v_mfma_f32_16x16x32_bf16 v[76:79], v[168:171], v[226:229], v[76:79]
	v_mfma_f32_16x16x32_bf16 v[136:139], v[172:175], v[198:201], 0
	v_mfma_f32_16x16x32_bf16 v[140:143], v[190:193], v[198:201], 0
	v_mfma_f32_16x16x32_bf16 v[120:123], v[172:175], v[206:209], 0
	v_mfma_f32_16x16x32_bf16 v[124:127], v[190:193], v[206:209], 0
	v_mfma_f32_16x16x32_bf16 v[104:107], v[172:175], v[214:217], 0
	v_mfma_f32_16x16x32_bf16 v[108:111], v[190:193], v[214:217], 0
	v_mfma_f32_16x16x32_bf16 v[88:91], v[172:175], v[222:225], 0
	v_mfma_f32_16x16x32_bf16 v[92:95], v[190:193], v[222:225], 0
	v_mfma_f32_16x16x32_bf16 v[136:139], v[182:185], v[202:205], v[136:139]
	v_mfma_f32_16x16x32_bf16 v[140:143], v[194:197], v[202:205], v[140:143]
	v_mfma_f32_16x16x32_bf16 v[120:123], v[182:185], v[210:213], v[120:123]
	v_mfma_f32_16x16x32_bf16 v[124:127], v[194:197], v[210:213], v[124:127]
	v_mfma_f32_16x16x32_bf16 v[104:107], v[182:185], v[218:221], v[104:107]
	v_mfma_f32_16x16x32_bf16 v[108:111], v[194:197], v[218:221], v[108:111]
	s_setprio 2
	s_barrier
	v_mfma_f32_16x16x32_bf16 v[88:91], v[182:185], v[226:229], v[88:91]
	v_mfma_f32_16x16x32_bf16 v[92:95], v[194:197], v[226:229], v[92:95]
	s_setprio 0
	s_add_i32 s56, s40, s27
	s_mov_b32 m0, s56
	ds_read_b128 v[198:201], v151 offset:16384
	ds_read_b128 v[202:205], v151 offset:17408
	ds_read_b128 v[206:209], v151 offset:18432
	ds_read_b128 v[210:213], v151 offset:19456
	ds_read_b128 v[214:217], v151 offset:20480
	ds_read_b128 v[218:221], v151 offset:21504
	ds_read_b128 v[222:225], v151 offset:22528
	ds_read_b128 v[226:229], v151 offset:23552
	global_load_lds_dwordx4 v2, s[20:21] sc1
	s_add_i32 m0, s56, 0x2000
	s_add_u32 s56, s20, 0x4000
	s_addc_u32 s57, s21, 0
	s_add_i32 s58, s41, s27
	global_load_lds_dwordx4 v6, s[20:21] sc1
	s_mov_b32 m0, s58
	s_nop 0
	global_load_lds_dwordx4 v2, s[56:57] sc1
	s_add_i32 m0, s58, 0x2000
	s_nop 0
	global_load_lds_dwordx4 v6, s[56:57] sc1
	s_mov_b32 m0, s29
	s_nop 0
	global_load_lds_dwordx4 v0, s[22:23] sc1
	s_mov_b32 m0, s30
	s_nop 0
	global_load_lds_dwordx4 v4, s[22:23] sc1
	s_waitcnt vmcnt(8)
	s_waitcnt lgkmcnt(0)
	s_setprio 1
	s_barrier
	v_mfma_f32_16x16x32_bf16 v[64:67], v[152:155], v[198:201], 0
	v_mfma_f32_16x16x32_bf16 v[68:71], v[164:167], v[198:201], 0
	v_mfma_f32_16x16x32_bf16 v[48:51], v[152:155], v[206:209], 0
	v_mfma_f32_16x16x32_bf16 v[52:55], v[164:167], v[206:209], 0
	v_mfma_f32_16x16x32_bf16 v[32:35], v[152:155], v[214:217], 0
	v_mfma_f32_16x16x32_bf16 v[36:39], v[164:167], v[214:217], 0
	v_mfma_f32_16x16x32_bf16 v[16:19], v[152:155], v[222:225], 0
	v_mfma_f32_16x16x32_bf16 v[20:23], v[164:167], v[222:225], 0
	v_mfma_f32_16x16x32_bf16 v[64:67], v[156:159], v[202:205], v[64:67]
	v_mfma_f32_16x16x32_bf16 v[68:71], v[168:171], v[202:205], v[68:71]
	v_mfma_f32_16x16x32_bf16 v[48:51], v[156:159], v[210:213], v[48:51]
	v_mfma_f32_16x16x32_bf16 v[52:55], v[168:171], v[210:213], v[52:55]
	v_mfma_f32_16x16x32_bf16 v[32:35], v[156:159], v[218:221], v[32:35]
	v_mfma_f32_16x16x32_bf16 v[36:39], v[168:171], v[218:221], v[36:39]
	v_mfma_f32_16x16x32_bf16 v[16:19], v[156:159], v[226:229], v[16:19]
	v_mfma_f32_16x16x32_bf16 v[20:23], v[168:171], v[226:229], v[20:23]
	v_mfma_f32_16x16x32_bf16 v[80:83], v[172:175], v[198:201], 0
	v_mfma_f32_16x16x32_bf16 v[84:87], v[190:193], v[198:201], 0
	v_mfma_f32_16x16x32_bf16 v[56:59], v[172:175], v[206:209], 0
	v_mfma_f32_16x16x32_bf16 v[60:63], v[190:193], v[206:209], 0
	v_mfma_f32_16x16x32_bf16 v[40:43], v[172:175], v[214:217], 0
	v_mfma_f32_16x16x32_bf16 v[44:47], v[190:193], v[214:217], 0
	v_mfma_f32_16x16x32_bf16 v[24:27], v[172:175], v[222:225], 0
	v_mfma_f32_16x16x32_bf16 v[28:31], v[190:193], v[222:225], 0
	v_mfma_f32_16x16x32_bf16 v[80:83], v[182:185], v[202:205], v[80:83]
	v_mfma_f32_16x16x32_bf16 v[84:87], v[194:197], v[202:205], v[84:87]
	v_mfma_f32_16x16x32_bf16 v[56:59], v[182:185], v[210:213], v[56:59]
	v_mfma_f32_16x16x32_bf16 v[60:63], v[194:197], v[210:213], v[60:63]
	v_mfma_f32_16x16x32_bf16 v[40:43], v[182:185], v[218:221], v[40:43]
	v_mfma_f32_16x16x32_bf16 v[44:47], v[194:197], v[218:221], v[44:47]
	s_setprio 2
	s_barrier
	v_mfma_f32_16x16x32_bf16 v[24:27], v[182:185], v[226:229], v[24:27]
	v_mfma_f32_16x16x32_bf16 v[28:31], v[194:197], v[226:229], v[28:31]
	s_setprio 0
	v_add_u32_e32 v160, s43, v150
	ds_read_b128 v[152:155], v160
	ds_read_b128 v[156:159], v160 offset:1024
	ds_read_b128 v[164:167], v160 offset:2048
	ds_read_b128 v[168:171], v160 offset:3072
	v_add_u32_e32 v160, s44, v150
	ds_read_b128 v[172:175], v160
	ds_read_b128 v[182:185], v160 offset:1024
	ds_read_b128 v[190:193], v160 offset:2048
	ds_read_b128 v[194:197], v160 offset:3072
	s_add_u32 s22, s22, 0x4000
	s_addc_u32 s23, s23, 0
	s_mov_b32 m0, s31
	ds_read_b128 v[198:201], v151 offset:32768
	ds_read_b128 v[202:205], v151 offset:33792
	ds_read_b128 v[206:209], v151 offset:34816
	ds_read_b128 v[210:213], v151 offset:35840
	ds_read_b128 v[214:217], v151 offset:36864
	ds_read_b128 v[218:221], v151 offset:37888
	ds_read_b128 v[222:225], v151 offset:38912
	ds_read_b128 v[226:229], v151 offset:39936
	global_load_lds_dwordx4 v0, s[22:23] sc1
	s_mov_b32 m0, s35
	s_nop 0
	global_load_lds_dwordx4 v4, s[22:23] sc1
	s_waitcnt vmcnt(8)
	s_waitcnt lgkmcnt(0)
	s_setprio 1
	s_barrier
	v_mfma_f32_16x16x32_bf16 v[128:131], v[152:155], v[198:201], v[128:131]
	v_mfma_f32_16x16x32_bf16 v[132:135], v[164:167], v[198:201], v[132:135]
	v_mfma_f32_16x16x32_bf16 v[112:115], v[152:155], v[206:209], v[112:115]
	v_mfma_f32_16x16x32_bf16 v[116:119], v[164:167], v[206:209], v[116:119]
	v_mfma_f32_16x16x32_bf16 v[96:99], v[152:155], v[214:217], v[96:99]
	v_mfma_f32_16x16x32_bf16 v[100:103], v[164:167], v[214:217], v[100:103]
	v_mfma_f32_16x16x32_bf16 v[72:75], v[152:155], v[222:225], v[72:75]
	v_mfma_f32_16x16x32_bf16 v[76:79], v[164:167], v[222:225], v[76:79]
	v_mfma_f32_16x16x32_bf16 v[128:131], v[156:159], v[202:205], v[128:131]
	v_mfma_f32_16x16x32_bf16 v[132:135], v[168:171], v[202:205], v[132:135]
	v_mfma_f32_16x16x32_bf16 v[112:115], v[156:159], v[210:213], v[112:115]
	v_mfma_f32_16x16x32_bf16 v[116:119], v[168:171], v[210:213], v[116:119]
	v_mfma_f32_16x16x32_bf16 v[96:99], v[156:159], v[218:221], v[96:99]
	v_mfma_f32_16x16x32_bf16 v[100:103], v[168:171], v[218:221], v[100:103]
	v_mfma_f32_16x16x32_bf16 v[72:75], v[156:159], v[226:229], v[72:75]
	v_mfma_f32_16x16x32_bf16 v[76:79], v[168:171], v[226:229], v[76:79]
	v_mfma_f32_16x16x32_bf16 v[136:139], v[172:175], v[198:201], v[136:139]
	v_mfma_f32_16x16x32_bf16 v[140:143], v[190:193], v[198:201], v[140:143]
	v_mfma_f32_16x16x32_bf16 v[120:123], v[172:175], v[206:209], v[120:123]
	v_mfma_f32_16x16x32_bf16 v[124:127], v[190:193], v[206:209], v[124:127]
	v_mfma_f32_16x16x32_bf16 v[104:107], v[172:175], v[214:217], v[104:107]
	v_mfma_f32_16x16x32_bf16 v[108:111], v[190:193], v[214:217], v[108:111]
	v_mfma_f32_16x16x32_bf16 v[88:91], v[172:175], v[222:225], v[88:91]
	v_mfma_f32_16x16x32_bf16 v[92:95], v[190:193], v[222:225], v[92:95]
	v_mfma_f32_16x16x32_bf16 v[136:139], v[182:185], v[202:205], v[136:139]
	v_mfma_f32_16x16x32_bf16 v[140:143], v[194:197], v[202:205], v[140:143]
	v_mfma_f32_16x16x32_bf16 v[120:123], v[182:185], v[210:213], v[120:123]
	v_mfma_f32_16x16x32_bf16 v[124:127], v[194:197], v[210:213], v[124:127]
	v_mfma_f32_16x16x32_bf16 v[104:107], v[182:185], v[218:221], v[104:107]
	v_mfma_f32_16x16x32_bf16 v[108:111], v[194:197], v[218:221], v[108:111]
	s_setprio 2
	s_barrier
	v_mfma_f32_16x16x32_bf16 v[88:91], v[182:185], v[226:229], v[88:91]
	v_mfma_f32_16x16x32_bf16 v[92:95], v[194:197], v[226:229], v[92:95]
	s_setprio 0
	s_add_u32 s22, s20, 0x8000
	s_addc_u32 s23, s21, 0
	s_add_i32 s56, s43, s27
	s_mov_b32 m0, s56
	ds_read_b128 v[198:201], v151 offset:49152
	ds_read_b128 v[202:205], v151 offset:50176
	ds_read_b128 v[206:209], v151 offset:51200
	ds_read_b128 v[210:213], v151 offset:52224
	ds_read_b128 v[214:217], v151 offset:53248
	ds_read_b128 v[218:221], v151 offset:54272
	ds_read_b128 v[222:225], v151 offset:55296
	ds_read_b128 v[226:229], v151 offset:56320
	global_load_lds_dwordx4 v2, s[22:23] sc1
	s_add_i32 m0, s56, 0x2000
	s_add_u32 s20, s20, 0xc000
	global_load_lds_dwordx4 v6, s[22:23] sc1
	s_addc_u32 s21, s21, 0
	s_add_i32 s22, s44, s27
	s_mov_b32 m0, s22
	s_nop 0
	global_load_lds_dwordx4 v2, s[20:21] sc1
	s_add_i32 m0, s22, 0x2000
	s_nop 0
	global_load_lds_dwordx4 v6, s[20:21] sc1
	s_mov_b32 m0, s38
	s_nop 0
	global_load_lds_dwordx4 v0, s[18:19] sc1
	s_mov_b32 m0, s39
	s_nop 0
	global_load_lds_dwordx4 v4, s[18:19] sc1
	s_waitcnt vmcnt(8)
	s_waitcnt lgkmcnt(0)
	s_setprio 1
	s_barrier
	v_mfma_f32_16x16x32_bf16 v[64:67], v[152:155], v[198:201], v[64:67]
	v_mfma_f32_16x16x32_bf16 v[68:71], v[164:167], v[198:201], v[68:71]
	v_mfma_f32_16x16x32_bf16 v[48:51], v[152:155], v[206:209], v[48:51]
	v_mfma_f32_16x16x32_bf16 v[52:55], v[164:167], v[206:209], v[52:55]
	v_mfma_f32_16x16x32_bf16 v[32:35], v[152:155], v[214:217], v[32:35]
	v_mfma_f32_16x16x32_bf16 v[36:39], v[164:167], v[214:217], v[36:39]
	v_mfma_f32_16x16x32_bf16 v[16:19], v[152:155], v[222:225], v[16:19]
	v_mfma_f32_16x16x32_bf16 v[20:23], v[164:167], v[222:225], v[20:23]
	v_mfma_f32_16x16x32_bf16 v[64:67], v[156:159], v[202:205], v[64:67]
	v_mfma_f32_16x16x32_bf16 v[68:71], v[168:171], v[202:205], v[68:71]
	v_mfma_f32_16x16x32_bf16 v[48:51], v[156:159], v[210:213], v[48:51]
	v_mfma_f32_16x16x32_bf16 v[52:55], v[168:171], v[210:213], v[52:55]
	v_mfma_f32_16x16x32_bf16 v[32:35], v[156:159], v[218:221], v[32:35]
	v_mfma_f32_16x16x32_bf16 v[36:39], v[168:171], v[218:221], v[36:39]
	v_mfma_f32_16x16x32_bf16 v[16:19], v[156:159], v[226:229], v[16:19]
	v_mfma_f32_16x16x32_bf16 v[20:23], v[168:171], v[226:229], v[20:23]
	v_mfma_f32_16x16x32_bf16 v[80:83], v[172:175], v[198:201], v[80:83]
	v_mfma_f32_16x16x32_bf16 v[84:87], v[190:193], v[198:201], v[84:87]
	v_mfma_f32_16x16x32_bf16 v[56:59], v[172:175], v[206:209], v[56:59]
	v_mfma_f32_16x16x32_bf16 v[60:63], v[190:193], v[206:209], v[60:63]
	v_mfma_f32_16x16x32_bf16 v[40:43], v[172:175], v[214:217], v[40:43]
	v_mfma_f32_16x16x32_bf16 v[44:47], v[190:193], v[214:217], v[44:47]
	v_mfma_f32_16x16x32_bf16 v[24:27], v[172:175], v[222:225], v[24:27]
	v_mfma_f32_16x16x32_bf16 v[28:31], v[190:193], v[222:225], v[28:31]
	v_mfma_f32_16x16x32_bf16 v[80:83], v[182:185], v[202:205], v[80:83]
	v_mfma_f32_16x16x32_bf16 v[84:87], v[194:197], v[202:205], v[84:87]
	v_mfma_f32_16x16x32_bf16 v[56:59], v[182:185], v[210:213], v[56:59]
	v_mfma_f32_16x16x32_bf16 v[60:63], v[194:197], v[210:213], v[60:63]
	v_mfma_f32_16x16x32_bf16 v[40:43], v[182:185], v[218:221], v[40:43]
	v_mfma_f32_16x16x32_bf16 v[44:47], v[194:197], v[218:221], v[44:47]
	s_setprio 2
	s_barrier
	v_mfma_f32_16x16x32_bf16 v[24:27], v[182:185], v[226:229], v[24:27]
	v_mfma_f32_16x16x32_bf16 v[28:31], v[194:197], v[226:229], v[28:31]
	s_setprio 0
	s_add_i32 s55, s55, 2
	s_add_u32 s6, s6, 0x10000
	s_addc_u32 s7, s7, 0
	s_cmp_gt_u32 s55, 41
.LBB0_1249:
	s_add_u32 s11, s12, s6
	v_add_u32_e32 v160, s40, v150
	s_addc_u32 s18, s13, s7
	ds_read_b128 v[152:155], v160
	ds_read_b128 v[156:159], v160 offset:1024
	ds_read_b128 v[164:167], v160 offset:2048
	ds_read_b128 v[168:171], v160 offset:3072
	v_add_u32_e32 v160, s41, v150
	s_add_u32 s11, s11, 0x10000
	ds_read_b128 v[172:175], v160
	ds_read_b128 v[182:185], v160 offset:1024
	ds_read_b128 v[190:193], v160 offset:2048
	ds_read_b128 v[194:197], v160 offset:3072
	s_addc_u32 s18, s18, 0
	s_add_u32 s19, s49, s6
	s_addc_u32 s21, s50, s7
	s_cmp_eq_u32 s6, 0x150000
	s_cselect_b32 s22, s52, s11
	s_cselect_b32 s23, s51, s18
	s_cselect_b32 s20, s54, s19
	s_cselect_b32 s21, s53, s21
	s_add_u32 s18, s22, 0x8000
	s_addc_u32 s19, s23, 0
	s_add_i32 s11, s29, 0xc000
	v_lshl_add_u64 v[160:161], v[144:145], 0, s[6:7]
	s_mov_b32 m0, s11
	s_add_i32 s48, s29, 0xe000
	ds_read_b128 v[198:201], v151
	ds_read_b128 v[202:205], v151 offset:1024
	ds_read_b128 v[206:209], v151 offset:2048
	ds_read_b128 v[210:213], v151 offset:3072
	ds_read_b128 v[214:217], v151 offset:4096
	ds_read_b128 v[218:221], v151 offset:5120
	ds_read_b128 v[222:225], v151 offset:6144
	ds_read_b128 v[226:229], v151 offset:7168
	global_load_lds_dwordx4 v[160:161], off sc1
	v_lshl_add_u64 v[160:161], v[146:147], 0, s[6:7]
	s_mov_b32 m0, s48
	s_nop 0
	global_load_lds_dwordx4 v[160:161], off sc1
	s_waitcnt vmcnt(8)
	s_waitcnt lgkmcnt(0)
	s_setprio 1
	s_barrier
	v_mfma_f32_16x16x32_bf16 v[128:131], v[152:155], v[198:201], v[128:131]
	v_mfma_f32_16x16x32_bf16 v[132:135], v[164:167], v[198:201], v[132:135]
	v_mfma_f32_16x16x32_bf16 v[112:115], v[152:155], v[206:209], v[112:115]
	v_mfma_f32_16x16x32_bf16 v[116:119], v[164:167], v[206:209], v[116:119]
	v_mfma_f32_16x16x32_bf16 v[96:99], v[152:155], v[214:217], v[96:99]
	v_mfma_f32_16x16x32_bf16 v[100:103], v[164:167], v[214:217], v[100:103]
	v_mfma_f32_16x16x32_bf16 v[72:75], v[152:155], v[222:225], v[72:75]
	v_mfma_f32_16x16x32_bf16 v[76:79], v[164:167], v[222:225], v[76:79]
	v_mfma_f32_16x16x32_bf16 v[128:131], v[156:159], v[202:205], v[128:131]
	v_mfma_f32_16x16x32_bf16 v[132:135], v[168:171], v[202:205], v[132:135]
	v_mfma_f32_16x16x32_bf16 v[112:115], v[156:159], v[210:213], v[112:115]
	v_mfma_f32_16x16x32_bf16 v[116:119], v[168:171], v[210:213], v[116:119]
	v_mfma_f32_16x16x32_bf16 v[96:99], v[156:159], v[218:221], v[96:99]
	v_mfma_f32_16x16x32_bf16 v[100:103], v[168:171], v[218:221], v[100:103]
	v_mfma_f32_16x16x32_bf16 v[72:75], v[156:159], v[226:229], v[72:75]
	v_mfma_f32_16x16x32_bf16 v[76:79], v[168:171], v[226:229], v[76:79]
	v_mfma_f32_16x16x32_bf16 v[136:139], v[172:175], v[198:201], v[136:139]
	v_mfma_f32_16x16x32_bf16 v[140:143], v[190:193], v[198:201], v[140:143]
	v_mfma_f32_16x16x32_bf16 v[120:123], v[172:175], v[206:209], v[120:123]
	v_mfma_f32_16x16x32_bf16 v[124:127], v[190:193], v[206:209], v[124:127]
	v_mfma_f32_16x16x32_bf16 v[104:107], v[172:175], v[214:217], v[104:107]
	v_mfma_f32_16x16x32_bf16 v[108:111], v[190:193], v[214:217], v[108:111]
	v_mfma_f32_16x16x32_bf16 v[88:91], v[172:175], v[222:225], v[88:91]
	v_mfma_f32_16x16x32_bf16 v[92:95], v[190:193], v[222:225], v[92:95]
	v_mfma_f32_16x16x32_bf16 v[136:139], v[182:185], v[202:205], v[136:139]
	v_mfma_f32_16x16x32_bf16 v[140:143], v[194:197], v[202:205], v[140:143]
	v_mfma_f32_16x16x32_bf16 v[120:123], v[182:185], v[210:213], v[120:123]
	v_mfma_f32_16x16x32_bf16 v[124:127], v[194:197], v[210:213], v[124:127]
	v_mfma_f32_16x16x32_bf16 v[104:107], v[182:185], v[218:221], v[104:107]
	v_mfma_f32_16x16x32_bf16 v[108:111], v[194:197], v[218:221], v[108:111]
	s_setprio 2
	s_barrier
	v_mfma_f32_16x16x32_bf16 v[88:91], v[182:185], v[226:229], v[88:91]
	v_mfma_f32_16x16x32_bf16 v[92:95], v[194:197], v[226:229], v[92:95]
	s_setprio 0
	s_add_i32 s56, s40, s27
	s_mov_b32 m0, s56
	ds_read_b128 v[198:201], v151 offset:16384
	ds_read_b128 v[202:205], v151 offset:17408
	ds_read_b128 v[206:209], v151 offset:18432
	ds_read_b128 v[210:213], v151 offset:19456
	ds_read_b128 v[214:217], v151 offset:20480
	ds_read_b128 v[218:221], v151 offset:21504
	ds_read_b128 v[222:225], v151 offset:22528
	ds_read_b128 v[226:229], v151 offset:23552
	global_load_lds_dwordx4 v2, s[20:21] sc1
	s_add_i32 m0, s56, 0x2000
	s_add_u32 s56, s20, 0x4000
	s_addc_u32 s57, s21, 0
	s_add_i32 s58, s41, s27
	global_load_lds_dwordx4 v6, s[20:21] sc1
	s_mov_b32 m0, s58
	s_nop 0
	global_load_lds_dwordx4 v2, s[56:57] sc1
	s_add_i32 m0, s58, 0x2000
	s_nop 0
	global_load_lds_dwordx4 v6, s[56:57] sc1
	s_mov_b32 m0, s29
	s_nop 0
	global_load_lds_dwordx4 v0, s[22:23] sc1
	s_mov_b32 m0, s30
	s_nop 0
	global_load_lds_dwordx4 v4, s[22:23] sc1
	s_waitcnt vmcnt(8)
	s_waitcnt lgkmcnt(0)
	s_setprio 1
	s_barrier
	v_mfma_f32_16x16x32_bf16 v[64:67], v[152:155], v[198:201], v[64:67]
	v_mfma_f32_16x16x32_bf16 v[68:71], v[164:167], v[198:201], v[68:71]
	v_mfma_f32_16x16x32_bf16 v[48:51], v[152:155], v[206:209], v[48:51]
	v_mfma_f32_16x16x32_bf16 v[52:55], v[164:167], v[206:209], v[52:55]
	v_mfma_f32_16x16x32_bf16 v[32:35], v[152:155], v[214:217], v[32:35]
	v_mfma_f32_16x16x32_bf16 v[36:39], v[164:167], v[214:217], v[36:39]
	v_mfma_f32_16x16x32_bf16 v[16:19], v[152:155], v[222:225], v[16:19]
	v_mfma_f32_16x16x32_bf16 v[20:23], v[164:167], v[222:225], v[20:23]
	v_mfma_f32_16x16x32_bf16 v[64:67], v[156:159], v[202:205], v[64:67]
	v_mfma_f32_16x16x32_bf16 v[68:71], v[168:171], v[202:205], v[68:71]
	v_mfma_f32_16x16x32_bf16 v[48:51], v[156:159], v[210:213], v[48:51]
	v_mfma_f32_16x16x32_bf16 v[52:55], v[168:171], v[210:213], v[52:55]
	v_mfma_f32_16x16x32_bf16 v[32:35], v[156:159], v[218:221], v[32:35]
	v_mfma_f32_16x16x32_bf16 v[36:39], v[168:171], v[218:221], v[36:39]
	v_mfma_f32_16x16x32_bf16 v[16:19], v[156:159], v[226:229], v[16:19]
	v_mfma_f32_16x16x32_bf16 v[20:23], v[168:171], v[226:229], v[20:23]
	v_mfma_f32_16x16x32_bf16 v[80:83], v[172:175], v[198:201], v[80:83]
	v_mfma_f32_16x16x32_bf16 v[84:87], v[190:193], v[198:201], v[84:87]
	v_mfma_f32_16x16x32_bf16 v[56:59], v[172:175], v[206:209], v[56:59]
	v_mfma_f32_16x16x32_bf16 v[60:63], v[190:193], v[206:209], v[60:63]
	v_mfma_f32_16x16x32_bf16 v[40:43], v[172:175], v[214:217], v[40:43]
	v_mfma_f32_16x16x32_bf16 v[44:47], v[190:193], v[214:217], v[44:47]
	v_mfma_f32_16x16x32_bf16 v[24:27], v[172:175], v[222:225], v[24:27]
	v_mfma_f32_16x16x32_bf16 v[28:31], v[190:193], v[222:225], v[28:31]
	v_mfma_f32_16x16x32_bf16 v[80:83], v[182:185], v[202:205], v[80:83]
	v_mfma_f32_16x16x32_bf16 v[84:87], v[194:197], v[202:205], v[84:87]
	v_mfma_f32_16x16x32_bf16 v[56:59], v[182:185], v[210:213], v[56:59]
	v_mfma_f32_16x16x32_bf16 v[60:63], v[194:197], v[210:213], v[60:63]
	v_mfma_f32_16x16x32_bf16 v[40:43], v[182:185], v[218:221], v[40:43]
	v_mfma_f32_16x16x32_bf16 v[44:47], v[194:197], v[218:221], v[44:47]
	s_setprio 2
	s_barrier
	v_mfma_f32_16x16x32_bf16 v[24:27], v[182:185], v[226:229], v[24:27]
	v_mfma_f32_16x16x32_bf16 v[28:31], v[194:197], v[226:229], v[28:31]
	s_setprio 0
	v_add_u32_e32 v160, s43, v150
	ds_read_b128 v[152:155], v160
	ds_read_b128 v[156:159], v160 offset:1024
	ds_read_b128 v[164:167], v160 offset:2048
	ds_read_b128 v[168:171], v160 offset:3072
	v_add_u32_e32 v160, s44, v150
	ds_read_b128 v[172:175], v160
	ds_read_b128 v[182:185], v160 offset:1024
	ds_read_b128 v[190:193], v160 offset:2048
	ds_read_b128 v[194:197], v160 offset:3072
	s_add_u32 s22, s22, 0x4000
	s_addc_u32 s23, s23, 0
	s_mov_b32 m0, s31
	ds_read_b128 v[198:201], v151 offset:32768
	ds_read_b128 v[202:205], v151 offset:33792
	ds_read_b128 v[206:209], v151 offset:34816
	ds_read_b128 v[210:213], v151 offset:35840
	ds_read_b128 v[214:217], v151 offset:36864
	ds_read_b128 v[218:221], v151 offset:37888
	ds_read_b128 v[222:225], v151 offset:38912
	ds_read_b128 v[226:229], v151 offset:39936
	global_load_lds_dwordx4 v0, s[22:23] sc1
	s_mov_b32 m0, s35
	s_nop 0
	global_load_lds_dwordx4 v4, s[22:23] sc1
	s_waitcnt vmcnt(8)
	s_waitcnt lgkmcnt(0)
	s_setprio 1
	s_barrier
	v_mfma_f32_16x16x32_bf16 v[128:131], v[152:155], v[198:201], v[128:131]
	v_mfma_f32_16x16x32_bf16 v[132:135], v[164:167], v[198:201], v[132:135]
	v_mfma_f32_16x16x32_bf16 v[112:115], v[152:155], v[206:209], v[112:115]
	v_mfma_f32_16x16x32_bf16 v[116:119], v[164:167], v[206:209], v[116:119]
	v_mfma_f32_16x16x32_bf16 v[96:99], v[152:155], v[214:217], v[96:99]
	v_mfma_f32_16x16x32_bf16 v[100:103], v[164:167], v[214:217], v[100:103]
	v_mfma_f32_16x16x32_bf16 v[72:75], v[152:155], v[222:225], v[72:75]
	v_mfma_f32_16x16x32_bf16 v[76:79], v[164:167], v[222:225], v[76:79]
	v_mfma_f32_16x16x32_bf16 v[128:131], v[156:159], v[202:205], v[128:131]
	v_mfma_f32_16x16x32_bf16 v[132:135], v[168:171], v[202:205], v[132:135]
	v_mfma_f32_16x16x32_bf16 v[112:115], v[156:159], v[210:213], v[112:115]
	v_mfma_f32_16x16x32_bf16 v[116:119], v[168:171], v[210:213], v[116:119]
	v_mfma_f32_16x16x32_bf16 v[96:99], v[156:159], v[218:221], v[96:99]
	v_mfma_f32_16x16x32_bf16 v[100:103], v[168:171], v[218:221], v[100:103]
	v_mfma_f32_16x16x32_bf16 v[72:75], v[156:159], v[226:229], v[72:75]
	v_mfma_f32_16x16x32_bf16 v[76:79], v[168:171], v[226:229], v[76:79]
	v_mfma_f32_16x16x32_bf16 v[136:139], v[172:175], v[198:201], v[136:139]
	v_mfma_f32_16x16x32_bf16 v[140:143], v[190:193], v[198:201], v[140:143]
	v_mfma_f32_16x16x32_bf16 v[120:123], v[172:175], v[206:209], v[120:123]
	v_mfma_f32_16x16x32_bf16 v[124:127], v[190:193], v[206:209], v[124:127]
	v_mfma_f32_16x16x32_bf16 v[104:107], v[172:175], v[214:217], v[104:107]
	v_mfma_f32_16x16x32_bf16 v[108:111], v[190:193], v[214:217], v[108:111]
	v_mfma_f32_16x16x32_bf16 v[88:91], v[172:175], v[222:225], v[88:91]
	v_mfma_f32_16x16x32_bf16 v[92:95], v[190:193], v[222:225], v[92:95]
	v_mfma_f32_16x16x32_bf16 v[136:139], v[182:185], v[202:205], v[136:139]
	v_mfma_f32_16x16x32_bf16 v[140:143], v[194:197], v[202:205], v[140:143]
	v_mfma_f32_16x16x32_bf16 v[120:123], v[182:185], v[210:213], v[120:123]
	v_mfma_f32_16x16x32_bf16 v[124:127], v[194:197], v[210:213], v[124:127]
	v_mfma_f32_16x16x32_bf16 v[104:107], v[182:185], v[218:221], v[104:107]
	v_mfma_f32_16x16x32_bf16 v[108:111], v[194:197], v[218:221], v[108:111]
	s_setprio 2
	s_barrier
	v_mfma_f32_16x16x32_bf16 v[88:91], v[182:185], v[226:229], v[88:91]
	v_mfma_f32_16x16x32_bf16 v[92:95], v[194:197], v[226:229], v[92:95]
	s_setprio 0
	s_add_u32 s22, s20, 0x8000
	s_addc_u32 s23, s21, 0
	s_add_i32 s56, s43, s27
	s_mov_b32 m0, s56
	ds_read_b128 v[198:201], v151 offset:49152
	ds_read_b128 v[202:205], v151 offset:50176
	ds_read_b128 v[206:209], v151 offset:51200
	ds_read_b128 v[210:213], v151 offset:52224
	ds_read_b128 v[214:217], v151 offset:53248
	ds_read_b128 v[218:221], v151 offset:54272
	ds_read_b128 v[222:225], v151 offset:55296
	ds_read_b128 v[226:229], v151 offset:56320
	global_load_lds_dwordx4 v2, s[22:23] sc1
	s_add_i32 m0, s56, 0x2000
	s_add_u32 s20, s20, 0xc000
	global_load_lds_dwordx4 v6, s[22:23] sc1
	s_addc_u32 s21, s21, 0
	s_add_i32 s22, s44, s27
	s_mov_b32 m0, s22
	s_nop 0
	global_load_lds_dwordx4 v2, s[20:21] sc1
	s_add_i32 m0, s22, 0x2000
	s_nop 0
	global_load_lds_dwordx4 v6, s[20:21] sc1
	s_mov_b32 m0, s38
	s_nop 0
	global_load_lds_dwordx4 v0, s[18:19] sc1
	s_mov_b32 m0, s39
	s_nop 0
	global_load_lds_dwordx4 v4, s[18:19] sc1
	s_waitcnt vmcnt(8)
	s_waitcnt lgkmcnt(0)
	s_setprio 1
	s_barrier
	v_mfma_f32_16x16x32_bf16 v[64:67], v[152:155], v[198:201], v[64:67]
	v_mfma_f32_16x16x32_bf16 v[68:71], v[164:167], v[198:201], v[68:71]
	v_mfma_f32_16x16x32_bf16 v[48:51], v[152:155], v[206:209], v[48:51]
	v_mfma_f32_16x16x32_bf16 v[52:55], v[164:167], v[206:209], v[52:55]
	v_mfma_f32_16x16x32_bf16 v[32:35], v[152:155], v[214:217], v[32:35]
	v_mfma_f32_16x16x32_bf16 v[36:39], v[164:167], v[214:217], v[36:39]
	v_mfma_f32_16x16x32_bf16 v[16:19], v[152:155], v[222:225], v[16:19]
	v_mfma_f32_16x16x32_bf16 v[20:23], v[164:167], v[222:225], v[20:23]
	v_mfma_f32_16x16x32_bf16 v[64:67], v[156:159], v[202:205], v[64:67]
	v_mfma_f32_16x16x32_bf16 v[68:71], v[168:171], v[202:205], v[68:71]
	v_mfma_f32_16x16x32_bf16 v[48:51], v[156:159], v[210:213], v[48:51]
	v_mfma_f32_16x16x32_bf16 v[52:55], v[168:171], v[210:213], v[52:55]
	v_mfma_f32_16x16x32_bf16 v[32:35], v[156:159], v[218:221], v[32:35]
	v_mfma_f32_16x16x32_bf16 v[36:39], v[168:171], v[218:221], v[36:39]
	v_mfma_f32_16x16x32_bf16 v[16:19], v[156:159], v[226:229], v[16:19]
	v_mfma_f32_16x16x32_bf16 v[20:23], v[168:171], v[226:229], v[20:23]
	v_mfma_f32_16x16x32_bf16 v[80:83], v[172:175], v[198:201], v[80:83]
	v_mfma_f32_16x16x32_bf16 v[84:87], v[190:193], v[198:201], v[84:87]
	v_mfma_f32_16x16x32_bf16 v[56:59], v[172:175], v[206:209], v[56:59]
	v_mfma_f32_16x16x32_bf16 v[60:63], v[190:193], v[206:209], v[60:63]
	v_mfma_f32_16x16x32_bf16 v[40:43], v[172:175], v[214:217], v[40:43]
	v_mfma_f32_16x16x32_bf16 v[44:47], v[190:193], v[214:217], v[44:47]
	v_mfma_f32_16x16x32_bf16 v[24:27], v[172:175], v[222:225], v[24:27]
	v_mfma_f32_16x16x32_bf16 v[28:31], v[190:193], v[222:225], v[28:31]
	v_mfma_f32_16x16x32_bf16 v[80:83], v[182:185], v[202:205], v[80:83]
	v_mfma_f32_16x16x32_bf16 v[84:87], v[194:197], v[202:205], v[84:87]
	v_mfma_f32_16x16x32_bf16 v[56:59], v[182:185], v[210:213], v[56:59]
	v_mfma_f32_16x16x32_bf16 v[60:63], v[194:197], v[210:213], v[60:63]
	v_mfma_f32_16x16x32_bf16 v[40:43], v[182:185], v[218:221], v[40:43]
	v_mfma_f32_16x16x32_bf16 v[44:47], v[194:197], v[218:221], v[44:47]
	s_setprio 2
	s_barrier
	v_mfma_f32_16x16x32_bf16 v[24:27], v[182:185], v[226:229], v[24:27]
	v_mfma_f32_16x16x32_bf16 v[28:31], v[194:197], v[226:229], v[28:31]
	s_setprio 0
	s_add_i32 s55, s55, 2
	s_add_u32 s6, s6, 0x10000
	s_addc_u32 s7, s7, 0
	s_cmp_gt_u32 s55, 41
	s_cbranch_scc0 .LBB0_1249
	s_add_u32 s6, s49, 0xffff0000
	s_addc_u32 s7, s50, -1
	s_and_b64 vcc, exec, s[4:5]
	s_cbranch_vccnz .LBB0_1236
	s_mov_b32 s8, s45
	s_mov_b32 s10, s46
	s_mov_b64 s[12:13], s[16:17]
	s_mov_b32 s42, s47
	s_andn2_b64 vcc, exec, s[0:1]
	s_cbranch_vccnz .LBB0_1237
